# stack11 minus the 40 adjacent s_setprio 0 / s_setprio 1 pairs in the middle of GEMM MFMA runs (priority stays raised through the run)
# speedup vs baseline: 1.0064x; 1.0064x over previous
; #define PG8_STAGE(bufoff, gbase, voff) do { _Pragma("unroll") for (int _i = 0; _i < 2; ++_i) \
;         __builtin_amdgcn_global_load_lds((const unsigned*)((const char*)(gbase) + (voff)[_i]), (PG8_LAS unsigned*)(lds + (bufoff) + ldsw + _i * 8192), 16, 0, 0); } while (0)
; #define PG8_LDA(dst, b, h) do { _Pragma("unroll") for (int m = 0; m < 4; ++m) _Pragma("unroll") for (int k = 0; k < 2; ++k) dst[m][k] = *(const PG8_LAS bf16x8*)(lds + PG8_SA(b, h) + aoff + m * 2048 + k * 1024); } while (0)
; #define PG8_LDB(dst, b, h) do { _Pragma("unroll") for (int n = 0; n < 2; ++n) _Pragma("unroll") for (int k = 0; k < 2; ++k) dst[n][k] = *(const PG8_LAS bf16x8*)(lds + PG8_SB(b, h) + boff + n * 2048 + k * 1024); } while (0)
; #define PG8_MMA(ai, bj, At, Bt) do { __builtin_amdgcn_s_setprio(1); _Pragma("unroll") for (int m = 0; m < 4; ++m) _Pragma("unroll") for (int n = 0; n < 2; ++n) _Pragma("unroll") for (int k = 0; k < 2; ++k) \
;         acc[ai][bj][m][n] = __builtin_amdgcn_mfma_f32_16x16x32_bf16(Bt[n][k], At[m][k], acc[ai][bj][m][n], 0, 0, 0); __builtin_amdgcn_s_setprio(0); } while (0)
; #define PG8_WAIT_V(n) asm volatile("s_waitcnt vmcnt(" #n ")" ::: "memory")
; #define PG8_WAIT_L(n) asm volatile("s_waitcnt lgkmcnt(" #n ")" ::: "memory")
; template <class Epi, class Sched, bool ALIGN_EPI = false, bool SP2 = false>
; __device__ __forceinline__ void gemm_phase(PG8_LAS unsigned char* lds, const Gemm g, const Sched& S, const Epi& E, int wave0) {
;     ...
;         for (int t = 0; t < nt; t += 2) {
;             const bool last = (t == nt - 2);
;             const char* a1 = cA + (size_t)(t + 1) * kstep;
;             const char* a2 = last ? nA : cA + (size_t)(t + 2) * kstep; const char* b2 = last ? nB : cB + (size_t)(t + 2) * kstep;
;             const char* a3 = a2 + kstep; const char* b3 = b2 + kstep;
;             if constexpr (SP2) {
;             PG8_LDB(B0, 0, 0); PG8_LDB(B1, 0, 1); PG8_SCHED; PG8_LDA(At, 0, 0); PG8_STAGE(PG8_SA(1, 1), a1 + hstep, voffA);
;             PG8_WAIT_V(8); PG8_WAIT_L(0); PG8_BAR; PG8_MMA(0, 0, At, B0); PG8_MMA(0, 1, At, B1); PG8_BAR; PG8_SCHED;
;             PG8_LDA(At, 0, 1); PG8_STAGE(PG8_SB(0, 0), b2, voffB); PG8_STAGE(PG8_SB(0, 1), b2 + hstep, voffB); PG8_STAGE(PG8_SA(0, 0), a2, voffA);
;             PG8_WAIT_V(8); PG8_WAIT_L(0); PG8_BAR; PG8_MMA(1, 0, At, B0); PG8_MMA(1, 1, At, B1); PG8_BAR; PG8_SCHED;
.LBB0_195:
	s_add_u32 s4, s0, 0xfffc0080
	s_addc_u32 s5, s1, -1
	s_add_i32 s86, 0, 0x10000
	s_cmp_eq_u32 s85, 12
	s_cselect_b32 s43, s44, s5
	s_cselect_b32 s42, s53, s4
	v_add_u32_e32 v0, s86, v174
	s_cselect_b32 s5, s51, s84
	s_cselect_b32 s4, s82, s83
	s_add_i32 s88, 0, 0x14000
	ds_read_b128 v[130:133], v0
	ds_read_b128 v[134:137], v0 offset:1024
	ds_read_b128 v[138:141], v0 offset:2048
	ds_read_b128 v[142:145], v0 offset:3072
	v_add_u32_e32 v0, s88, v174
	s_waitcnt lgkmcnt(0)
	ds_read_b128 v[158:161], v0
	ds_read_b128 v[162:165], v0 offset:1024
	ds_read_b128 v[166:169], v0 offset:2048
	ds_read_b128 v[170:173], v0 offset:3072
	v_lshl_add_u64 v[208:209], s[0:1], 0, v[154:155]
	s_add_i32 m0, s62, 0xc000
	ds_read_b128 v[176:179], v175
	ds_read_b128 v[180:183], v175 offset:1024
	ds_read_b128 v[184:187], v175 offset:2048
	ds_read_b128 v[188:191], v175 offset:3072
	ds_read_b128 v[192:195], v175 offset:4096
	ds_read_b128 v[196:199], v175 offset:5120
	ds_read_b128 v[200:203], v175 offset:6144
	ds_read_b128 v[204:207], v175 offset:7168
	global_load_lds_dwordx4 v[208:209], off
	v_lshl_add_u64 v[208:209], s[0:1], 0, v[156:157]
	s_add_i32 m0, s62, 0xe000
	s_nop 0
	global_load_lds_dwordx4 v[208:209], off
	s_waitcnt vmcnt(8)
	s_waitcnt lgkmcnt(0)
	s_barrier
	s_setprio 1
	s_waitcnt lgkmcnt(0)
	v_mfma_f32_16x16x32_bf16 v[126:129], v[130:133], v[176:179], v[126:129]
	v_mfma_f32_16x16x32_bf16 v[122:125], v[138:141], v[176:179], v[122:125]
	v_mfma_f32_16x16x32_bf16 v[110:113], v[130:133], v[184:187], v[110:113]
	v_mfma_f32_16x16x32_bf16 v[106:109], v[138:141], v[184:187], v[106:109]
	v_mfma_f32_16x16x32_bf16 v[94:97], v[130:133], v[192:195], v[94:97]
	v_mfma_f32_16x16x32_bf16 v[90:93], v[138:141], v[192:195], v[90:93]
	v_mfma_f32_16x16x32_bf16 v[78:81], v[130:133], v[200:203], v[78:81]
	v_mfma_f32_16x16x32_bf16 v[74:77], v[138:141], v[200:203], v[74:77]
	v_mfma_f32_16x16x32_bf16 v[126:129], v[134:137], v[180:183], v[126:129]
	v_mfma_f32_16x16x32_bf16 v[122:125], v[142:145], v[180:183], v[122:125]
	v_mfma_f32_16x16x32_bf16 v[110:113], v[134:137], v[188:191], v[110:113]
	v_mfma_f32_16x16x32_bf16 v[106:109], v[142:145], v[188:191], v[106:109]
	v_mfma_f32_16x16x32_bf16 v[94:97], v[134:137], v[196:199], v[94:97]
	v_mfma_f32_16x16x32_bf16 v[90:93], v[142:145], v[196:199], v[90:93]
	v_mfma_f32_16x16x32_bf16 v[78:81], v[134:137], v[204:207], v[78:81]
	v_mfma_f32_16x16x32_bf16 v[74:77], v[142:145], v[204:207], v[74:77]
	v_mfma_f32_16x16x32_bf16 v[118:121], v[158:161], v[176:179], v[118:121]
	v_mfma_f32_16x16x32_bf16 v[114:117], v[166:169], v[176:179], v[114:117]
	v_mfma_f32_16x16x32_bf16 v[102:105], v[158:161], v[184:187], v[102:105]
	v_mfma_f32_16x16x32_bf16 v[98:101], v[166:169], v[184:187], v[98:101]
	v_mfma_f32_16x16x32_bf16 v[86:89], v[158:161], v[192:195], v[86:89]
	v_mfma_f32_16x16x32_bf16 v[82:85], v[166:169], v[192:195], v[82:85]
	v_mfma_f32_16x16x32_bf16 v[70:73], v[158:161], v[200:203], v[70:73]
	v_mfma_f32_16x16x32_bf16 v[66:69], v[166:169], v[200:203], v[66:69]
	v_mfma_f32_16x16x32_bf16 v[118:121], v[162:165], v[180:183], v[118:121]
	v_mfma_f32_16x16x32_bf16 v[114:117], v[170:173], v[180:183], v[114:117]
	v_mfma_f32_16x16x32_bf16 v[102:105], v[162:165], v[188:191], v[102:105]
	v_mfma_f32_16x16x32_bf16 v[98:101], v[170:173], v[188:191], v[98:101]
	v_mfma_f32_16x16x32_bf16 v[86:89], v[162:165], v[196:199], v[86:89]
	v_mfma_f32_16x16x32_bf16 v[82:85], v[170:173], v[196:199], v[82:85]
	v_mfma_f32_16x16x32_bf16 v[70:73], v[162:165], v[204:207], v[70:73]
	v_mfma_f32_16x16x32_bf16 v[66:69], v[170:173], v[204:207], v[66:69]
	s_setprio 0
	s_barrier
	s_add_i32 s86, s86, s61
	v_lshl_add_u64 v[208:209], s[4:5], 0, v[150:151]
	s_mov_b32 m0, s86
	ds_read_b128 v[176:179], v175 offset:16384
	ds_read_b128 v[180:183], v175 offset:17408
	ds_read_b128 v[184:187], v175 offset:18432
	ds_read_b128 v[188:191], v175 offset:19456
	ds_read_b128 v[192:195], v175 offset:20480
	ds_read_b128 v[196:199], v175 offset:21504
	ds_read_b128 v[200:203], v175 offset:22528
	ds_read_b128 v[204:207], v175 offset:23552
	global_load_lds_dwordx4 v[208:209], off
	s_add_i32 m0, s86, 0x2000
	s_add_u32 s86, s4, 0x40000
	v_lshl_add_u64 v[210:211], s[4:5], 0, v[146:147]
	s_addc_u32 s87, s5, 0
	s_add_i32 s88, s88, s61
	global_load_lds_dwordx4 v[210:211], off
	v_lshl_add_u64 v[212:213], s[86:87], 0, v[150:151]
	s_mov_b32 m0, s88
	v_lshl_add_u64 v[214:215], s[42:43], 0, v[148:149]
	global_load_lds_dwordx4 v[212:213], off
	v_lshl_add_u64 v[212:213], s[86:87], 0, v[146:147]
	s_add_i32 m0, s88, 0x2000
	s_nop 0
	global_load_lds_dwordx4 v[212:213], off
	v_lshl_add_u64 v[212:213], s[42:43], 0, v[152:153]
	s_mov_b32 m0, s62
	s_nop 0
	global_load_lds_dwordx4 v[212:213], off
	s_mov_b32 m0, s63
	s_nop 0
	global_load_lds_dwordx4 v[214:215], off
	s_waitcnt vmcnt(8)
	s_waitcnt lgkmcnt(0)
	s_barrier
; #define PG8_STAGE(bufoff, gbase, voff) do { _Pragma("unroll") for (int _i = 0; _i < 2; ++_i) \
;         __builtin_amdgcn_global_load_lds((const unsigned*)((const char*)(gbase) + (voff)[_i]), (PG8_LAS unsigned*)(lds + (bufoff) + ldsw + _i * 8192), 16, 0, 0); } while (0)
; #define PG8_LDA(dst, b, h) do { _Pragma("unroll") for (int m = 0; m < 4; ++m) _Pragma("unroll") for (int k = 0; k < 2; ++k) dst[m][k] = *(const PG8_LAS bf16x8*)(lds + PG8_SA(b, h) + aoff + m * 2048 + k * 1024); } while (0)
; #define PG8_LDB(dst, b, h) do { _Pragma("unroll") for (int n = 0; n < 2; ++n) _Pragma("unroll") for (int k = 0; k < 2; ++k) dst[n][k] = *(const PG8_LAS bf16x8*)(lds + PG8_SB(b, h) + boff + n * 2048 + k * 1024); } while (0)
; #define PG8_MMA(ai, bj, At, Bt) do { __builtin_amdgcn_s_setprio(1); _Pragma("unroll") for (int m = 0; m < 4; ++m) _Pragma("unroll") for (int n = 0; n < 2; ++n) _Pragma("unroll") for (int k = 0; k < 2; ++k) \
;         acc[ai][bj][m][n] = __builtin_amdgcn_mfma_f32_16x16x32_bf16(Bt[n][k], At[m][k], acc[ai][bj][m][n], 0, 0, 0); __builtin_amdgcn_s_setprio(0); } while (0)
; #define PG8_WAIT_V(n) asm volatile("s_waitcnt vmcnt(" #n ")" ::: "memory")
; #define PG8_WAIT_L(n) asm volatile("s_waitcnt lgkmcnt(" #n ")" ::: "memory")
; #define PG8_BAR __builtin_amdgcn_s_barrier()
; #define PG8_SCHED __builtin_amdgcn_sched_barrier(0)
; template <class Epi, class Sched, bool ALIGN_EPI = false, bool SP2 = false>
; __device__ __forceinline__ void gemm_phase(PG8_LAS unsigned char* lds, const Gemm g, const Sched& S, const Epi& E, int wave0) {
;     ...
;             PG8_WAIT_V(8); PG8_WAIT_L(0); PG8_BAR; PG8_MMA(1, 0, At, B0); PG8_MMA(1, 1, At, B1); PG8_BAR; PG8_SCHED;
;             PG8_LDB(B0, 1, 0); PG8_LDB(B1, 1, 1); PG8_SCHED; PG8_LDA(At, 1, 0); PG8_STAGE(PG8_SA(0, 1), a2 + hstep, voffA);
;             PG8_WAIT_V(8); PG8_WAIT_L(0); PG8_BAR; PG8_MMA(0, 0, At, B0); PG8_MMA(0, 1, At, B1); PG8_BAR; PG8_SCHED;
	s_setprio 1
	s_waitcnt lgkmcnt(0)
	v_mfma_f32_16x16x32_bf16 v[62:65], v[130:133], v[176:179], v[62:65]
	v_mfma_f32_16x16x32_bf16 v[58:61], v[138:141], v[176:179], v[58:61]
	v_mfma_f32_16x16x32_bf16 v[46:49], v[130:133], v[184:187], v[46:49]
	v_mfma_f32_16x16x32_bf16 v[42:45], v[138:141], v[184:187], v[42:45]
	v_mfma_f32_16x16x32_bf16 v[30:33], v[130:133], v[192:195], v[30:33]
	v_mfma_f32_16x16x32_bf16 v[26:29], v[138:141], v[192:195], v[26:29]
	v_mfma_f32_16x16x32_bf16 v[14:17], v[130:133], v[200:203], v[14:17]
	v_mfma_f32_16x16x32_bf16 v[10:13], v[138:141], v[200:203], v[10:13]
	v_mfma_f32_16x16x32_bf16 v[62:65], v[134:137], v[180:183], v[62:65]
	v_mfma_f32_16x16x32_bf16 v[58:61], v[142:145], v[180:183], v[58:61]
	v_mfma_f32_16x16x32_bf16 v[46:49], v[134:137], v[188:191], v[46:49]
	v_mfma_f32_16x16x32_bf16 v[42:45], v[142:145], v[188:191], v[42:45]
	v_mfma_f32_16x16x32_bf16 v[30:33], v[134:137], v[196:199], v[30:33]
	v_mfma_f32_16x16x32_bf16 v[26:29], v[142:145], v[196:199], v[26:29]
	v_mfma_f32_16x16x32_bf16 v[14:17], v[134:137], v[204:207], v[14:17]
	v_mfma_f32_16x16x32_bf16 v[10:13], v[142:145], v[204:207], v[10:13]
	v_mfma_f32_16x16x32_bf16 v[54:57], v[158:161], v[176:179], v[54:57]
	v_mfma_f32_16x16x32_bf16 v[50:53], v[166:169], v[176:179], v[50:53]
	v_mfma_f32_16x16x32_bf16 v[38:41], v[158:161], v[184:187], v[38:41]
	v_mfma_f32_16x16x32_bf16 v[34:37], v[166:169], v[184:187], v[34:37]
	v_mfma_f32_16x16x32_bf16 v[22:25], v[158:161], v[192:195], v[22:25]
	v_mfma_f32_16x16x32_bf16 v[18:21], v[166:169], v[192:195], v[18:21]
	v_mfma_f32_16x16x32_bf16 v[6:9], v[158:161], v[200:203], v[6:9]
	v_mfma_f32_16x16x32_bf16 v[2:5], v[166:169], v[200:203], v[2:5]
	v_mfma_f32_16x16x32_bf16 v[54:57], v[162:165], v[180:183], v[54:57]
	v_mfma_f32_16x16x32_bf16 v[50:53], v[170:173], v[180:183], v[50:53]
	v_mfma_f32_16x16x32_bf16 v[38:41], v[162:165], v[188:191], v[38:41]
	v_mfma_f32_16x16x32_bf16 v[34:37], v[170:173], v[188:191], v[34:37]
	v_mfma_f32_16x16x32_bf16 v[22:25], v[162:165], v[196:199], v[22:25]
	v_mfma_f32_16x16x32_bf16 v[18:21], v[170:173], v[196:199], v[18:21]
	v_mfma_f32_16x16x32_bf16 v[6:9], v[162:165], v[204:207], v[6:9]
	v_mfma_f32_16x16x32_bf16 v[2:5], v[170:173], v[204:207], v[2:5]
	s_setprio 0
	s_barrier
	s_add_i32 s86, 0, 0x18000
	v_add_u32_e32 v0, s86, v174
	s_add_i32 s87, 0, 0x1c000
	ds_read_b128 v[130:133], v0
	ds_read_b128 v[134:137], v0 offset:1024
	ds_read_b128 v[138:141], v0 offset:2048
	ds_read_b128 v[142:145], v0 offset:3072
	v_add_u32_e32 v0, s87, v174
	ds_read_b128 v[158:161], v0
	ds_read_b128 v[162:165], v0 offset:1024
	ds_read_b128 v[166:169], v0 offset:2048
	ds_read_b128 v[170:173], v0 offset:3072
	s_add_u32 s42, s42, 0x40000
	s_addc_u32 s43, s43, 0
	s_mov_b32 m0, s64
	v_lshl_add_u64 v[216:217], s[42:43], 0, v[152:153]
	ds_read_b128 v[176:179], v175 offset:32768
	ds_read_b128 v[180:183], v175 offset:33792
	ds_read_b128 v[184:187], v175 offset:34816
	ds_read_b128 v[188:191], v175 offset:35840
	ds_read_b128 v[192:195], v175 offset:36864
	ds_read_b128 v[196:199], v175 offset:37888
	ds_read_b128 v[200:203], v175 offset:38912
	ds_read_b128 v[204:207], v175 offset:39936
	global_load_lds_dwordx4 v[216:217], off
	v_lshl_add_u64 v[216:217], s[42:43], 0, v[148:149]
	s_mov_b32 m0, s65
	s_nop 0
	global_load_lds_dwordx4 v[216:217], off
	s_waitcnt vmcnt(8)
	s_waitcnt lgkmcnt(0)
	s_barrier
	s_setprio 1
	s_waitcnt lgkmcnt(0)
	v_mfma_f32_16x16x32_bf16 v[126:129], v[130:133], v[176:179], v[126:129]
	v_mfma_f32_16x16x32_bf16 v[122:125], v[138:141], v[176:179], v[122:125]
	v_mfma_f32_16x16x32_bf16 v[110:113], v[130:133], v[184:187], v[110:113]
	v_mfma_f32_16x16x32_bf16 v[106:109], v[138:141], v[184:187], v[106:109]
	v_mfma_f32_16x16x32_bf16 v[94:97], v[130:133], v[192:195], v[94:97]
	v_mfma_f32_16x16x32_bf16 v[90:93], v[138:141], v[192:195], v[90:93]
	v_mfma_f32_16x16x32_bf16 v[78:81], v[130:133], v[200:203], v[78:81]
	v_mfma_f32_16x16x32_bf16 v[74:77], v[138:141], v[200:203], v[74:77]
	v_mfma_f32_16x16x32_bf16 v[126:129], v[134:137], v[180:183], v[126:129]
	v_mfma_f32_16x16x32_bf16 v[122:125], v[142:145], v[180:183], v[122:125]
	v_mfma_f32_16x16x32_bf16 v[110:113], v[134:137], v[188:191], v[110:113]
	v_mfma_f32_16x16x32_bf16 v[106:109], v[142:145], v[188:191], v[106:109]
	v_mfma_f32_16x16x32_bf16 v[94:97], v[134:137], v[196:199], v[94:97]
	v_mfma_f32_16x16x32_bf16 v[90:93], v[142:145], v[196:199], v[90:93]
	v_mfma_f32_16x16x32_bf16 v[78:81], v[134:137], v[204:207], v[78:81]
	v_mfma_f32_16x16x32_bf16 v[74:77], v[142:145], v[204:207], v[74:77]
	v_mfma_f32_16x16x32_bf16 v[118:121], v[158:161], v[176:179], v[118:121]
	v_mfma_f32_16x16x32_bf16 v[114:117], v[166:169], v[176:179], v[114:117]
	v_mfma_f32_16x16x32_bf16 v[102:105], v[158:161], v[184:187], v[102:105]
	v_mfma_f32_16x16x32_bf16 v[98:101], v[166:169], v[184:187], v[98:101]
	v_mfma_f32_16x16x32_bf16 v[86:89], v[158:161], v[192:195], v[86:89]
	v_mfma_f32_16x16x32_bf16 v[82:85], v[166:169], v[192:195], v[82:85]
	v_mfma_f32_16x16x32_bf16 v[70:73], v[158:161], v[200:203], v[70:73]
	v_mfma_f32_16x16x32_bf16 v[66:69], v[166:169], v[200:203], v[66:69]
	v_mfma_f32_16x16x32_bf16 v[118:121], v[162:165], v[180:183], v[118:121]
	v_mfma_f32_16x16x32_bf16 v[114:117], v[170:173], v[180:183], v[114:117]
	v_mfma_f32_16x16x32_bf16 v[102:105], v[162:165], v[188:191], v[102:105]
	v_mfma_f32_16x16x32_bf16 v[98:101], v[170:173], v[188:191], v[98:101]
	v_mfma_f32_16x16x32_bf16 v[86:89], v[162:165], v[196:199], v[86:89]
	v_mfma_f32_16x16x32_bf16 v[82:85], v[170:173], v[196:199], v[82:85]
	v_mfma_f32_16x16x32_bf16 v[70:73], v[162:165], v[204:207], v[70:73]
	v_mfma_f32_16x16x32_bf16 v[66:69], v[170:173], v[204:207], v[66:69]
	s_setprio 0
	s_barrier
; #define PG8_STAGE(bufoff, gbase, voff) do { _Pragma("unroll") for (int _i = 0; _i < 2; ++_i) \
;         __builtin_amdgcn_global_load_lds((const unsigned*)((const char*)(gbase) + (voff)[_i]), (PG8_LAS unsigned*)(lds + (bufoff) + ldsw + _i * 8192), 16, 0, 0); } while (0)
; #define PG8_LDA(dst, b, h) do { _Pragma("unroll") for (int m = 0; m < 4; ++m) _Pragma("unroll") for (int k = 0; k < 2; ++k) dst[m][k] = *(const PG8_LAS bf16x8*)(lds + PG8_SA(b, h) + aoff + m * 2048 + k * 1024); } while (0)
; #define PG8_WAIT_V(n) asm volatile("s_waitcnt vmcnt(" #n ")" ::: "memory")
; #define PG8_WAIT_L(n) asm volatile("s_waitcnt lgkmcnt(" #n ")" ::: "memory")
; #define PG8_BAR __builtin_amdgcn_s_barrier()
; template <class Epi, class Sched, bool ALIGN_EPI = false, bool SP2 = false>
; __device__ __forceinline__ void gemm_phase(PG8_LAS unsigned char* lds, const Gemm g, const Sched& S, const Epi& E, int wave0) {
;     ...
;         for (int t = 0; t < nt; t += 2) {
;             const bool last = (t == nt - 2);
;             const char* a1 = cA + (size_t)(t + 1) * kstep;
;             const char* a2 = last ? nA : cA + (size_t)(t + 2) * kstep; const char* b2 = last ? nB : cB + (size_t)(t + 2) * kstep;
;             const char* a3 = a2 + kstep; const char* b3 = b2 + kstep;
;             if constexpr (SP2) {
;             PG8_LDB(B0, 0, 0); PG8_LDB(B1, 0, 1); PG8_SCHED; PG8_LDA(At, 0, 0); PG8_STAGE(PG8_SA(1, 1), a1 + hstep, voffA);
;             PG8_WAIT_V(8); PG8_WAIT_L(0); PG8_BAR; PG8_MMA(0, 0, At, B0); PG8_MMA(0, 1, At, B1); PG8_BAR; PG8_SCHED;
;             PG8_LDA(At, 0, 1); PG8_STAGE(PG8_SB(0, 0), b2, voffB); PG8_STAGE(PG8_SB(0, 1), b2 + hstep, voffB); PG8_STAGE(PG8_SA(0, 0), a2, voffA);
;             PG8_WAIT_V(8); PG8_WAIT_L(0); PG8_BAR; PG8_MMA(1, 0, At, B0); PG8_MMA(1, 1, At, B1); PG8_BAR; PG8_SCHED;
;             PG8_LDB(B0, 1, 0); PG8_LDB(B1, 1, 1); PG8_SCHED; PG8_LDA(At, 1, 0); PG8_STAGE(PG8_SA(0, 1), a2 + hstep, voffA);
;             PG8_WAIT_V(8); PG8_WAIT_L(0); PG8_BAR; PG8_MMA(0, 0, At, B0); PG8_MMA(0, 1, At, B1); PG8_BAR; PG8_SCHED;
;             PG8_LDA(At, 1, 1); PG8_STAGE(PG8_SB(1, 0), b3, voffB); PG8_STAGE(PG8_SB(1, 1), b3 + hstep, voffB); PG8_STAGE(PG8_SA(1, 0), a3, voffA);
;             PG8_WAIT_V(8); PG8_WAIT_L(0); PG8_BAR; PG8_MMA(1, 0, At, B0); PG8_MMA(1, 1, At, B1); PG8_BAR; PG8_SCHED;
;     ...
;         if constexpr (ALIGN_EPI) { if (wr == 0) PG8_BAR; }
	s_add_i32 s42, s86, s61
	v_lshl_add_u64 v[208:209], v[208:209], 0, s[34:35]
	s_mov_b32 m0, s42
	ds_read_b128 v[176:179], v175 offset:49152
	ds_read_b128 v[180:183], v175 offset:50176
	ds_read_b128 v[184:187], v175 offset:51200
	ds_read_b128 v[188:191], v175 offset:52224
	ds_read_b128 v[192:195], v175 offset:53248
	ds_read_b128 v[196:199], v175 offset:54272
	ds_read_b128 v[200:203], v175 offset:55296
	ds_read_b128 v[204:207], v175 offset:56320
	global_load_lds_dwordx4 v[208:209], off
	s_add_i32 m0, s42, 0x2000
	s_add_u32 s4, s4, 0x40080
	v_lshl_add_u64 v[208:209], v[210:211], 0, s[34:35]
	s_addc_u32 s5, s5, 0
	s_add_i32 s42, s87, s61
	global_load_lds_dwordx4 v[208:209], off
	v_lshl_add_u64 v[208:209], s[4:5], 0, v[150:151]
	s_mov_b32 m0, s42
	s_nop 0
	global_load_lds_dwordx4 v[208:209], off
	v_lshl_add_u64 v[208:209], s[4:5], 0, v[146:147]
	s_add_i32 m0, s42, 0x2000
	s_nop 0
	global_load_lds_dwordx4 v[208:209], off
	v_lshl_add_u64 v[208:209], v[212:213], 0, s[34:35]
	s_mov_b32 m0, s74
	s_nop 0
	global_load_lds_dwordx4 v[208:209], off
	v_lshl_add_u64 v[208:209], v[214:215], 0, s[34:35]
	s_mov_b32 m0, s75
	s_nop 0
	global_load_lds_dwordx4 v[208:209], off
	s_waitcnt vmcnt(8)
	s_waitcnt lgkmcnt(0)
	s_barrier
	s_setprio 1
	s_waitcnt lgkmcnt(0)
	v_mfma_f32_16x16x32_bf16 v[62:65], v[130:133], v[176:179], v[62:65]
	v_mfma_f32_16x16x32_bf16 v[58:61], v[138:141], v[176:179], v[58:61]
	v_mfma_f32_16x16x32_bf16 v[46:49], v[130:133], v[184:187], v[46:49]
	v_mfma_f32_16x16x32_bf16 v[42:45], v[138:141], v[184:187], v[42:45]
	v_mfma_f32_16x16x32_bf16 v[30:33], v[130:133], v[192:195], v[30:33]
	v_mfma_f32_16x16x32_bf16 v[26:29], v[138:141], v[192:195], v[26:29]
	v_mfma_f32_16x16x32_bf16 v[14:17], v[130:133], v[200:203], v[14:17]
	v_mfma_f32_16x16x32_bf16 v[10:13], v[138:141], v[200:203], v[10:13]
	v_mfma_f32_16x16x32_bf16 v[62:65], v[134:137], v[180:183], v[62:65]
	v_mfma_f32_16x16x32_bf16 v[58:61], v[142:145], v[180:183], v[58:61]
	v_mfma_f32_16x16x32_bf16 v[46:49], v[134:137], v[188:191], v[46:49]
	v_mfma_f32_16x16x32_bf16 v[42:45], v[142:145], v[188:191], v[42:45]
	v_mfma_f32_16x16x32_bf16 v[30:33], v[134:137], v[196:199], v[30:33]
	v_mfma_f32_16x16x32_bf16 v[26:29], v[142:145], v[196:199], v[26:29]
	v_mfma_f32_16x16x32_bf16 v[14:17], v[134:137], v[204:207], v[14:17]
	v_mfma_f32_16x16x32_bf16 v[10:13], v[142:145], v[204:207], v[10:13]
	v_mfma_f32_16x16x32_bf16 v[54:57], v[158:161], v[176:179], v[54:57]
	v_mfma_f32_16x16x32_bf16 v[50:53], v[166:169], v[176:179], v[50:53]
	v_mfma_f32_16x16x32_bf16 v[38:41], v[158:161], v[184:187], v[38:41]
	v_mfma_f32_16x16x32_bf16 v[34:37], v[166:169], v[184:187], v[34:37]
	v_mfma_f32_16x16x32_bf16 v[22:25], v[158:161], v[192:195], v[22:25]
	v_mfma_f32_16x16x32_bf16 v[18:21], v[166:169], v[192:195], v[18:21]
	v_mfma_f32_16x16x32_bf16 v[6:9], v[158:161], v[200:203], v[6:9]
	v_mfma_f32_16x16x32_bf16 v[2:5], v[166:169], v[200:203], v[2:5]
	v_mfma_f32_16x16x32_bf16 v[54:57], v[162:165], v[180:183], v[54:57]
	v_mfma_f32_16x16x32_bf16 v[50:53], v[170:173], v[180:183], v[50:53]
	v_mfma_f32_16x16x32_bf16 v[38:41], v[162:165], v[188:191], v[38:41]
	v_mfma_f32_16x16x32_bf16 v[34:37], v[170:173], v[188:191], v[34:37]
	v_mfma_f32_16x16x32_bf16 v[22:25], v[162:165], v[196:199], v[22:25]
	v_mfma_f32_16x16x32_bf16 v[18:21], v[170:173], v[196:199], v[18:21]
	v_mfma_f32_16x16x32_bf16 v[6:9], v[162:165], v[204:207], v[6:9]
	v_mfma_f32_16x16x32_bf16 v[2:5], v[170:173], v[204:207], v[2:5]
	s_setprio 0
	s_barrier
	s_add_i32 s85, s85, 2
	s_add_u32 s0, s0, 0x100
	s_addc_u32 s1, s1, 0
	s_add_u32 s83, s83, 0x100
	s_addc_u32 s84, s84, 0
	s_cmp_gt_u32 s85, 13
	s_cbranch_scc0 .LBB0_195
	s_and_b64 vcc, exec, s[48:49]
	s_cbranch_vccz .LBB0_198
	s_barrier

; #define PG8_STAGE(bufoff, gbase, voff) do { _Pragma("unroll") for (int _i = 0; _i < 2; ++_i) \
;         __builtin_amdgcn_global_load_lds((const unsigned*)((const char*)(gbase) + (voff)[_i]), (PG8_LAS unsigned*)(lds + (bufoff) + ldsw + _i * 8192), 16, 0, 0); } while (0)
; #define PG8_LDA(dst, b, h) do { _Pragma("unroll") for (int m = 0; m < 4; ++m) _Pragma("unroll") for (int k = 0; k < 2; ++k) dst[m][k] = *(const PG8_LAS bf16x8*)(lds + PG8_SA(b, h) + aoff + m * 2048 + k * 1024); } while (0)
; #define PG8_LDB(dst, b, h) do { _Pragma("unroll") for (int n = 0; n < 2; ++n) _Pragma("unroll") for (int k = 0; k < 2; ++k) dst[n][k] = *(const PG8_LAS bf16x8*)(lds + PG8_SB(b, h) + boff + n * 2048 + k * 1024); } while (0)
; #define PG8_MMA(ai, bj, At, Bt) do { __builtin_amdgcn_s_setprio(1); _Pragma("unroll") for (int m = 0; m < 4; ++m) _Pragma("unroll") for (int n = 0; n < 2; ++n) _Pragma("unroll") for (int k = 0; k < 2; ++k) \
;         acc[ai][bj][m][n] = __builtin_amdgcn_mfma_f32_16x16x32_bf16(Bt[n][k], At[m][k], acc[ai][bj][m][n], 0, 0, 0); __builtin_amdgcn_s_setprio(0); } while (0)
; #define PG8_WAIT_V(n) asm volatile("s_waitcnt vmcnt(" #n ")" ::: "memory")
; #define PG8_WAIT_L(n) asm volatile("s_waitcnt lgkmcnt(" #n ")" ::: "memory")
; #define PG8_BAR __builtin_amdgcn_s_barrier()
; #define PG8_SCHED __builtin_amdgcn_sched_barrier(0)
; template <class Epi, class Sched, bool ALIGN_EPI = false, bool SP2 = false>
; __device__ __forceinline__ void gemm_phase(PG8_LAS unsigned char* lds, const Gemm g, const Sched& S, const Epi& E, int wave0) {
;     ...
;             PG8_LDB(B0, 0, 0); PG8_LDB(B1, 0, 1); PG8_SCHED; PG8_LDA(At, 0, 0); PG8_STAGE(PG8_SA(1, 1), a1 + hstep, voffA);
;             PG8_WAIT_V(8); PG8_WAIT_L(0); PG8_BAR; PG8_MMA(0, 0, At, B0); PG8_MMA(0, 1, At, B1); PG8_BAR; PG8_SCHED;
;             PG8_LDA(At, 0, 1); PG8_STAGE(PG8_SB(0, 0), b2, voffB); PG8_STAGE(PG8_SB(0, 1), b2 + hstep, voffB); PG8_STAGE(PG8_SA(0, 0), a2, voffA);
;             PG8_WAIT_V(8); PG8_WAIT_L(0); PG8_BAR; PG8_MMA(1, 0, At, B0); PG8_MMA(1, 1, At, B1); PG8_BAR; PG8_SCHED;
.LBB0_374:
	s_add_i32 s74, 0, 0x10000
	s_add_i32 s72, 0, 0x14000
	v_add_u32_e32 v0, s74, v179
	v_add_u32_e32 v10, s72, v179
	ds_read_b128 v[12:15], v0
	ds_read_b128 v[16:19], v0 offset:1024
	ds_read_b128 v[20:23], v0 offset:2048
	ds_read_b128 v[24:27], v0 offset:3072
	ds_read_b128 v[28:31], v10
	ds_read_b128 v[32:35], v10 offset:1024
	ds_read_b128 v[36:39], v10 offset:2048
	ds_read_b128 v[40:43], v10 offset:3072
	s_add_u32 s0, s52, 0x18080
	s_addc_u32 s1, s53, 0
	s_add_i32 s77, s60, 0xc000
	v_lshl_add_u64 v[68:69], s[0:1], 0, v[168:169]
	s_mov_b32 m0, s77
	ds_read_b128 v[2:5], v181
	ds_read_b128 v[6:9], v181 offset:1024
	ds_read_b128 v[44:47], v181 offset:2048
	ds_read_b128 v[48:51], v181 offset:3072
	ds_read_b128 v[52:55], v181 offset:4096
	ds_read_b128 v[56:59], v181 offset:5120
	ds_read_b128 v[60:63], v181 offset:6144
	ds_read_b128 v[64:67], v181 offset:7168
	global_load_lds_dwordx4 v[68:69], off
	v_lshl_add_u64 v[68:69], s[0:1], 0, v[164:165]
	s_add_i32 s0, s60, 0xe000
	s_mov_b32 m0, s0
	s_nop 0
	global_load_lds_dwordx4 v[68:69], off
	s_waitcnt vmcnt(8)
	s_waitcnt lgkmcnt(0)
	s_barrier
	s_setprio 1
	s_waitcnt lgkmcnt(0)
	v_mfma_f32_16x16x32_bf16 v[68:71], v[12:15], v[2:5], 0
	v_mfma_f32_16x16x32_bf16 v[72:75], v[20:23], v[2:5], 0
	v_mfma_f32_16x16x32_bf16 v[76:79], v[12:15], v[44:47], 0
	v_mfma_f32_16x16x32_bf16 v[80:83], v[20:23], v[44:47], 0
	v_mfma_f32_16x16x32_bf16 v[84:87], v[12:15], v[52:55], 0
	v_mfma_f32_16x16x32_bf16 v[88:91], v[20:23], v[52:55], 0
	v_mfma_f32_16x16x32_bf16 v[92:95], v[12:15], v[60:63], 0
	v_mfma_f32_16x16x32_bf16 v[96:99], v[20:23], v[60:63], 0
	v_mfma_f32_16x16x32_bf16 v[68:71], v[16:19], v[6:9], v[68:71]
	v_mfma_f32_16x16x32_bf16 v[72:75], v[24:27], v[6:9], v[72:75]
	v_mfma_f32_16x16x32_bf16 v[76:79], v[16:19], v[48:51], v[76:79]
	v_mfma_f32_16x16x32_bf16 v[80:83], v[24:27], v[48:51], v[80:83]
	v_mfma_f32_16x16x32_bf16 v[84:87], v[16:19], v[56:59], v[84:87]
	v_mfma_f32_16x16x32_bf16 v[88:91], v[24:27], v[56:59], v[88:91]
	v_mfma_f32_16x16x32_bf16 v[92:95], v[16:19], v[64:67], v[92:95]
	v_mfma_f32_16x16x32_bf16 v[96:99], v[24:27], v[64:67], v[96:99]
	v_mfma_f32_16x16x32_bf16 v[100:103], v[28:31], v[2:5], 0
	v_mfma_f32_16x16x32_bf16 v[2:5], v[36:39], v[2:5], 0
	v_mfma_f32_16x16x32_bf16 v[104:107], v[40:43], v[6:9], v[2:5]
	v_mfma_f32_16x16x32_bf16 v[2:5], v[28:31], v[44:47], 0
	v_mfma_f32_16x16x32_bf16 v[108:111], v[32:35], v[48:51], v[2:5]
	v_mfma_f32_16x16x32_bf16 v[2:5], v[36:39], v[44:47], 0
	v_mfma_f32_16x16x32_bf16 v[44:47], v[40:43], v[48:51], v[2:5]
	v_mfma_f32_16x16x32_bf16 v[2:5], v[28:31], v[52:55], 0
	v_mfma_f32_16x16x32_bf16 v[48:51], v[32:35], v[56:59], v[2:5]
	v_mfma_f32_16x16x32_bf16 v[2:5], v[36:39], v[52:55], 0
	v_mfma_f32_16x16x32_bf16 v[52:55], v[40:43], v[56:59], v[2:5]
	v_mfma_f32_16x16x32_bf16 v[2:5], v[28:31], v[60:63], 0
	v_mfma_f32_16x16x32_bf16 v[56:59], v[32:35], v[64:67], v[2:5]
	v_mfma_f32_16x16x32_bf16 v[2:5], v[36:39], v[60:63], 0
	v_mfma_f32_16x16x32_bf16 v[100:103], v[32:35], v[6:9], v[100:103]
	v_mfma_f32_16x16x32_bf16 v[60:63], v[40:43], v[64:67], v[2:5]
	s_setprio 0
	s_barrier
	s_nop 3
	v_lshl_add_u64 v[2:3], s[54:55], 0, v[166:167]
	s_mov_b64 s[80:81], 0x100
	s_add_i32 s74, s74, s59
	v_lshl_add_u64 v[4:5], v[2:3], 0, s[80:81]
	s_mov_b32 m0, s74
	s_add_i32 s1, s74, 0x2000
	ds_read_b128 v[64:67], v181 offset:16384
	ds_read_b128 v[112:115], v181 offset:17408
	ds_read_b128 v[116:119], v181 offset:18432
	ds_read_b128 v[120:123], v181 offset:19456
	ds_read_b128 v[124:127], v181 offset:20480
	ds_read_b128 v[128:131], v181 offset:21504
	ds_read_b128 v[132:135], v181 offset:22528
	ds_read_b128 v[136:139], v181 offset:23552
	global_load_lds_dwordx4 v[4:5], off
	v_lshl_add_u64 v[4:5], s[54:55], 0, v[162:163]
	s_add_u32 s78, s54, 0x18100
	v_lshl_add_u64 v[6:7], v[4:5], 0, s[80:81]
	s_mov_b32 m0, s1
	s_addc_u32 s79, s55, 0
	s_add_i32 s72, s72, s59
	global_load_lds_dwordx4 v[6:7], off
	v_lshl_add_u64 v[6:7], s[78:79], 0, v[166:167]
	s_mov_b32 m0, s72
	s_add_i32 s73, s72, 0x2000
	global_load_lds_dwordx4 v[6:7], off
	v_lshl_add_u64 v[6:7], s[78:79], 0, v[162:163]
	s_mov_b32 m0, s73
	s_nop 0
	global_load_lds_dwordx4 v[6:7], off
	v_lshl_add_u64 v[6:7], s[52:53], 0, v[168:169]
	v_lshl_add_u64 v[8:9], v[6:7], 0, s[80:81]
	s_mov_b32 m0, s60
	s_nop 0
	global_load_lds_dwordx4 v[8:9], off
	v_lshl_add_u64 v[8:9], s[52:53], 0, v[164:165]
	v_lshl_add_u64 v[140:141], v[8:9], 0, s[80:81]
	s_mov_b32 m0, s61
	s_nop 0
	global_load_lds_dwordx4 v[140:141], off
	s_waitcnt vmcnt(8)
	s_waitcnt lgkmcnt(0)
	s_barrier
	s_setprio 1
	s_waitcnt lgkmcnt(0)
	v_mfma_f32_16x16x32_bf16 v[140:143], v[12:15], v[64:67], 0
	v_mfma_f32_16x16x32_bf16 v[148:151], v[12:15], v[116:119], 0
	v_mfma_f32_16x16x32_bf16 v[156:159], v[12:15], v[124:127], 0
	v_mfma_f32_16x16x32_bf16 v[12:15], v[12:15], v[132:135], 0
	v_mfma_f32_16x16x32_bf16 v[140:143], v[16:19], v[112:115], v[140:143]
	v_mfma_f32_16x16x32_bf16 v[144:147], v[20:23], v[64:67], 0
	v_mfma_f32_16x16x32_bf16 v[148:151], v[16:19], v[120:123], v[148:151]
	v_mfma_f32_16x16x32_bf16 v[152:155], v[20:23], v[116:119], 0
	v_mfma_f32_16x16x32_bf16 v[156:159], v[16:19], v[128:131], v[156:159]
	v_mfma_f32_16x16x32_bf16 v[174:177], v[20:23], v[124:127], 0
	v_mfma_f32_16x16x32_bf16 v[14:17], v[16:19], v[136:139], v[12:15]
	v_mfma_f32_16x16x32_bf16 v[18:21], v[20:23], v[132:135], 0
	v_mfma_f32_16x16x32_bf16 v[18:21], v[24:27], v[136:139], v[18:21]
	v_mfma_f32_16x16x32_bf16 v[144:147], v[24:27], v[112:115], v[144:147]
	v_mfma_f32_16x16x32_bf16 v[152:155], v[24:27], v[120:123], v[152:155]
	v_mfma_f32_16x16x32_bf16 v[174:177], v[24:27], v[128:131], v[174:177]
	v_mfma_f32_16x16x32_bf16 v[22:25], v[28:31], v[64:67], 0
	v_mfma_f32_16x16x32_bf16 v[64:67], v[36:39], v[64:67], 0
	v_mfma_f32_16x16x32_bf16 v[22:25], v[32:35], v[112:115], v[22:25]
	v_mfma_f32_16x16x32_bf16 v[64:67], v[40:43], v[112:115], v[64:67]
	v_mfma_f32_16x16x32_bf16 v[112:115], v[28:31], v[116:119], 0
	v_mfma_f32_16x16x32_bf16 v[116:119], v[36:39], v[116:119], 0
	v_mfma_f32_16x16x32_bf16 v[112:115], v[32:35], v[120:123], v[112:115]
	v_mfma_f32_16x16x32_bf16 v[116:119], v[40:43], v[120:123], v[116:119]
	v_mfma_f32_16x16x32_bf16 v[120:123], v[28:31], v[124:127], 0
	v_mfma_f32_16x16x32_bf16 v[26:29], v[28:31], v[132:135], 0
	v_mfma_f32_16x16x32_bf16 v[120:123], v[32:35], v[128:131], v[120:123]
	v_mfma_f32_16x16x32_bf16 v[124:127], v[36:39], v[124:127], 0
	v_mfma_f32_16x16x32_bf16 v[26:29], v[32:35], v[136:139], v[26:29]
	v_mfma_f32_16x16x32_bf16 v[30:33], v[36:39], v[132:135], 0
	v_mfma_f32_16x16x32_bf16 v[124:127], v[40:43], v[128:131], v[124:127]
	v_mfma_f32_16x16x32_bf16 v[30:33], v[40:43], v[136:139], v[30:33]
	s_setprio 0
	s_barrier
; #define PG8_STAGE(bufoff, gbase, voff) do { _Pragma("unroll") for (int _i = 0; _i < 2; ++_i) \
;         __builtin_amdgcn_global_load_lds((const unsigned*)((const char*)(gbase) + (voff)[_i]), (PG8_LAS unsigned*)(lds + (bufoff) + ldsw + _i * 8192), 16, 0, 0); } while (0)
; #define PG8_LDA(dst, b, h) do { _Pragma("unroll") for (int m = 0; m < 4; ++m) _Pragma("unroll") for (int k = 0; k < 2; ++k) dst[m][k] = *(const PG8_LAS bf16x8*)(lds + PG8_SA(b, h) + aoff + m * 2048 + k * 1024); } while (0)
; #define PG8_LDB(dst, b, h) do { _Pragma("unroll") for (int n = 0; n < 2; ++n) _Pragma("unroll") for (int k = 0; k < 2; ++k) dst[n][k] = *(const PG8_LAS bf16x8*)(lds + PG8_SB(b, h) + boff + n * 2048 + k * 1024); } while (0)
; #define PG8_MMA(ai, bj, At, Bt) do { __builtin_amdgcn_s_setprio(1); _Pragma("unroll") for (int m = 0; m < 4; ++m) _Pragma("unroll") for (int n = 0; n < 2; ++n) _Pragma("unroll") for (int k = 0; k < 2; ++k) \
;         acc[ai][bj][m][n] = __builtin_amdgcn_mfma_f32_16x16x32_bf16(Bt[n][k], At[m][k], acc[ai][bj][m][n], 0, 0, 0); __builtin_amdgcn_s_setprio(0); } while (0)
; #define PG8_WAIT_V(n) asm volatile("s_waitcnt vmcnt(" #n ")" ::: "memory")
; #define PG8_WAIT_L(n) asm volatile("s_waitcnt lgkmcnt(" #n ")" ::: "memory")
; #define PG8_BAR __builtin_amdgcn_s_barrier()
; #define PG8_SCHED __builtin_amdgcn_sched_barrier(0)
; template <class Epi, class Sched, bool ALIGN_EPI = false, bool SP2 = false>
; __device__ __forceinline__ void gemm_phase(PG8_LAS unsigned char* lds, const Gemm g, const Sched& S, const Epi& E, int wave0) {
;     ...
;             PG8_LDB(B0, 1, 0); PG8_LDB(B1, 1, 1); PG8_SCHED; PG8_LDA(At, 1, 0); PG8_STAGE(PG8_SA(0, 1), a2 + hstep, voffA);
;             PG8_WAIT_V(8); PG8_WAIT_L(0); PG8_BAR; PG8_MMA(0, 0, At, B0); PG8_MMA(0, 1, At, B1); PG8_BAR; PG8_SCHED;
;             PG8_LDA(At, 1, 1); PG8_STAGE(PG8_SB(1, 0), b3, voffB); PG8_STAGE(PG8_SB(1, 1), b3 + hstep, voffB); PG8_STAGE(PG8_SA(1, 0), a3, voffA);
	s_add_i32 s75, 0, 0x18000
	s_add_i32 s76, 0, 0x1c000
	v_add_u32_e32 v11, s75, v179
	v_add_u32_e32 v12, s76, v179
	ds_read_b128 v[34:37], v11
	ds_read_b128 v[38:41], v11 offset:1024
	ds_read_b128 v[128:131], v11 offset:2048
	ds_read_b128 v[132:135], v11 offset:3072
	ds_read_b128 v[136:139], v12
	ds_read_b128 v[182:185], v12 offset:1024
	ds_read_b128 v[186:189], v12 offset:2048
	ds_read_b128 v[190:193], v12 offset:3072
	s_add_u32 s78, s52, 0x18100
	s_addc_u32 s79, s53, 0
	s_mov_b32 m0, s62
	v_lshl_add_u64 v[42:43], s[78:79], 0, v[168:169]
	ds_read_b128 v[194:197], v181 offset:32768
	ds_read_b128 v[198:201], v181 offset:33792
	ds_read_b128 v[202:205], v181 offset:34816
	ds_read_b128 v[218:221], v181 offset:35840
	ds_read_b128 v[222:225], v181 offset:36864
	ds_read_b128 v[226:229], v181 offset:37888
	ds_read_b128 v[238:241], v181 offset:38912
	ds_read_b128 v[242:245], v181 offset:39936
	global_load_lds_dwordx4 v[42:43], off
	v_lshl_add_u64 v[42:43], s[78:79], 0, v[164:165]
	s_mov_b32 m0, s63
	s_nop 0
	global_load_lds_dwordx4 v[42:43], off
	s_waitcnt vmcnt(8)
	s_waitcnt lgkmcnt(0)
	s_barrier
	s_setprio 1
	s_waitcnt lgkmcnt(0)
	v_mfma_f32_16x16x32_bf16 v[68:71], v[34:37], v[194:197], v[68:71]
	v_mfma_f32_16x16x32_bf16 v[72:75], v[128:131], v[194:197], v[72:75]
	v_mfma_f32_16x16x32_bf16 v[76:79], v[34:37], v[202:205], v[76:79]
	v_mfma_f32_16x16x32_bf16 v[80:83], v[128:131], v[202:205], v[80:83]
	v_mfma_f32_16x16x32_bf16 v[84:87], v[34:37], v[222:225], v[84:87]
	v_mfma_f32_16x16x32_bf16 v[88:91], v[128:131], v[222:225], v[88:91]
	v_mfma_f32_16x16x32_bf16 v[92:95], v[34:37], v[238:241], v[92:95]
	v_mfma_f32_16x16x32_bf16 v[96:99], v[128:131], v[238:241], v[96:99]
	v_mfma_f32_16x16x32_bf16 v[68:71], v[38:41], v[198:201], v[68:71]
	v_mfma_f32_16x16x32_bf16 v[72:75], v[132:135], v[198:201], v[72:75]
	v_mfma_f32_16x16x32_bf16 v[76:79], v[38:41], v[218:221], v[76:79]
	v_mfma_f32_16x16x32_bf16 v[80:83], v[132:135], v[218:221], v[80:83]
	v_mfma_f32_16x16x32_bf16 v[84:87], v[38:41], v[226:229], v[84:87]
	v_mfma_f32_16x16x32_bf16 v[88:91], v[132:135], v[226:229], v[88:91]
	v_mfma_f32_16x16x32_bf16 v[92:95], v[38:41], v[242:245], v[92:95]
	v_mfma_f32_16x16x32_bf16 v[96:99], v[132:135], v[242:245], v[96:99]
	v_mfma_f32_16x16x32_bf16 v[100:103], v[136:139], v[194:197], v[100:103]
	v_mfma_f32_16x16x32_bf16 v[104:107], v[186:189], v[194:197], v[104:107]
	v_mfma_f32_16x16x32_bf16 v[108:111], v[136:139], v[202:205], v[108:111]
	v_mfma_f32_16x16x32_bf16 v[42:45], v[186:189], v[202:205], v[44:47]
	v_mfma_f32_16x16x32_bf16 v[46:49], v[136:139], v[222:225], v[48:51]
	v_mfma_f32_16x16x32_bf16 v[50:53], v[186:189], v[222:225], v[52:55]
	v_mfma_f32_16x16x32_bf16 v[54:57], v[136:139], v[238:241], v[56:59]
	v_mfma_f32_16x16x32_bf16 v[58:61], v[186:189], v[238:241], v[60:63]
	v_mfma_f32_16x16x32_bf16 v[100:103], v[182:185], v[198:201], v[100:103]
	v_mfma_f32_16x16x32_bf16 v[104:107], v[190:193], v[198:201], v[104:107]
	v_mfma_f32_16x16x32_bf16 v[108:111], v[182:185], v[218:221], v[108:111]
	v_mfma_f32_16x16x32_bf16 v[42:45], v[190:193], v[218:221], v[42:45]
	v_mfma_f32_16x16x32_bf16 v[46:49], v[182:185], v[226:229], v[46:49]
	v_mfma_f32_16x16x32_bf16 v[50:53], v[190:193], v[226:229], v[50:53]
	v_mfma_f32_16x16x32_bf16 v[54:57], v[182:185], v[242:245], v[54:57]
	v_mfma_f32_16x16x32_bf16 v[58:61], v[190:193], v[242:245], v[58:61]
	s_setprio 0
	s_barrier
	s_add_i32 s79, s75, s59
	s_mov_b64 s[82:83], 0x180
	s_add_i32 s75, s79, 0x2000
	v_lshl_add_u64 v[62:63], v[2:3], 0, s[82:83]
	s_mov_b32 m0, s79
	s_add_u32 s80, s54, 0x18180
	ds_read_b128 v[194:197], v181 offset:49152
	ds_read_b128 v[198:201], v181 offset:50176
	ds_read_b128 v[202:205], v181 offset:51200
	ds_read_b128 v[218:221], v181 offset:52224
	ds_read_b128 v[222:225], v181 offset:53248
	ds_read_b128 v[226:229], v181 offset:54272
	ds_read_b128 v[238:241], v181 offset:55296
	ds_read_b128 v[242:245], v181 offset:56320
	global_load_lds_dwordx4 v[62:63], off
	v_lshl_add_u64 v[62:63], v[4:5], 0, s[82:83]
	s_mov_b32 m0, s75
	s_addc_u32 s81, s55, 0
	s_add_i32 s76, s76, s59
	global_load_lds_dwordx4 v[62:63], off
	v_lshl_add_u64 v[62:63], s[80:81], 0, v[166:167]
	s_mov_b32 m0, s76
	s_add_i32 s78, s76, 0x2000
	global_load_lds_dwordx4 v[62:63], off
	v_lshl_add_u64 v[62:63], s[80:81], 0, v[162:163]
	s_mov_b32 m0, s78
	s_nop 0
	global_load_lds_dwordx4 v[62:63], off
	v_lshl_add_u64 v[62:63], v[6:7], 0, s[82:83]
	s_mov_b32 m0, s66
	s_nop 0
	global_load_lds_dwordx4 v[62:63], off
	v_lshl_add_u64 v[62:63], v[8:9], 0, s[82:83]
	s_mov_b32 m0, s67
	s_nop 0
	global_load_lds_dwordx4 v[62:63], off
	s_waitcnt vmcnt(8)
	s_waitcnt lgkmcnt(0)
	s_barrier
; #define PG8_STAGE(bufoff, gbase, voff) do { _Pragma("unroll") for (int _i = 0; _i < 2; ++_i) \
;         __builtin_amdgcn_global_load_lds((const unsigned*)((const char*)(gbase) + (voff)[_i]), (PG8_LAS unsigned*)(lds + (bufoff) + ldsw + _i * 8192), 16, 0, 0); } while (0)
; #define PG8_LDA(dst, b, h) do { _Pragma("unroll") for (int m = 0; m < 4; ++m) _Pragma("unroll") for (int k = 0; k < 2; ++k) dst[m][k] = *(const PG8_LAS bf16x8*)(lds + PG8_SA(b, h) + aoff + m * 2048 + k * 1024); } while (0)
; #define PG8_LDB(dst, b, h) do { _Pragma("unroll") for (int n = 0; n < 2; ++n) _Pragma("unroll") for (int k = 0; k < 2; ++k) dst[n][k] = *(const PG8_LAS bf16x8*)(lds + PG8_SB(b, h) + boff + n * 2048 + k * 1024); } while (0)
; #define PG8_MMA(ai, bj, At, Bt) do { __builtin_amdgcn_s_setprio(1); _Pragma("unroll") for (int m = 0; m < 4; ++m) _Pragma("unroll") for (int n = 0; n < 2; ++n) _Pragma("unroll") for (int k = 0; k < 2; ++k) \
;         acc[ai][bj][m][n] = __builtin_amdgcn_mfma_f32_16x16x32_bf16(Bt[n][k], At[m][k], acc[ai][bj][m][n], 0, 0, 0); __builtin_amdgcn_s_setprio(0); } while (0)
; #define PG8_BAR __builtin_amdgcn_s_barrier()
; template <class Epi, class Sched, bool ALIGN_EPI = false, bool SP2 = false>
; __device__ __forceinline__ void gemm_phase(PG8_LAS unsigned char* lds, const Gemm g, const Sched& S, const Epi& E, int wave0) {
;     ...
;             PG8_LDB(B0, 0, 0); PG8_LDB(B1, 0, 1); PG8_SCHED; PG8_LDA(At, 0, 0); PG8_STAGE(PG8_SA(1, 1), a1 + hstep, voffA);
;             PG8_WAIT_V(8); PG8_WAIT_L(0); PG8_BAR; PG8_MMA(0, 0, At, B0); PG8_MMA(0, 1, At, B1); PG8_BAR; PG8_SCHED;
;             PG8_LDA(At, 0, 1); PG8_STAGE(PG8_SB(0, 0), b2, voffB); PG8_STAGE(PG8_SB(0, 1), b2 + hstep, voffB); PG8_STAGE(PG8_SA(0, 0), a2, voffA);
;             PG8_WAIT_V(8); PG8_WAIT_L(0); PG8_BAR; PG8_MMA(1, 0, At, B0); PG8_MMA(1, 1, At, B1); PG8_BAR; PG8_SCHED;
;             PG8_LDB(B0, 1, 0); PG8_LDB(B1, 1, 1); PG8_SCHED; PG8_LDA(At, 1, 0); PG8_STAGE(PG8_SA(0, 1), a2 + hstep, voffA);
;             PG8_WAIT_V(8); PG8_WAIT_L(0); PG8_BAR; PG8_MMA(0, 0, At, B0); PG8_MMA(0, 1, At, B1); PG8_BAR; PG8_SCHED;
;             PG8_LDA(At, 1, 1); PG8_STAGE(PG8_SB(1, 0), b3, voffB); PG8_STAGE(PG8_SB(1, 1), b3 + hstep, voffB); PG8_STAGE(PG8_SA(1, 0), a3, voffA);
;             PG8_WAIT_V(8); PG8_WAIT_L(0); PG8_BAR; PG8_MMA(1, 0, At, B0); PG8_MMA(1, 1, At, B1); PG8_BAR; PG8_SCHED;
	s_setprio 1
	s_waitcnt lgkmcnt(0)
	v_mfma_f32_16x16x32_bf16 v[14:17], v[34:37], v[238:241], v[14:17]
	v_mfma_f32_16x16x32_bf16 v[18:21], v[128:131], v[238:241], v[18:21]
	v_mfma_f32_16x16x32_bf16 v[140:143], v[34:37], v[194:197], v[140:143]
	v_mfma_f32_16x16x32_bf16 v[144:147], v[128:131], v[194:197], v[144:147]
	v_mfma_f32_16x16x32_bf16 v[148:151], v[34:37], v[202:205], v[148:151]
	v_mfma_f32_16x16x32_bf16 v[152:155], v[128:131], v[202:205], v[152:155]
	v_mfma_f32_16x16x32_bf16 v[156:159], v[34:37], v[222:225], v[156:159]
	v_mfma_f32_16x16x32_bf16 v[174:177], v[128:131], v[222:225], v[174:177]
	v_mfma_f32_16x16x32_bf16 v[14:17], v[38:41], v[242:245], v[14:17]
	v_mfma_f32_16x16x32_bf16 v[18:21], v[132:135], v[242:245], v[18:21]
	v_mfma_f32_16x16x32_bf16 v[140:143], v[38:41], v[198:201], v[140:143]
	v_mfma_f32_16x16x32_bf16 v[144:147], v[132:135], v[198:201], v[144:147]
	v_mfma_f32_16x16x32_bf16 v[148:151], v[38:41], v[218:221], v[148:151]
	v_mfma_f32_16x16x32_bf16 v[152:155], v[132:135], v[218:221], v[152:155]
	v_mfma_f32_16x16x32_bf16 v[156:159], v[38:41], v[226:229], v[156:159]
	v_mfma_f32_16x16x32_bf16 v[174:177], v[132:135], v[226:229], v[174:177]
	v_mfma_f32_16x16x32_bf16 v[22:25], v[136:139], v[194:197], v[22:25]
	v_mfma_f32_16x16x32_bf16 v[34:37], v[186:189], v[194:197], v[64:67]
	v_mfma_f32_16x16x32_bf16 v[38:41], v[136:139], v[202:205], v[112:115]
	v_mfma_f32_16x16x32_bf16 v[62:65], v[186:189], v[202:205], v[116:119]
	v_mfma_f32_16x16x32_bf16 v[112:115], v[136:139], v[222:225], v[120:123]
	v_mfma_f32_16x16x32_bf16 v[116:119], v[186:189], v[222:225], v[124:127]
	v_mfma_f32_16x16x32_bf16 v[26:29], v[136:139], v[238:241], v[26:29]
	v_mfma_f32_16x16x32_bf16 v[30:33], v[186:189], v[238:241], v[30:33]
	v_mfma_f32_16x16x32_bf16 v[22:25], v[182:185], v[198:201], v[22:25]
	v_mfma_f32_16x16x32_bf16 v[34:37], v[190:193], v[198:201], v[34:37]
	v_mfma_f32_16x16x32_bf16 v[38:41], v[182:185], v[218:221], v[38:41]
	v_mfma_f32_16x16x32_bf16 v[62:65], v[190:193], v[218:221], v[62:65]
	v_mfma_f32_16x16x32_bf16 v[112:115], v[182:185], v[226:229], v[112:115]
	v_mfma_f32_16x16x32_bf16 v[116:119], v[190:193], v[226:229], v[116:119]
	v_mfma_f32_16x16x32_bf16 v[26:29], v[182:185], v[242:245], v[26:29]
	v_mfma_f32_16x16x32_bf16 v[30:33], v[190:193], v[242:245], v[30:33]
	s_setprio 0
	s_barrier
	ds_read_b128 v[120:123], v0
	ds_read_b128 v[124:127], v0 offset:1024
	ds_read_b128 v[128:131], v0 offset:2048
	ds_read_b128 v[132:135], v0 offset:3072
	ds_read_b128 v[136:139], v10
	ds_read_b128 v[182:185], v10 offset:1024
	ds_read_b128 v[186:189], v10 offset:2048
	ds_read_b128 v[190:193], v10 offset:3072
	s_add_u32 s80, s52, 0x18180
	s_addc_u32 s81, s53, 0
	s_mov_b32 m0, s77
	v_lshl_add_u64 v[66:67], s[80:81], 0, v[168:169]
	ds_read_b128 v[194:197], v181
	ds_read_b128 v[198:201], v181 offset:1024
	ds_read_b128 v[202:205], v181 offset:2048
	ds_read_b128 v[218:221], v181 offset:3072
	ds_read_b128 v[222:225], v181 offset:4096
	ds_read_b128 v[226:229], v181 offset:5120
	ds_read_b128 v[238:241], v181 offset:6144
	ds_read_b128 v[242:245], v181 offset:7168
	global_load_lds_dwordx4 v[66:67], off
	v_lshl_add_u64 v[66:67], s[80:81], 0, v[164:165]
	s_mov_b32 m0, s0
	s_nop 0
	global_load_lds_dwordx4 v[66:67], off
	s_waitcnt vmcnt(8)
	s_waitcnt lgkmcnt(0)
	s_barrier
	s_setprio 1
	s_waitcnt lgkmcnt(0)
	v_mfma_f32_16x16x32_bf16 v[66:69], v[120:123], v[194:197], v[68:71]
	v_mfma_f32_16x16x32_bf16 v[70:73], v[128:131], v[194:197], v[72:75]
	v_mfma_f32_16x16x32_bf16 v[74:77], v[120:123], v[202:205], v[76:79]
	v_mfma_f32_16x16x32_bf16 v[78:81], v[128:131], v[202:205], v[80:83]
	v_mfma_f32_16x16x32_bf16 v[82:85], v[120:123], v[222:225], v[84:87]
	v_mfma_f32_16x16x32_bf16 v[86:89], v[128:131], v[222:225], v[88:91]
	v_mfma_f32_16x16x32_bf16 v[90:93], v[120:123], v[238:241], v[92:95]
	v_mfma_f32_16x16x32_bf16 v[94:97], v[128:131], v[238:241], v[96:99]
	v_mfma_f32_16x16x32_bf16 v[66:69], v[124:127], v[198:201], v[66:69]
	v_mfma_f32_16x16x32_bf16 v[70:73], v[132:135], v[198:201], v[70:73]
	v_mfma_f32_16x16x32_bf16 v[74:77], v[124:127], v[218:221], v[74:77]
	v_mfma_f32_16x16x32_bf16 v[78:81], v[132:135], v[218:221], v[78:81]
	v_mfma_f32_16x16x32_bf16 v[82:85], v[124:127], v[226:229], v[82:85]
	v_mfma_f32_16x16x32_bf16 v[86:89], v[132:135], v[226:229], v[86:89]
	v_mfma_f32_16x16x32_bf16 v[90:93], v[124:127], v[242:245], v[90:93]
	v_mfma_f32_16x16x32_bf16 v[94:97], v[132:135], v[242:245], v[94:97]
	v_mfma_f32_16x16x32_bf16 v[98:101], v[136:139], v[194:197], v[100:103]
	v_mfma_f32_16x16x32_bf16 v[102:105], v[186:189], v[194:197], v[104:107]
	v_mfma_f32_16x16x32_bf16 v[106:109], v[136:139], v[202:205], v[108:111]
	v_mfma_f32_16x16x32_bf16 v[42:45], v[186:189], v[202:205], v[42:45]
	v_mfma_f32_16x16x32_bf16 v[46:49], v[136:139], v[222:225], v[46:49]
	v_mfma_f32_16x16x32_bf16 v[50:53], v[186:189], v[222:225], v[50:53]
	v_mfma_f32_16x16x32_bf16 v[54:57], v[136:139], v[238:241], v[54:57]
	v_mfma_f32_16x16x32_bf16 v[58:61], v[186:189], v[238:241], v[58:61]
	v_mfma_f32_16x16x32_bf16 v[98:101], v[182:185], v[198:201], v[98:101]
	v_mfma_f32_16x16x32_bf16 v[102:105], v[190:193], v[198:201], v[102:105]
	v_mfma_f32_16x16x32_bf16 v[106:109], v[182:185], v[218:221], v[106:109]
	v_mfma_f32_16x16x32_bf16 v[42:45], v[190:193], v[218:221], v[42:45]
	v_mfma_f32_16x16x32_bf16 v[46:49], v[182:185], v[226:229], v[46:49]
	v_mfma_f32_16x16x32_bf16 v[50:53], v[190:193], v[226:229], v[50:53]
	v_mfma_f32_16x16x32_bf16 v[54:57], v[182:185], v[242:245], v[54:57]
	v_mfma_f32_16x16x32_bf16 v[58:61], v[190:193], v[242:245], v[58:61]
	s_setprio 0
	s_barrier
; #define PG8_STAGE(bufoff, gbase, voff) do { _Pragma("unroll") for (int _i = 0; _i < 2; ++_i) \
;         __builtin_amdgcn_global_load_lds((const unsigned*)((const char*)(gbase) + (voff)[_i]), (PG8_LAS unsigned*)(lds + (bufoff) + ldsw + _i * 8192), 16, 0, 0); } while (0)
; #define PG8_LDA(dst, b, h) do { _Pragma("unroll") for (int m = 0; m < 4; ++m) _Pragma("unroll") for (int k = 0; k < 2; ++k) dst[m][k] = *(const PG8_LAS bf16x8*)(lds + PG8_SA(b, h) + aoff + m * 2048 + k * 1024); } while (0)
; #define PG8_LDB(dst, b, h) do { _Pragma("unroll") for (int n = 0; n < 2; ++n) _Pragma("unroll") for (int k = 0; k < 2; ++k) dst[n][k] = *(const PG8_LAS bf16x8*)(lds + PG8_SB(b, h) + boff + n * 2048 + k * 1024); } while (0)
; #define PG8_MMA(ai, bj, At, Bt) do { __builtin_amdgcn_s_setprio(1); _Pragma("unroll") for (int m = 0; m < 4; ++m) _Pragma("unroll") for (int n = 0; n < 2; ++n) _Pragma("unroll") for (int k = 0; k < 2; ++k) \
;         acc[ai][bj][m][n] = __builtin_amdgcn_mfma_f32_16x16x32_bf16(Bt[n][k], At[m][k], acc[ai][bj][m][n], 0, 0, 0); __builtin_amdgcn_s_setprio(0); } while (0)
; #define PG8_WAIT_V(n) asm volatile("s_waitcnt vmcnt(" #n ")" ::: "memory")
; #define PG8_WAIT_L(n) asm volatile("s_waitcnt lgkmcnt(" #n ")" ::: "memory")
; #define PG8_BAR __builtin_amdgcn_s_barrier()
; #define PG8_SCHED __builtin_amdgcn_sched_barrier(0)
; template <class Epi, class Sched, bool ALIGN_EPI = false, bool SP2 = false>
; __device__ __forceinline__ void gemm_phase(PG8_LAS unsigned char* lds, const Gemm g, const Sched& S, const Epi& E, int wave0) {
;     ...
;             PG8_LDA(At, 0, 1); PG8_STAGE(PG8_SB(0, 0), b2, voffB); PG8_STAGE(PG8_SB(0, 1), b2 + hstep, voffB); PG8_STAGE(PG8_SA(0, 0), a2, voffA);
;             PG8_WAIT_V(8); PG8_WAIT_L(0); PG8_BAR; PG8_MMA(1, 0, At, B0); PG8_MMA(1, 1, At, B1); PG8_BAR; PG8_SCHED;
;             PG8_LDB(B0, 1, 0); PG8_LDB(B1, 1, 1); PG8_SCHED; PG8_LDA(At, 1, 0); PG8_STAGE(PG8_SA(0, 1), a2 + hstep, voffA);
	s_mov_b64 s[82:83], 0x200
	s_mov_b32 m0, s74
	v_lshl_add_u64 v[110:111], v[2:3], 0, s[82:83]
	s_add_u32 s80, s54, 0x18200
	ds_read_b128 v[194:197], v181 offset:16384
	ds_read_b128 v[198:201], v181 offset:17408
	ds_read_b128 v[202:205], v181 offset:18432
	ds_read_b128 v[218:221], v181 offset:19456
	ds_read_b128 v[222:225], v181 offset:20480
	ds_read_b128 v[226:229], v181 offset:21504
	ds_read_b128 v[238:241], v181 offset:22528
	ds_read_b128 v[242:245], v181 offset:23552
	global_load_lds_dwordx4 v[110:111], off
	v_lshl_add_u64 v[110:111], v[4:5], 0, s[82:83]
	s_mov_b32 m0, s1
	s_addc_u32 s81, s55, 0
	global_load_lds_dwordx4 v[110:111], off
	v_lshl_add_u64 v[110:111], s[80:81], 0, v[166:167]
	s_mov_b32 m0, s72
	s_nop 0
	global_load_lds_dwordx4 v[110:111], off
	v_lshl_add_u64 v[110:111], s[80:81], 0, v[162:163]
	s_mov_b32 m0, s73
	s_nop 0
	global_load_lds_dwordx4 v[110:111], off
	v_lshl_add_u64 v[110:111], v[6:7], 0, s[82:83]
	s_mov_b32 m0, s60
	s_nop 0
	global_load_lds_dwordx4 v[110:111], off
	v_lshl_add_u64 v[110:111], v[8:9], 0, s[82:83]
	s_mov_b32 m0, s61
	s_nop 0
	global_load_lds_dwordx4 v[110:111], off
	s_waitcnt vmcnt(8)
	s_waitcnt lgkmcnt(0)
	s_barrier
	s_setprio 1
	s_waitcnt lgkmcnt(0)
	v_mfma_f32_16x16x32_bf16 v[14:17], v[120:123], v[238:241], v[14:17]
	v_mfma_f32_16x16x32_bf16 v[18:21], v[128:131], v[238:241], v[18:21]
	v_mfma_f32_16x16x32_bf16 v[140:143], v[120:123], v[194:197], v[140:143]
	v_mfma_f32_16x16x32_bf16 v[144:147], v[128:131], v[194:197], v[144:147]
	v_mfma_f32_16x16x32_bf16 v[148:151], v[120:123], v[202:205], v[148:151]
	v_mfma_f32_16x16x32_bf16 v[152:155], v[128:131], v[202:205], v[152:155]
	v_mfma_f32_16x16x32_bf16 v[156:159], v[120:123], v[222:225], v[156:159]
	v_mfma_f32_16x16x32_bf16 v[174:177], v[128:131], v[222:225], v[174:177]
	v_mfma_f32_16x16x32_bf16 v[14:17], v[124:127], v[242:245], v[14:17]
	v_mfma_f32_16x16x32_bf16 v[18:21], v[132:135], v[242:245], v[18:21]
	v_mfma_f32_16x16x32_bf16 v[140:143], v[124:127], v[198:201], v[140:143]
	v_mfma_f32_16x16x32_bf16 v[144:147], v[132:135], v[198:201], v[144:147]
	v_mfma_f32_16x16x32_bf16 v[148:151], v[124:127], v[218:221], v[148:151]
	v_mfma_f32_16x16x32_bf16 v[152:155], v[132:135], v[218:221], v[152:155]
	v_mfma_f32_16x16x32_bf16 v[156:159], v[124:127], v[226:229], v[156:159]
	v_mfma_f32_16x16x32_bf16 v[174:177], v[132:135], v[226:229], v[174:177]
	v_mfma_f32_16x16x32_bf16 v[22:25], v[136:139], v[194:197], v[22:25]
	v_mfma_f32_16x16x32_bf16 v[34:37], v[186:189], v[194:197], v[34:37]
	v_mfma_f32_16x16x32_bf16 v[38:41], v[136:139], v[202:205], v[38:41]
	v_mfma_f32_16x16x32_bf16 v[62:65], v[186:189], v[202:205], v[62:65]
	v_mfma_f32_16x16x32_bf16 v[110:113], v[136:139], v[222:225], v[112:115]
	v_mfma_f32_16x16x32_bf16 v[114:117], v[186:189], v[222:225], v[116:119]
	v_mfma_f32_16x16x32_bf16 v[26:29], v[136:139], v[238:241], v[26:29]
	v_mfma_f32_16x16x32_bf16 v[30:33], v[186:189], v[238:241], v[30:33]
	v_mfma_f32_16x16x32_bf16 v[22:25], v[182:185], v[198:201], v[22:25]
	v_mfma_f32_16x16x32_bf16 v[34:37], v[190:193], v[198:201], v[34:37]
	v_mfma_f32_16x16x32_bf16 v[38:41], v[182:185], v[218:221], v[38:41]
	v_mfma_f32_16x16x32_bf16 v[62:65], v[190:193], v[218:221], v[62:65]
	v_mfma_f32_16x16x32_bf16 v[110:113], v[182:185], v[226:229], v[110:113]
	v_mfma_f32_16x16x32_bf16 v[114:117], v[190:193], v[226:229], v[114:117]
	v_mfma_f32_16x16x32_bf16 v[26:29], v[182:185], v[242:245], v[26:29]
	v_mfma_f32_16x16x32_bf16 v[30:33], v[190:193], v[242:245], v[30:33]
	s_setprio 0
	s_barrier
	ds_read_b128 v[118:121], v11
	ds_read_b128 v[122:125], v11 offset:1024
	ds_read_b128 v[126:129], v11 offset:2048
	ds_read_b128 v[130:133], v11 offset:3072
	ds_read_b128 v[134:137], v12
	ds_read_b128 v[182:185], v12 offset:1024
	ds_read_b128 v[186:189], v12 offset:2048
	ds_read_b128 v[190:193], v12 offset:3072
	s_add_u32 s80, s52, 0x18200
	s_addc_u32 s81, s53, 0
	s_mov_b32 m0, s62
	v_lshl_add_u64 v[138:139], s[80:81], 0, v[168:169]
	ds_read_b128 v[194:197], v181 offset:32768
	ds_read_b128 v[198:201], v181 offset:33792
	ds_read_b128 v[202:205], v181 offset:34816
	ds_read_b128 v[218:221], v181 offset:35840
	ds_read_b128 v[222:225], v181 offset:36864
	ds_read_b128 v[226:229], v181 offset:37888
	ds_read_b128 v[238:241], v181 offset:38912
	ds_read_b128 v[242:245], v181 offset:39936
	global_load_lds_dwordx4 v[138:139], off
	v_lshl_add_u64 v[138:139], s[80:81], 0, v[164:165]
	s_mov_b32 m0, s63
	s_nop 0
	global_load_lds_dwordx4 v[138:139], off
	s_waitcnt vmcnt(8)
	s_waitcnt lgkmcnt(0)
	s_barrier
; #define PG8_STAGE(bufoff, gbase, voff) do { _Pragma("unroll") for (int _i = 0; _i < 2; ++_i) \
;         __builtin_amdgcn_global_load_lds((const unsigned*)((const char*)(gbase) + (voff)[_i]), (PG8_LAS unsigned*)(lds + (bufoff) + ldsw + _i * 8192), 16, 0, 0); } while (0)
; #define PG8_LDA(dst, b, h) do { _Pragma("unroll") for (int m = 0; m < 4; ++m) _Pragma("unroll") for (int k = 0; k < 2; ++k) dst[m][k] = *(const PG8_LAS bf16x8*)(lds + PG8_SA(b, h) + aoff + m * 2048 + k * 1024); } while (0)
; #define PG8_MMA(ai, bj, At, Bt) do { __builtin_amdgcn_s_setprio(1); _Pragma("unroll") for (int m = 0; m < 4; ++m) _Pragma("unroll") for (int n = 0; n < 2; ++n) _Pragma("unroll") for (int k = 0; k < 2; ++k) \
;         acc[ai][bj][m][n] = __builtin_amdgcn_mfma_f32_16x16x32_bf16(Bt[n][k], At[m][k], acc[ai][bj][m][n], 0, 0, 0); __builtin_amdgcn_s_setprio(0); } while (0)
; #define PG8_WAIT_V(n) asm volatile("s_waitcnt vmcnt(" #n ")" ::: "memory")
; #define PG8_WAIT_L(n) asm volatile("s_waitcnt lgkmcnt(" #n ")" ::: "memory")
; #define PG8_BAR __builtin_amdgcn_s_barrier()
; #define PG8_SCHED __builtin_amdgcn_sched_barrier(0)
; template <class Epi, class Sched, bool ALIGN_EPI = false, bool SP2 = false>
; __device__ __forceinline__ void gemm_phase(PG8_LAS unsigned char* lds, const Gemm g, const Sched& S, const Epi& E, int wave0) {
;     ...
;             PG8_WAIT_V(8); PG8_WAIT_L(0); PG8_BAR; PG8_MMA(0, 0, At, B0); PG8_MMA(0, 1, At, B1); PG8_BAR; PG8_SCHED;
;             PG8_LDA(At, 1, 1); PG8_STAGE(PG8_SB(1, 0), b3, voffB); PG8_STAGE(PG8_SB(1, 1), b3 + hstep, voffB); PG8_STAGE(PG8_SA(1, 0), a3, voffA);
;             PG8_WAIT_V(8); PG8_WAIT_L(0); PG8_BAR; PG8_MMA(1, 0, At, B0); PG8_MMA(1, 1, At, B1); PG8_BAR; PG8_SCHED;
	s_setprio 1
	s_waitcnt lgkmcnt(0)
	v_mfma_f32_16x16x32_bf16 v[66:69], v[118:121], v[194:197], v[66:69]
	v_mfma_f32_16x16x32_bf16 v[70:73], v[126:129], v[194:197], v[70:73]
	v_mfma_f32_16x16x32_bf16 v[74:77], v[118:121], v[202:205], v[74:77]
	v_mfma_f32_16x16x32_bf16 v[78:81], v[126:129], v[202:205], v[78:81]
	v_mfma_f32_16x16x32_bf16 v[82:85], v[118:121], v[222:225], v[82:85]
	v_mfma_f32_16x16x32_bf16 v[86:89], v[126:129], v[222:225], v[86:89]
	v_mfma_f32_16x16x32_bf16 v[90:93], v[118:121], v[238:241], v[90:93]
	v_mfma_f32_16x16x32_bf16 v[94:97], v[126:129], v[238:241], v[94:97]
	v_mfma_f32_16x16x32_bf16 v[66:69], v[122:125], v[198:201], v[66:69]
	v_mfma_f32_16x16x32_bf16 v[70:73], v[130:133], v[198:201], v[70:73]
	v_mfma_f32_16x16x32_bf16 v[74:77], v[122:125], v[218:221], v[74:77]
	v_mfma_f32_16x16x32_bf16 v[78:81], v[130:133], v[218:221], v[78:81]
	v_mfma_f32_16x16x32_bf16 v[82:85], v[122:125], v[226:229], v[82:85]
	v_mfma_f32_16x16x32_bf16 v[86:89], v[130:133], v[226:229], v[86:89]
	v_mfma_f32_16x16x32_bf16 v[90:93], v[122:125], v[242:245], v[90:93]
	v_mfma_f32_16x16x32_bf16 v[94:97], v[130:133], v[242:245], v[94:97]
	v_mfma_f32_16x16x32_bf16 v[98:101], v[134:137], v[194:197], v[98:101]
	v_mfma_f32_16x16x32_bf16 v[102:105], v[186:189], v[194:197], v[102:105]
	v_mfma_f32_16x16x32_bf16 v[106:109], v[134:137], v[202:205], v[106:109]
	v_mfma_f32_16x16x32_bf16 v[42:45], v[186:189], v[202:205], v[42:45]
	v_mfma_f32_16x16x32_bf16 v[46:49], v[134:137], v[222:225], v[46:49]
	v_mfma_f32_16x16x32_bf16 v[50:53], v[186:189], v[222:225], v[50:53]
	v_mfma_f32_16x16x32_bf16 v[54:57], v[134:137], v[238:241], v[54:57]
	v_mfma_f32_16x16x32_bf16 v[58:61], v[186:189], v[238:241], v[58:61]
	v_mfma_f32_16x16x32_bf16 v[98:101], v[182:185], v[198:201], v[98:101]
	v_mfma_f32_16x16x32_bf16 v[102:105], v[190:193], v[198:201], v[102:105]
	v_mfma_f32_16x16x32_bf16 v[106:109], v[182:185], v[218:221], v[106:109]
	v_mfma_f32_16x16x32_bf16 v[42:45], v[190:193], v[218:221], v[42:45]
	v_mfma_f32_16x16x32_bf16 v[46:49], v[182:185], v[226:229], v[46:49]
	v_mfma_f32_16x16x32_bf16 v[50:53], v[190:193], v[226:229], v[50:53]
	v_mfma_f32_16x16x32_bf16 v[54:57], v[182:185], v[242:245], v[54:57]
	v_mfma_f32_16x16x32_bf16 v[58:61], v[190:193], v[242:245], v[58:61]
	s_setprio 0
	s_barrier
	s_mov_b64 s[80:81], 0x280
	s_mov_b32 m0, s79
	v_lshl_add_u64 v[2:3], v[2:3], 0, s[80:81]
	s_add_u32 s54, s54, 0x18280
	ds_read_b128 v[194:197], v181 offset:49152
	ds_read_b128 v[198:201], v181 offset:50176
	ds_read_b128 v[202:205], v181 offset:51200
	ds_read_b128 v[218:221], v181 offset:52224
	ds_read_b128 v[222:225], v181 offset:53248
	ds_read_b128 v[226:229], v181 offset:54272
	ds_read_b128 v[238:241], v181 offset:55296
	ds_read_b128 v[242:245], v181 offset:56320
	global_load_lds_dwordx4 v[2:3], off
	v_lshl_add_u64 v[2:3], v[4:5], 0, s[80:81]
	s_mov_b32 m0, s75
	s_addc_u32 s55, s55, 0
	global_load_lds_dwordx4 v[2:3], off
	v_lshl_add_u64 v[2:3], s[54:55], 0, v[166:167]
	s_mov_b32 m0, s76
	s_nop 0
	global_load_lds_dwordx4 v[2:3], off
	v_lshl_add_u64 v[2:3], s[54:55], 0, v[162:163]
	s_mov_b32 m0, s78
	s_nop 0
	global_load_lds_dwordx4 v[2:3], off
	v_lshl_add_u64 v[2:3], v[6:7], 0, s[80:81]
	s_mov_b32 m0, s66
	s_nop 0
	global_load_lds_dwordx4 v[2:3], off
	v_lshl_add_u64 v[2:3], v[8:9], 0, s[80:81]
	s_mov_b32 m0, s67
	s_nop 0
	global_load_lds_dwordx4 v[2:3], off
	s_waitcnt vmcnt(8)
	s_waitcnt lgkmcnt(0)
	s_barrier
	s_setprio 1
	s_waitcnt lgkmcnt(0)
	v_mfma_f32_16x16x32_bf16 v[2:5], v[118:121], v[194:197], v[140:143]
	v_mfma_f32_16x16x32_bf16 v[6:9], v[126:129], v[194:197], v[144:147]
	v_mfma_f32_16x16x32_bf16 v[14:17], v[118:121], v[238:241], v[14:17]
	v_mfma_f32_16x16x32_bf16 v[18:21], v[126:129], v[238:241], v[18:21]
	v_mfma_f32_16x16x32_bf16 v[2:5], v[122:125], v[198:201], v[2:5]
	v_mfma_f32_16x16x32_bf16 v[6:9], v[130:133], v[198:201], v[6:9]
	v_mfma_f32_16x16x32_bf16 v[138:141], v[118:121], v[202:205], v[148:151]
	v_mfma_f32_16x16x32_bf16 v[142:145], v[126:129], v[202:205], v[152:155]
	v_mfma_f32_16x16x32_bf16 v[146:149], v[118:121], v[222:225], v[156:159]
	v_mfma_f32_16x16x32_bf16 v[150:153], v[126:129], v[222:225], v[174:177]
	v_mfma_f32_16x16x32_bf16 v[14:17], v[122:125], v[242:245], v[14:17]
	v_mfma_f32_16x16x32_bf16 v[18:21], v[130:133], v[242:245], v[18:21]
	v_mfma_f32_16x16x32_bf16 v[138:141], v[122:125], v[218:221], v[138:141]
	v_mfma_f32_16x16x32_bf16 v[142:145], v[130:133], v[218:221], v[142:145]
	v_mfma_f32_16x16x32_bf16 v[146:149], v[122:125], v[226:229], v[146:149]
	v_mfma_f32_16x16x32_bf16 v[150:153], v[130:133], v[226:229], v[150:153]
	v_mfma_f32_16x16x32_bf16 v[22:25], v[134:137], v[194:197], v[22:25]
	v_mfma_f32_16x16x32_bf16 v[34:37], v[186:189], v[194:197], v[34:37]
	v_mfma_f32_16x16x32_bf16 v[38:41], v[134:137], v[202:205], v[38:41]
	v_mfma_f32_16x16x32_bf16 v[62:65], v[186:189], v[202:205], v[62:65]
	v_mfma_f32_16x16x32_bf16 v[110:113], v[134:137], v[222:225], v[110:113]
	v_mfma_f32_16x16x32_bf16 v[114:117], v[186:189], v[222:225], v[114:117]
	v_mfma_f32_16x16x32_bf16 v[26:29], v[134:137], v[238:241], v[26:29]
	v_mfma_f32_16x16x32_bf16 v[30:33], v[186:189], v[238:241], v[30:33]
	v_mfma_f32_16x16x32_bf16 v[22:25], v[182:185], v[198:201], v[22:25]
	v_mfma_f32_16x16x32_bf16 v[34:37], v[190:193], v[198:201], v[34:37]
	v_mfma_f32_16x16x32_bf16 v[38:41], v[182:185], v[218:221], v[38:41]
	v_mfma_f32_16x16x32_bf16 v[62:65], v[190:193], v[218:221], v[62:65]
	v_mfma_f32_16x16x32_bf16 v[110:113], v[182:185], v[226:229], v[110:113]
	v_mfma_f32_16x16x32_bf16 v[114:117], v[190:193], v[226:229], v[114:117]
	v_mfma_f32_16x16x32_bf16 v[26:29], v[182:185], v[242:245], v[26:29]
	v_mfma_f32_16x16x32_bf16 v[30:33], v[190:193], v[242:245], v[30:33]
	s_setprio 0
	s_barrier
; #define PG8_STAGE(bufoff, gbase, voff) do { _Pragma("unroll") for (int _i = 0; _i < 2; ++_i) \
;         __builtin_amdgcn_global_load_lds((const unsigned*)((const char*)(gbase) + (voff)[_i]), (PG8_LAS unsigned*)(lds + (bufoff) + ldsw + _i * 8192), 16, 0, 0); } while (0)
; #define PG8_LDA(dst, b, h) do { _Pragma("unroll") for (int m = 0; m < 4; ++m) _Pragma("unroll") for (int k = 0; k < 2; ++k) dst[m][k] = *(const PG8_LAS bf16x8*)(lds + PG8_SA(b, h) + aoff + m * 2048 + k * 1024); } while (0)
; #define PG8_LDB(dst, b, h) do { _Pragma("unroll") for (int n = 0; n < 2; ++n) _Pragma("unroll") for (int k = 0; k < 2; ++k) dst[n][k] = *(const PG8_LAS bf16x8*)(lds + PG8_SB(b, h) + boff + n * 2048 + k * 1024); } while (0)
; #define PG8_MMA(ai, bj, At, Bt) do { __builtin_amdgcn_s_setprio(1); _Pragma("unroll") for (int m = 0; m < 4; ++m) _Pragma("unroll") for (int n = 0; n < 2; ++n) _Pragma("unroll") for (int k = 0; k < 2; ++k) \
;         acc[ai][bj][m][n] = __builtin_amdgcn_mfma_f32_16x16x32_bf16(Bt[n][k], At[m][k], acc[ai][bj][m][n], 0, 0, 0); __builtin_amdgcn_s_setprio(0); } while (0)
; #define PG8_WAIT_V(n) asm volatile("s_waitcnt vmcnt(" #n ")" ::: "memory")
; #define PG8_WAIT_L(n) asm volatile("s_waitcnt lgkmcnt(" #n ")" ::: "memory")
; #define PG8_BAR __builtin_amdgcn_s_barrier()
; #define PG8_SCHED __builtin_amdgcn_sched_barrier(0)
; template <class Epi, class Sched, bool ALIGN_EPI = false, bool SP2 = false>
; __device__ __forceinline__ void gemm_phase(PG8_LAS unsigned char* lds, const Gemm g, const Sched& S, const Epi& E, int wave0) {
;     ...
;             const char* a2 = last ? nA : cA + (size_t)(t + 2) * kstep; const char* b2 = last ? nB : cB + (size_t)(t + 2) * kstep;
;             const char* a3 = a2 + kstep; const char* b3 = b2 + kstep;
;             if constexpr (SP2) {
;             PG8_LDB(B0, 0, 0); PG8_LDB(B1, 0, 1); PG8_SCHED; PG8_LDA(At, 0, 0); PG8_STAGE(PG8_SA(1, 1), a1 + hstep, voffA);
;             PG8_WAIT_V(8); PG8_WAIT_L(0); PG8_BAR; PG8_MMA(0, 0, At, B0); PG8_MMA(0, 1, At, B1); PG8_BAR; PG8_SCHED;
;             PG8_LDA(At, 0, 1); PG8_STAGE(PG8_SB(0, 0), b2, voffB); PG8_STAGE(PG8_SB(0, 1), b2 + hstep, voffB); PG8_STAGE(PG8_SA(0, 0), a2, voffA);
;             PG8_WAIT_V(8); PG8_WAIT_L(0); PG8_BAR; PG8_MMA(1, 0, At, B0); PG8_MMA(1, 1, At, B1); PG8_BAR; PG8_SCHED;
	ds_read_b128 v[118:121], v0
	ds_read_b128 v[122:125], v0 offset:1024
	ds_read_b128 v[126:129], v0 offset:2048
	ds_read_b128 v[130:133], v0 offset:3072
	ds_read_b128 v[134:137], v10
	ds_read_b128 v[154:157], v10 offset:1024
	ds_read_b128 v[158:161], v10 offset:2048
	ds_read_b128 v[174:177], v10 offset:3072
	s_add_u32 s52, s52, 0x18280
	s_addc_u32 s53, s53, 0
	s_mov_b32 m0, s77
	v_lshl_add_u64 v[170:171], s[52:53], 0, v[168:169]
	ds_read_b128 v[182:185], v181
	ds_read_b128 v[186:189], v181 offset:1024
	ds_read_b128 v[190:193], v181 offset:2048
	ds_read_b128 v[194:197], v181 offset:3072
	ds_read_b128 v[198:201], v181 offset:4096
	ds_read_b128 v[202:205], v181 offset:5120
	ds_read_b128 v[218:221], v181 offset:6144
	ds_read_b128 v[222:225], v181 offset:7168
	global_load_lds_dwordx4 v[170:171], off
	v_lshl_add_u64 v[170:171], s[52:53], 0, v[164:165]
	s_mov_b32 m0, s0
	s_nop 0
	global_load_lds_dwordx4 v[170:171], off
	s_waitcnt vmcnt(8)
	s_waitcnt lgkmcnt(0)
	s_barrier
	s_setprio 1
	s_waitcnt lgkmcnt(0)
	v_mfma_f32_16x16x32_bf16 v[66:69], v[118:121], v[182:185], v[66:69]
	v_mfma_f32_16x16x32_bf16 v[70:73], v[126:129], v[182:185], v[70:73]
	v_mfma_f32_16x16x32_bf16 v[74:77], v[118:121], v[190:193], v[74:77]
	v_mfma_f32_16x16x32_bf16 v[78:81], v[126:129], v[190:193], v[78:81]
	v_mfma_f32_16x16x32_bf16 v[82:85], v[118:121], v[198:201], v[82:85]
	v_mfma_f32_16x16x32_bf16 v[86:89], v[126:129], v[198:201], v[86:89]
	v_mfma_f32_16x16x32_bf16 v[90:93], v[118:121], v[218:221], v[90:93]
	v_mfma_f32_16x16x32_bf16 v[66:69], v[122:125], v[186:189], v[66:69]
	v_mfma_f32_16x16x32_bf16 v[70:73], v[130:133], v[186:189], v[70:73]
	v_mfma_f32_16x16x32_bf16 v[74:77], v[122:125], v[194:197], v[74:77]
	v_mfma_f32_16x16x32_bf16 v[78:81], v[130:133], v[194:197], v[78:81]
	v_mfma_f32_16x16x32_bf16 v[82:85], v[122:125], v[202:205], v[82:85]
	v_mfma_f32_16x16x32_bf16 v[86:89], v[130:133], v[202:205], v[86:89]
	v_mfma_f32_16x16x32_bf16 v[90:93], v[122:125], v[222:225], v[90:93]
	v_mfma_f32_16x16x32_bf16 v[94:97], v[126:129], v[218:221], v[94:97]
	v_mfma_f32_16x16x32_bf16 v[226:229], v[130:133], v[222:225], v[94:97]
	v_mfma_f32_16x16x32_bf16 v[94:97], v[134:137], v[182:185], v[98:101]
	v_mfma_f32_16x16x32_bf16 v[98:101], v[154:157], v[186:189], v[94:97]
	v_mfma_f32_16x16x32_bf16 v[94:97], v[158:161], v[182:185], v[102:105]
	v_mfma_f32_16x16x32_bf16 v[182:185], v[174:177], v[186:189], v[94:97]
	v_mfma_f32_16x16x32_bf16 v[94:97], v[134:137], v[190:193], v[106:109]
	v_mfma_f32_16x16x32_bf16 v[42:45], v[158:161], v[190:193], v[42:45]
	v_mfma_f32_16x16x32_bf16 v[46:49], v[134:137], v[198:201], v[46:49]
	v_mfma_f32_16x16x32_bf16 v[50:53], v[158:161], v[198:201], v[50:53]
	v_mfma_f32_16x16x32_bf16 v[54:57], v[134:137], v[218:221], v[54:57]
	v_mfma_f32_16x16x32_bf16 v[58:61], v[158:161], v[218:221], v[58:61]
	v_mfma_f32_16x16x32_bf16 v[106:109], v[154:157], v[194:197], v[94:97]
	v_mfma_f32_16x16x32_bf16 v[42:45], v[174:177], v[194:197], v[42:45]
	v_mfma_f32_16x16x32_bf16 v[46:49], v[154:157], v[202:205], v[46:49]
	v_mfma_f32_16x16x32_bf16 v[50:53], v[174:177], v[202:205], v[50:53]
	v_mfma_f32_16x16x32_bf16 v[54:57], v[154:157], v[222:225], v[54:57]
	v_mfma_f32_16x16x32_bf16 v[58:61], v[174:177], v[222:225], v[58:61]
	s_setprio 0
	s_barrier
	s_mov_b32 m0, s74
	v_lshl_add_u64 v[170:171], s[50:51], 0, v[166:167]
	s_add_u32 s0, s50, 0x18000
	ds_read_b128 v[94:97], v181 offset:16384
	ds_read_b128 v[102:105], v181 offset:17408
	ds_read_b128 v[186:189], v181 offset:18432
	ds_read_b128 v[190:193], v181 offset:19456
	ds_read_b128 v[194:197], v181 offset:20480
	ds_read_b128 v[198:201], v181 offset:21504
	ds_read_b128 v[202:205], v181 offset:22528
	ds_read_b128 v[218:221], v181 offset:23552
	global_load_lds_dwordx4 v[170:171], off
	v_lshl_add_u64 v[230:231], s[50:51], 0, v[162:163]
	s_mov_b32 m0, s1
	s_addc_u32 s1, s51, 0
	global_load_lds_dwordx4 v[230:231], off
	v_lshl_add_u64 v[206:207], s[0:1], 0, v[166:167]
	s_mov_b32 m0, s72
	v_lshl_add_u64 v[232:233], s[48:49], 0, v[168:169]
	global_load_lds_dwordx4 v[206:207], off
	v_lshl_add_u64 v[206:207], s[0:1], 0, v[162:163]
	s_mov_b32 m0, s73
	v_lshl_add_u64 v[234:235], s[48:49], 0, v[164:165]
	global_load_lds_dwordx4 v[206:207], off
	s_mov_b32 m0, s60
	s_nop 0
	global_load_lds_dwordx4 v[232:233], off
	s_mov_b32 m0, s61
	s_nop 0
	global_load_lds_dwordx4 v[234:235], off
	s_waitcnt vmcnt(8)
	s_waitcnt lgkmcnt(0)
	s_barrier
	s_setprio 1
	s_waitcnt lgkmcnt(0)
	v_mfma_f32_16x16x32_bf16 v[2:5], v[118:121], v[94:97], v[2:5]
	v_mfma_f32_16x16x32_bf16 v[6:9], v[126:129], v[94:97], v[6:9]
	v_mfma_f32_16x16x32_bf16 v[14:17], v[118:121], v[202:205], v[14:17]
	v_mfma_f32_16x16x32_bf16 v[18:21], v[126:129], v[202:205], v[18:21]
	v_mfma_f32_16x16x32_bf16 v[2:5], v[122:125], v[102:105], v[2:5]
	v_mfma_f32_16x16x32_bf16 v[6:9], v[130:133], v[102:105], v[6:9]
	v_mfma_f32_16x16x32_bf16 v[138:141], v[118:121], v[186:189], v[138:141]
	v_mfma_f32_16x16x32_bf16 v[142:145], v[126:129], v[186:189], v[142:145]
	v_mfma_f32_16x16x32_bf16 v[146:149], v[118:121], v[194:197], v[146:149]
	v_mfma_f32_16x16x32_bf16 v[150:153], v[126:129], v[194:197], v[150:153]
	v_mfma_f32_16x16x32_bf16 v[14:17], v[122:125], v[218:221], v[14:17]
	v_mfma_f32_16x16x32_bf16 v[18:21], v[130:133], v[218:221], v[18:21]
	v_mfma_f32_16x16x32_bf16 v[138:141], v[122:125], v[190:193], v[138:141]
	v_mfma_f32_16x16x32_bf16 v[142:145], v[130:133], v[190:193], v[142:145]
	v_mfma_f32_16x16x32_bf16 v[146:149], v[122:125], v[198:201], v[146:149]
	v_mfma_f32_16x16x32_bf16 v[150:153], v[130:133], v[198:201], v[150:153]
	v_mfma_f32_16x16x32_bf16 v[22:25], v[134:137], v[94:97], v[22:25]
	v_mfma_f32_16x16x32_bf16 v[130:133], v[154:157], v[102:105], v[22:25]
	v_mfma_f32_16x16x32_bf16 v[22:25], v[158:161], v[94:97], v[34:37]
	v_mfma_f32_16x16x32_bf16 v[34:37], v[174:177], v[102:105], v[22:25]
	v_mfma_f32_16x16x32_bf16 v[22:25], v[134:137], v[186:189], v[38:41]
	v_mfma_f32_16x16x32_bf16 v[222:225], v[154:157], v[190:193], v[22:25]
	v_mfma_f32_16x16x32_bf16 v[22:25], v[158:161], v[186:189], v[62:65]
	v_mfma_f32_16x16x32_bf16 v[186:189], v[174:177], v[190:193], v[22:25]
	v_mfma_f32_16x16x32_bf16 v[22:25], v[134:137], v[194:197], v[110:113]
	v_mfma_f32_16x16x32_bf16 v[190:193], v[154:157], v[198:201], v[22:25]
	v_mfma_f32_16x16x32_bf16 v[22:25], v[158:161], v[194:197], v[114:117]
	v_mfma_f32_16x16x32_bf16 v[194:197], v[174:177], v[198:201], v[22:25]
	v_mfma_f32_16x16x32_bf16 v[22:25], v[134:137], v[202:205], v[26:29]
	v_mfma_f32_16x16x32_bf16 v[134:137], v[154:157], v[218:221], v[22:25]
	v_mfma_f32_16x16x32_bf16 v[22:25], v[158:161], v[202:205], v[30:33]
	v_mfma_f32_16x16x32_bf16 v[154:157], v[174:177], v[218:221], v[22:25]
	s_setprio 0
	s_barrier
; #define PG8_STAGE(bufoff, gbase, voff) do { _Pragma("unroll") for (int _i = 0; _i < 2; ++_i) \
;         __builtin_amdgcn_global_load_lds((const unsigned*)((const char*)(gbase) + (voff)[_i]), (PG8_LAS unsigned*)(lds + (bufoff) + ldsw + _i * 8192), 16, 0, 0); } while (0)
; #define PG8_LDA(dst, b, h) do { _Pragma("unroll") for (int m = 0; m < 4; ++m) _Pragma("unroll") for (int k = 0; k < 2; ++k) dst[m][k] = *(const PG8_LAS bf16x8*)(lds + PG8_SA(b, h) + aoff + m * 2048 + k * 1024); } while (0)
; #define PG8_LDB(dst, b, h) do { _Pragma("unroll") for (int n = 0; n < 2; ++n) _Pragma("unroll") for (int k = 0; k < 2; ++k) dst[n][k] = *(const PG8_LAS bf16x8*)(lds + PG8_SB(b, h) + boff + n * 2048 + k * 1024); } while (0)
; #define PG8_MMA(ai, bj, At, Bt) do { __builtin_amdgcn_s_setprio(1); _Pragma("unroll") for (int m = 0; m < 4; ++m) _Pragma("unroll") for (int n = 0; n < 2; ++n) _Pragma("unroll") for (int k = 0; k < 2; ++k) \
;         acc[ai][bj][m][n] = __builtin_amdgcn_mfma_f32_16x16x32_bf16(Bt[n][k], At[m][k], acc[ai][bj][m][n], 0, 0, 0); __builtin_amdgcn_s_setprio(0); } while (0)
; #define PG8_WAIT_V(n) asm volatile("s_waitcnt vmcnt(" #n ")" ::: "memory")
; #define PG8_WAIT_L(n) asm volatile("s_waitcnt lgkmcnt(" #n ")" ::: "memory")
; #define PG8_BAR __builtin_amdgcn_s_barrier()
; #define PG8_SCHED __builtin_amdgcn_sched_barrier(0)
; template <class Epi, class Sched, bool ALIGN_EPI = false, bool SP2 = false>
; __device__ __forceinline__ void gemm_phase(PG8_LAS unsigned char* lds, const Gemm g, const Sched& S, const Epi& E, int wave0) {
;     ...
;             PG8_LDB(B0, 1, 0); PG8_LDB(B1, 1, 1); PG8_SCHED; PG8_LDA(At, 1, 0); PG8_STAGE(PG8_SA(0, 1), a2 + hstep, voffA);
;             PG8_WAIT_V(8); PG8_WAIT_L(0); PG8_BAR; PG8_MMA(0, 0, At, B0); PG8_MMA(0, 1, At, B1); PG8_BAR; PG8_SCHED;
;             PG8_LDA(At, 1, 1); PG8_STAGE(PG8_SB(1, 0), b3, voffB); PG8_STAGE(PG8_SB(1, 1), b3 + hstep, voffB); PG8_STAGE(PG8_SA(1, 0), a3, voffA);
;             PG8_WAIT_V(8); PG8_WAIT_L(0); PG8_BAR; PG8_MMA(1, 0, At, B0); PG8_MMA(1, 1, At, B1); PG8_BAR; PG8_SCHED;
;     ...
;         if constexpr (ALIGN_EPI) { if (wr == 0) PG8_BAR; }
	ds_read_b128 v[26:29], v11
	ds_read_b128 v[158:161], v11 offset:1024
	ds_read_b128 v[174:177], v11 offset:2048
	ds_read_b128 v[198:201], v11 offset:3072
	ds_read_b128 v[202:205], v12
	ds_read_b128 v[218:221], v12 offset:1024
	ds_read_b128 v[238:241], v12 offset:2048
	ds_read_b128 v[242:245], v12 offset:3072
	s_add_u32 s0, s48, 0x18000
	s_addc_u32 s1, s49, 0
	s_mov_b32 m0, s62
	v_lshl_add_u64 v[94:95], s[0:1], 0, v[168:169]
	ds_read_b128 v[10:13], v181 offset:32768
	ds_read_b128 v[22:25], v181 offset:33792
	ds_read_b128 v[30:33], v181 offset:34816
	ds_read_b128 v[38:41], v181 offset:35840
	ds_read_b128 v[62:65], v181 offset:36864
	ds_read_b128 v[246:249], v181 offset:37888
	ds_read_b128 v[206:209], v181 offset:38912
	ds_read_b128 v[214:217], v181 offset:39936
	global_load_lds_dwordx4 v[94:95], off
	v_lshl_add_u64 v[94:95], s[0:1], 0, v[164:165]
	s_mov_b32 m0, s63
	s_nop 0
	global_load_lds_dwordx4 v[94:95], off
	s_waitcnt vmcnt(8)
	s_waitcnt lgkmcnt(0)
	s_barrier
	s_setprio 1
	s_waitcnt lgkmcnt(0)
	v_mfma_f32_16x16x32_bf16 v[66:69], v[26:29], v[10:13], v[66:69]
	v_mfma_f32_16x16x32_bf16 v[126:129], v[158:161], v[22:25], v[66:69]
	v_mfma_f32_16x16x32_bf16 v[66:69], v[174:177], v[10:13], v[70:73]
	v_mfma_f32_16x16x32_bf16 v[118:121], v[198:201], v[22:25], v[66:69]
	v_mfma_f32_16x16x32_bf16 v[66:69], v[26:29], v[30:33], v[74:77]
	v_mfma_f32_16x16x32_bf16 v[110:113], v[158:161], v[38:41], v[66:69]
	v_mfma_f32_16x16x32_bf16 v[66:69], v[174:177], v[30:33], v[78:81]
	v_mfma_f32_16x16x32_bf16 v[102:105], v[198:201], v[38:41], v[66:69]
	v_mfma_f32_16x16x32_bf16 v[66:69], v[26:29], v[62:65], v[82:85]
	v_mfma_f32_16x16x32_bf16 v[94:97], v[158:161], v[246:249], v[66:69]
	v_mfma_f32_16x16x32_bf16 v[66:69], v[174:177], v[62:65], v[86:89]
	v_mfma_f32_16x16x32_bf16 v[86:89], v[198:201], v[246:249], v[66:69]
	v_mfma_f32_16x16x32_bf16 v[66:69], v[26:29], v[206:209], v[90:93]
	v_mfma_f32_16x16x32_bf16 v[78:81], v[158:161], v[214:217], v[66:69]
	v_mfma_f32_16x16x32_bf16 v[66:69], v[174:177], v[206:209], v[226:229]
	v_mfma_f32_16x16x32_bf16 v[70:73], v[198:201], v[214:217], v[66:69]
	v_mfma_f32_16x16x32_bf16 v[66:69], v[202:205], v[10:13], v[98:101]
	v_mfma_f32_16x16x32_bf16 v[10:13], v[238:241], v[10:13], v[182:185]
	v_mfma_f32_16x16x32_bf16 v[114:117], v[242:245], v[22:25], v[10:13]
	v_mfma_f32_16x16x32_bf16 v[10:13], v[202:205], v[30:33], v[106:109]
	v_mfma_f32_16x16x32_bf16 v[106:109], v[218:221], v[38:41], v[10:13]
	v_mfma_f32_16x16x32_bf16 v[10:13], v[238:241], v[30:33], v[42:45]
	v_mfma_f32_16x16x32_bf16 v[98:101], v[242:245], v[38:41], v[10:13]
	v_mfma_f32_16x16x32_bf16 v[10:13], v[202:205], v[62:65], v[46:49]
	v_mfma_f32_16x16x32_bf16 v[90:93], v[218:221], v[246:249], v[10:13]
	v_mfma_f32_16x16x32_bf16 v[10:13], v[238:241], v[62:65], v[50:53]
	v_mfma_f32_16x16x32_bf16 v[82:85], v[242:245], v[246:249], v[10:13]
	v_mfma_f32_16x16x32_bf16 v[10:13], v[202:205], v[206:209], v[54:57]
	v_mfma_f32_16x16x32_bf16 v[74:77], v[218:221], v[214:217], v[10:13]
	v_mfma_f32_16x16x32_bf16 v[10:13], v[238:241], v[206:209], v[58:61]
	v_mfma_f32_16x16x32_bf16 v[122:125], v[218:221], v[22:25], v[66:69]
	v_mfma_f32_16x16x32_bf16 v[66:69], v[242:245], v[214:217], v[10:13]
	s_setprio 0
	s_barrier
	s_mov_b32 m0, s79
	v_lshl_add_u64 v[22:23], v[170:171], 0, s[34:35]
	s_add_u32 s0, s50, 0x18080
	s_nop 0
	ds_read_b128 v[10:13], v181 offset:49152
	ds_read_b128 v[42:45], v181 offset:50176
	ds_read_b128 v[182:185], v181 offset:51200
	ds_read_b128 v[206:209], v181 offset:52224
	ds_read_b128 v[214:217], v181 offset:53248
	ds_read_b128 v[226:229], v181 offset:54272
	ds_read_b128 v[246:249], v181 offset:55296
	ds_read_b128 v[210:213], v181 offset:56320
	global_load_lds_dwordx4 v[22:23], off
	v_lshl_add_u64 v[22:23], v[230:231], 0, s[34:35]
	s_mov_b32 m0, s75
	s_addc_u32 s1, s51, 0
	global_load_lds_dwordx4 v[22:23], off
	v_lshl_add_u64 v[22:23], s[0:1], 0, v[166:167]
	s_mov_b32 m0, s76
	s_nop 0
	global_load_lds_dwordx4 v[22:23], off
	v_lshl_add_u64 v[22:23], s[0:1], 0, v[162:163]
	s_mov_b32 m0, s78
	s_nop 0
	global_load_lds_dwordx4 v[22:23], off
	v_lshl_add_u64 v[22:23], v[232:233], 0, s[34:35]
	s_mov_b32 m0, s66
	s_nop 0
	global_load_lds_dwordx4 v[22:23], off
	v_lshl_add_u64 v[22:23], v[234:235], 0, s[34:35]
	s_mov_b32 m0, s67
	s_nop 0
	global_load_lds_dwordx4 v[22:23], off
	s_waitcnt vmcnt(8)
	s_waitcnt lgkmcnt(0)
	s_barrier
	s_setprio 1
	s_waitcnt lgkmcnt(0)
	v_mfma_f32_16x16x32_bf16 v[2:5], v[26:29], v[10:13], v[2:5]
	v_mfma_f32_16x16x32_bf16 v[62:65], v[158:161], v[42:45], v[2:5]
	v_mfma_f32_16x16x32_bf16 v[2:5], v[174:177], v[10:13], v[6:9]
	v_mfma_f32_16x16x32_bf16 v[54:57], v[198:201], v[42:45], v[2:5]
	v_mfma_f32_16x16x32_bf16 v[2:5], v[26:29], v[182:185], v[138:141]
	v_mfma_f32_16x16x32_bf16 v[46:49], v[158:161], v[206:209], v[2:5]
	v_mfma_f32_16x16x32_bf16 v[2:5], v[174:177], v[182:185], v[142:145]
	v_mfma_f32_16x16x32_bf16 v[38:41], v[198:201], v[206:209], v[2:5]
	v_mfma_f32_16x16x32_bf16 v[2:5], v[26:29], v[214:217], v[146:149]
	v_mfma_f32_16x16x32_bf16 v[30:33], v[158:161], v[226:229], v[2:5]
	v_mfma_f32_16x16x32_bf16 v[2:5], v[174:177], v[214:217], v[150:153]
	v_mfma_f32_16x16x32_bf16 v[22:25], v[198:201], v[226:229], v[2:5]
	v_mfma_f32_16x16x32_bf16 v[2:5], v[26:29], v[246:249], v[14:17]
	v_mfma_f32_16x16x32_bf16 v[14:17], v[158:161], v[210:213], v[2:5]
	v_mfma_f32_16x16x32_bf16 v[2:5], v[174:177], v[246:249], v[18:21]
	v_mfma_f32_16x16x32_bf16 v[6:9], v[198:201], v[210:213], v[2:5]
	v_mfma_f32_16x16x32_bf16 v[2:5], v[202:205], v[10:13], v[130:133]
	v_mfma_f32_16x16x32_bf16 v[58:61], v[218:221], v[42:45], v[2:5]
	v_mfma_f32_16x16x32_bf16 v[2:5], v[238:241], v[10:13], v[34:37]
	v_mfma_f32_16x16x32_bf16 v[50:53], v[242:245], v[42:45], v[2:5]
	v_mfma_f32_16x16x32_bf16 v[2:5], v[202:205], v[182:185], v[222:225]
	v_mfma_f32_16x16x32_bf16 v[42:45], v[218:221], v[206:209], v[2:5]
	v_mfma_f32_16x16x32_bf16 v[2:5], v[238:241], v[182:185], v[186:189]
	v_mfma_f32_16x16x32_bf16 v[34:37], v[242:245], v[206:209], v[2:5]
	v_mfma_f32_16x16x32_bf16 v[2:5], v[202:205], v[214:217], v[190:193]
	v_mfma_f32_16x16x32_bf16 v[26:29], v[218:221], v[226:229], v[2:5]
	v_mfma_f32_16x16x32_bf16 v[2:5], v[238:241], v[214:217], v[194:197]
	v_mfma_f32_16x16x32_bf16 v[18:21], v[242:245], v[226:229], v[2:5]
	v_mfma_f32_16x16x32_bf16 v[2:5], v[202:205], v[246:249], v[134:137]
	v_mfma_f32_16x16x32_bf16 v[10:13], v[218:221], v[210:213], v[2:5]
	v_mfma_f32_16x16x32_bf16 v[2:5], v[238:241], v[246:249], v[154:157]
	v_mfma_f32_16x16x32_bf16 v[2:5], v[242:245], v[210:213], v[2:5]
	s_setprio 0
	s_barrier
	s_andn2_b64 vcc, exec, s[42:43]
	s_cbranch_vccnz .LBB0_376
	s_barrier

; #define PG8_STAGE(bufoff, gbase, voff) do { _Pragma("unroll") for (int _i = 0; _i < 2; ++_i) \
;         __builtin_amdgcn_global_load_lds((const unsigned*)((const char*)(gbase) + (voff)[_i]), (PG8_LAS unsigned*)(lds + (bufoff) + ldsw + _i * 8192), 16, 0, 0); } while (0)
; #define PG8_LDA(dst, b, h) do { _Pragma("unroll") for (int m = 0; m < 4; ++m) _Pragma("unroll") for (int k = 0; k < 2; ++k) dst[m][k] = *(const PG8_LAS bf16x8*)(lds + PG8_SA(b, h) + aoff + m * 2048 + k * 1024); } while (0)
; #define PG8_LDB(dst, b, h) do { _Pragma("unroll") for (int n = 0; n < 2; ++n) _Pragma("unroll") for (int k = 0; k < 2; ++k) dst[n][k] = *(const PG8_LAS bf16x8*)(lds + PG8_SB(b, h) + boff + n * 2048 + k * 1024); } while (0)
; #define PG8_MMA(ai, bj, At, Bt) do { __builtin_amdgcn_s_setprio(1); _Pragma("unroll") for (int m = 0; m < 4; ++m) _Pragma("unroll") for (int n = 0; n < 2; ++n) _Pragma("unroll") for (int k = 0; k < 2; ++k) \
;         acc[ai][bj][m][n] = __builtin_amdgcn_mfma_f32_16x16x32_bf16(Bt[n][k], At[m][k], acc[ai][bj][m][n], 0, 0, 0); __builtin_amdgcn_s_setprio(0); } while (0)
; #define PG8_BAR __builtin_amdgcn_s_barrier()
; template <class Epi, class Sched, bool ALIGN_EPI = false, bool SP2 = false>
; __device__ __forceinline__ void gemm_phase(PG8_LAS unsigned char* lds, const Gemm g, const Sched& S, const Epi& E, int wave0) {
;     ...
;         const bool has_next = S.next(ui + 1, nxt);
;         const char* nA = has_next ? gA + (size_t)nxt.pm * tstep + (size_t)nxt.pz * g.azs : cA; const char* nB = has_next ? gB + (size_t)nxt.pn * tstep + (size_t)nxt.pz * g.bzs : cB;
;         for (int t = 0; t < nt; t += 2) {
;             const bool last = (t == nt - 2);
;             const char* a1 = cA + (size_t)(t + 1) * kstep;
;             const char* a2 = last ? nA : cA + (size_t)(t + 2) * kstep; const char* b2 = last ? nB : cB + (size_t)(t + 2) * kstep;
;             const char* a3 = a2 + kstep; const char* b3 = b2 + kstep;
;             if constexpr (SP2) {
;             PG8_LDB(B0, 0, 0); PG8_LDB(B1, 0, 1); PG8_SCHED; PG8_LDA(At, 0, 0); PG8_STAGE(PG8_SA(1, 1), a1 + hstep, voffA);
;             PG8_WAIT_V(8); PG8_WAIT_L(0); PG8_BAR; PG8_MMA(0, 0, At, B0); PG8_MMA(0, 1, At, B1); PG8_BAR; PG8_SCHED;
;             PG8_LDA(At, 0, 1); PG8_STAGE(PG8_SB(0, 0), b2, voffB); PG8_STAGE(PG8_SB(0, 1), b2 + hstep, voffB); PG8_STAGE(PG8_SA(0, 0), a2, voffA);
.LBB0_412:
	s_ashr_i32 s47, s46, 31
	s_lshl_b64 s[48:49], s[46:47], 17
	s_add_u32 s48, s44, s48
	s_addc_u32 s49, s58, s49
	s_and_b64 s[50:51], s[0:1], exec
	s_cselect_b32 s57, s49, s5
	s_cselect_b32 s56, s48, s4
	s_ashr_i32 s29, s28, 31
	s_lshl_b64 s[50:51], s[28:29], 17
	s_add_u32 s50, s3, s50
	s_addc_u32 s51, s33, s51
	s_and_b64 s[54:55], s[0:1], exec
	s_cselect_b32 s55, s51, s53
	s_cselect_b32 s54, s50, s52
	s_add_i32 s47, 0, 0x10000
	s_add_i32 s71, 0, 0x14000
	v_add_u32_e32 v152, s47, v153
	v_add_u32_e32 v158, s71, v153
	ds_read_b128 v[2:5], v152
	ds_read_b128 v[6:9], v152 offset:1024
	ds_read_b128 v[10:13], v152 offset:2048
	ds_read_b128 v[14:17], v152 offset:3072
	ds_read_b128 v[18:21], v158
	ds_read_b128 v[22:25], v158 offset:1024
	ds_read_b128 v[26:29], v158 offset:2048
	ds_read_b128 v[30:33], v158 offset:3072
	s_add_u32 s72, s4, 0x10080
	s_addc_u32 s73, s5, 0
	s_add_i32 s75, s60, 0xc000
	v_lshl_add_u64 v[66:67], s[72:73], 0, v[150:151]
	s_mov_b32 m0, s75
	s_add_i32 s29, s60, 0xe000
	ds_read_b128 v[34:37], v159
	ds_read_b128 v[38:41], v159 offset:1024
	ds_read_b128 v[42:45], v159 offset:2048
	ds_read_b128 v[46:49], v159 offset:3072
	ds_read_b128 v[50:53], v159 offset:4096
	ds_read_b128 v[54:57], v159 offset:5120
	ds_read_b128 v[58:61], v159 offset:6144
	ds_read_b128 v[62:65], v159 offset:7168
	global_load_lds_dwordx4 v[66:67], off
	v_lshl_add_u64 v[66:67], s[72:73], 0, v[148:149]
	s_mov_b32 m0, s29
	s_nop 0
	global_load_lds_dwordx4 v[66:67], off
	s_waitcnt vmcnt(8)
	s_waitcnt lgkmcnt(0)
	s_barrier
	s_setprio 1
	s_waitcnt lgkmcnt(0)
	v_mfma_f32_16x16x32_bf16 v[66:69], v[2:5], v[34:37], 0
	v_mfma_f32_16x16x32_bf16 v[70:73], v[10:13], v[34:37], 0
	v_mfma_f32_16x16x32_bf16 v[74:77], v[2:5], v[42:45], 0
	v_mfma_f32_16x16x32_bf16 v[78:81], v[10:13], v[42:45], 0
	v_mfma_f32_16x16x32_bf16 v[82:85], v[2:5], v[50:53], 0
	v_mfma_f32_16x16x32_bf16 v[86:89], v[10:13], v[50:53], 0
	v_mfma_f32_16x16x32_bf16 v[90:93], v[2:5], v[58:61], 0
	v_mfma_f32_16x16x32_bf16 v[94:97], v[10:13], v[58:61], 0
	v_mfma_f32_16x16x32_bf16 v[66:69], v[6:9], v[38:41], v[66:69]
	v_mfma_f32_16x16x32_bf16 v[70:73], v[14:17], v[38:41], v[70:73]
	v_mfma_f32_16x16x32_bf16 v[74:77], v[6:9], v[46:49], v[74:77]
	v_mfma_f32_16x16x32_bf16 v[78:81], v[14:17], v[46:49], v[78:81]
	v_mfma_f32_16x16x32_bf16 v[82:85], v[6:9], v[54:57], v[82:85]
	v_mfma_f32_16x16x32_bf16 v[86:89], v[14:17], v[54:57], v[86:89]
	v_mfma_f32_16x16x32_bf16 v[90:93], v[6:9], v[62:65], v[90:93]
	v_mfma_f32_16x16x32_bf16 v[94:97], v[14:17], v[62:65], v[94:97]
	v_mfma_f32_16x16x32_bf16 v[98:101], v[18:21], v[34:37], 0
	v_mfma_f32_16x16x32_bf16 v[34:37], v[26:29], v[34:37], 0
	v_mfma_f32_16x16x32_bf16 v[98:101], v[22:25], v[38:41], v[98:101]
	v_mfma_f32_16x16x32_bf16 v[34:37], v[30:33], v[38:41], v[34:37]
	v_mfma_f32_16x16x32_bf16 v[38:41], v[18:21], v[42:45], 0
	v_mfma_f32_16x16x32_bf16 v[42:45], v[26:29], v[42:45], 0
	v_mfma_f32_16x16x32_bf16 v[38:41], v[22:25], v[46:49], v[38:41]
	v_mfma_f32_16x16x32_bf16 v[42:45], v[30:33], v[46:49], v[42:45]
	v_mfma_f32_16x16x32_bf16 v[46:49], v[18:21], v[50:53], 0
	v_mfma_f32_16x16x32_bf16 v[50:53], v[26:29], v[50:53], 0
	v_mfma_f32_16x16x32_bf16 v[46:49], v[22:25], v[54:57], v[46:49]
	v_mfma_f32_16x16x32_bf16 v[50:53], v[30:33], v[54:57], v[50:53]
	v_mfma_f32_16x16x32_bf16 v[54:57], v[18:21], v[58:61], 0
	v_mfma_f32_16x16x32_bf16 v[58:61], v[26:29], v[58:61], 0
	v_mfma_f32_16x16x32_bf16 v[54:57], v[22:25], v[62:65], v[54:57]
	v_mfma_f32_16x16x32_bf16 v[58:61], v[30:33], v[62:65], v[58:61]
	s_setprio 0
	s_barrier
	s_add_i32 s73, s47, s59
	v_lshl_add_u64 v[206:207], s[52:53], 0, v[0:1]
	s_mov_b64 s[78:79], 0x100
	s_add_i32 s47, s73, 0x2000
	v_lshl_add_u64 v[130:131], v[206:207], 0, s[78:79]
	s_mov_b32 m0, s73
	v_lshl_add_u64 v[208:209], s[52:53], 0, v[146:147]
	s_add_u32 s76, s52, 0x10100
	ds_read_b128 v[62:65], v159 offset:16384
	ds_read_b128 v[102:105], v159 offset:17408
	ds_read_b128 v[106:109], v159 offset:18432
	ds_read_b128 v[110:113], v159 offset:19456
	ds_read_b128 v[114:117], v159 offset:20480
	ds_read_b128 v[118:121], v159 offset:21504
	ds_read_b128 v[122:125], v159 offset:22528
	ds_read_b128 v[126:129], v159 offset:23552
	global_load_lds_dwordx4 v[130:131], off
	v_lshl_add_u64 v[130:131], v[208:209], 0, s[78:79]
	s_mov_b32 m0, s47
	s_addc_u32 s77, s53, 0
	s_add_i32 s71, s71, s59
	global_load_lds_dwordx4 v[130:131], off
	v_lshl_add_u64 v[130:131], s[76:77], 0, v[0:1]
	s_mov_b32 m0, s71
	s_add_i32 s72, s71, 0x2000
	global_load_lds_dwordx4 v[130:131], off
	v_lshl_add_u64 v[130:131], s[76:77], 0, v[146:147]
	s_mov_b32 m0, s72
	v_lshl_add_u64 v[210:211], s[4:5], 0, v[150:151]
	global_load_lds_dwordx4 v[130:131], off
	v_lshl_add_u64 v[130:131], v[210:211], 0, s[78:79]
	s_mov_b32 m0, s60
	v_lshl_add_u64 v[212:213], s[4:5], 0, v[148:149]
	global_load_lds_dwordx4 v[130:131], off
	v_lshl_add_u64 v[130:131], v[212:213], 0, s[78:79]
	s_mov_b32 m0, s61
	s_nop 0
	global_load_lds_dwordx4 v[130:131], off
	s_waitcnt vmcnt(8)
	s_waitcnt lgkmcnt(0)
	s_barrier
; #define PG8_STAGE(bufoff, gbase, voff) do { _Pragma("unroll") for (int _i = 0; _i < 2; ++_i) \
;         __builtin_amdgcn_global_load_lds((const unsigned*)((const char*)(gbase) + (voff)[_i]), (PG8_LAS unsigned*)(lds + (bufoff) + ldsw + _i * 8192), 16, 0, 0); } while (0)
; #define PG8_LDA(dst, b, h) do { _Pragma("unroll") for (int m = 0; m < 4; ++m) _Pragma("unroll") for (int k = 0; k < 2; ++k) dst[m][k] = *(const PG8_LAS bf16x8*)(lds + PG8_SA(b, h) + aoff + m * 2048 + k * 1024); } while (0)
; #define PG8_LDB(dst, b, h) do { _Pragma("unroll") for (int n = 0; n < 2; ++n) _Pragma("unroll") for (int k = 0; k < 2; ++k) dst[n][k] = *(const PG8_LAS bf16x8*)(lds + PG8_SB(b, h) + boff + n * 2048 + k * 1024); } while (0)
; #define PG8_MMA(ai, bj, At, Bt) do { __builtin_amdgcn_s_setprio(1); _Pragma("unroll") for (int m = 0; m < 4; ++m) _Pragma("unroll") for (int n = 0; n < 2; ++n) _Pragma("unroll") for (int k = 0; k < 2; ++k) \
;         acc[ai][bj][m][n] = __builtin_amdgcn_mfma_f32_16x16x32_bf16(Bt[n][k], At[m][k], acc[ai][bj][m][n], 0, 0, 0); __builtin_amdgcn_s_setprio(0); } while (0)
; #define PG8_WAIT_V(n) asm volatile("s_waitcnt vmcnt(" #n ")" ::: "memory")
; #define PG8_WAIT_L(n) asm volatile("s_waitcnt lgkmcnt(" #n ")" ::: "memory")
; #define PG8_BAR __builtin_amdgcn_s_barrier()
; #define PG8_SCHED __builtin_amdgcn_sched_barrier(0)
; template <class Epi, class Sched, bool ALIGN_EPI = false, bool SP2 = false>
; __device__ __forceinline__ void gemm_phase(PG8_LAS unsigned char* lds, const Gemm g, const Sched& S, const Epi& E, int wave0) {
;     ...
;             PG8_WAIT_V(8); PG8_WAIT_L(0); PG8_BAR; PG8_MMA(1, 0, At, B0); PG8_MMA(1, 1, At, B1); PG8_BAR; PG8_SCHED;
;             PG8_LDB(B0, 1, 0); PG8_LDB(B1, 1, 1); PG8_SCHED; PG8_LDA(At, 1, 0); PG8_STAGE(PG8_SA(0, 1), a2 + hstep, voffA);
;             PG8_WAIT_V(8); PG8_WAIT_L(0); PG8_BAR; PG8_MMA(0, 0, At, B0); PG8_MMA(0, 1, At, B1); PG8_BAR; PG8_SCHED;
	s_setprio 1
	s_waitcnt lgkmcnt(0)
	v_mfma_f32_16x16x32_bf16 v[130:133], v[2:5], v[62:65], 0
	v_mfma_f32_16x16x32_bf16 v[138:141], v[2:5], v[106:109], 0
	v_mfma_f32_16x16x32_bf16 v[154:157], v[2:5], v[114:117], 0
	v_mfma_f32_16x16x32_bf16 v[2:5], v[2:5], v[122:125], 0
	v_mfma_f32_16x16x32_bf16 v[130:133], v[6:9], v[102:105], v[130:133]
	v_mfma_f32_16x16x32_bf16 v[138:141], v[6:9], v[110:113], v[138:141]
	v_mfma_f32_16x16x32_bf16 v[154:157], v[6:9], v[118:121], v[154:157]
	v_mfma_f32_16x16x32_bf16 v[2:5], v[6:9], v[126:129], v[2:5]
	v_mfma_f32_16x16x32_bf16 v[6:9], v[10:13], v[122:125], 0
	v_mfma_f32_16x16x32_bf16 v[134:137], v[10:13], v[62:65], 0
	v_mfma_f32_16x16x32_bf16 v[142:145], v[10:13], v[106:109], 0
	v_mfma_f32_16x16x32_bf16 v[160:163], v[10:13], v[114:117], 0
	v_mfma_f32_16x16x32_bf16 v[6:9], v[14:17], v[126:129], v[6:9]
	v_mfma_f32_16x16x32_bf16 v[134:137], v[14:17], v[102:105], v[134:137]
	v_mfma_f32_16x16x32_bf16 v[142:145], v[14:17], v[110:113], v[142:145]
	v_mfma_f32_16x16x32_bf16 v[160:163], v[14:17], v[118:121], v[160:163]
	v_mfma_f32_16x16x32_bf16 v[10:13], v[18:21], v[62:65], 0
	v_mfma_f32_16x16x32_bf16 v[14:17], v[26:29], v[62:65], 0
	v_mfma_f32_16x16x32_bf16 v[10:13], v[22:25], v[102:105], v[10:13]
	v_mfma_f32_16x16x32_bf16 v[14:17], v[30:33], v[102:105], v[14:17]
	v_mfma_f32_16x16x32_bf16 v[62:65], v[18:21], v[106:109], 0
	v_mfma_f32_16x16x32_bf16 v[102:105], v[26:29], v[106:109], 0
	v_mfma_f32_16x16x32_bf16 v[106:109], v[18:21], v[114:117], 0
	v_mfma_f32_16x16x32_bf16 v[18:21], v[18:21], v[122:125], 0
	v_mfma_f32_16x16x32_bf16 v[62:65], v[22:25], v[110:113], v[62:65]
	v_mfma_f32_16x16x32_bf16 v[102:105], v[30:33], v[110:113], v[102:105]
	v_mfma_f32_16x16x32_bf16 v[106:109], v[22:25], v[118:121], v[106:109]
	v_mfma_f32_16x16x32_bf16 v[110:113], v[26:29], v[114:117], 0
	v_mfma_f32_16x16x32_bf16 v[18:21], v[22:25], v[126:129], v[18:21]
	v_mfma_f32_16x16x32_bf16 v[22:25], v[26:29], v[122:125], 0
	v_mfma_f32_16x16x32_bf16 v[110:113], v[30:33], v[118:121], v[110:113]
	v_mfma_f32_16x16x32_bf16 v[22:25], v[30:33], v[126:129], v[22:25]
	s_setprio 0
	s_barrier
	s_add_i32 s74, 0, 0x18000
	s_add_i32 s80, 0, 0x1c000
	v_add_u32_e32 v172, s74, v153
	v_add_u32_e32 v216, s80, v153
	ds_read_b128 v[26:29], v172
	ds_read_b128 v[30:33], v172 offset:1024
	ds_read_b128 v[114:117], v172 offset:2048
	ds_read_b128 v[118:121], v172 offset:3072
	ds_read_b128 v[122:125], v216
	ds_read_b128 v[126:129], v216 offset:1024
	ds_read_b128 v[164:167], v216 offset:2048
	ds_read_b128 v[168:171], v216 offset:3072
	s_add_u32 s76, s4, 0x10100
	s_addc_u32 s77, s5, 0
	s_mov_b32 m0, s62
	v_lshl_add_u64 v[214:215], s[76:77], 0, v[150:151]
	ds_read_b128 v[174:177], v159 offset:32768
	ds_read_b128 v[178:181], v159 offset:33792
	ds_read_b128 v[182:185], v159 offset:34816
	ds_read_b128 v[186:189], v159 offset:35840
	ds_read_b128 v[190:193], v159 offset:36864
	ds_read_b128 v[194:197], v159 offset:37888
	ds_read_b128 v[198:201], v159 offset:38912
	ds_read_b128 v[202:205], v159 offset:39936
	global_load_lds_dwordx4 v[214:215], off
	v_lshl_add_u64 v[214:215], s[76:77], 0, v[148:149]
	s_mov_b32 m0, s63
	s_nop 0
	global_load_lds_dwordx4 v[214:215], off
	s_waitcnt vmcnt(8)
	s_waitcnt lgkmcnt(0)
	s_barrier
	s_setprio 1
	s_waitcnt lgkmcnt(0)
	v_mfma_f32_16x16x32_bf16 v[66:69], v[26:29], v[174:177], v[66:69]
	v_mfma_f32_16x16x32_bf16 v[70:73], v[114:117], v[174:177], v[70:73]
	v_mfma_f32_16x16x32_bf16 v[74:77], v[26:29], v[182:185], v[74:77]
	v_mfma_f32_16x16x32_bf16 v[78:81], v[114:117], v[182:185], v[78:81]
	v_mfma_f32_16x16x32_bf16 v[82:85], v[26:29], v[190:193], v[82:85]
	v_mfma_f32_16x16x32_bf16 v[86:89], v[114:117], v[190:193], v[86:89]
	v_mfma_f32_16x16x32_bf16 v[90:93], v[26:29], v[198:201], v[90:93]
	v_mfma_f32_16x16x32_bf16 v[94:97], v[114:117], v[198:201], v[94:97]
	v_mfma_f32_16x16x32_bf16 v[66:69], v[30:33], v[178:181], v[66:69]
	v_mfma_f32_16x16x32_bf16 v[70:73], v[118:121], v[178:181], v[70:73]
	v_mfma_f32_16x16x32_bf16 v[74:77], v[30:33], v[186:189], v[74:77]
	v_mfma_f32_16x16x32_bf16 v[78:81], v[118:121], v[186:189], v[78:81]
	v_mfma_f32_16x16x32_bf16 v[82:85], v[30:33], v[194:197], v[82:85]
	v_mfma_f32_16x16x32_bf16 v[86:89], v[118:121], v[194:197], v[86:89]
	v_mfma_f32_16x16x32_bf16 v[90:93], v[30:33], v[202:205], v[90:93]
	v_mfma_f32_16x16x32_bf16 v[94:97], v[118:121], v[202:205], v[94:97]
	v_mfma_f32_16x16x32_bf16 v[98:101], v[122:125], v[174:177], v[98:101]
	v_mfma_f32_16x16x32_bf16 v[34:37], v[164:167], v[174:177], v[34:37]
	v_mfma_f32_16x16x32_bf16 v[38:41], v[122:125], v[182:185], v[38:41]
	v_mfma_f32_16x16x32_bf16 v[42:45], v[164:167], v[182:185], v[42:45]
	v_mfma_f32_16x16x32_bf16 v[46:49], v[122:125], v[190:193], v[46:49]
	v_mfma_f32_16x16x32_bf16 v[50:53], v[164:167], v[190:193], v[50:53]
	v_mfma_f32_16x16x32_bf16 v[54:57], v[122:125], v[198:201], v[54:57]
	v_mfma_f32_16x16x32_bf16 v[58:61], v[164:167], v[198:201], v[58:61]
	v_mfma_f32_16x16x32_bf16 v[98:101], v[126:129], v[178:181], v[98:101]
	v_mfma_f32_16x16x32_bf16 v[34:37], v[168:171], v[178:181], v[34:37]
	v_mfma_f32_16x16x32_bf16 v[38:41], v[126:129], v[186:189], v[38:41]
	v_mfma_f32_16x16x32_bf16 v[42:45], v[168:171], v[186:189], v[42:45]
	v_mfma_f32_16x16x32_bf16 v[46:49], v[126:129], v[194:197], v[46:49]
	v_mfma_f32_16x16x32_bf16 v[50:53], v[168:171], v[194:197], v[50:53]
	v_mfma_f32_16x16x32_bf16 v[54:57], v[126:129], v[202:205], v[54:57]
	v_mfma_f32_16x16x32_bf16 v[58:61], v[168:171], v[202:205], v[58:61]
	s_setprio 0
	s_barrier
; #define PG8_STAGE(bufoff, gbase, voff) do { _Pragma("unroll") for (int _i = 0; _i < 2; ++_i) \
;         __builtin_amdgcn_global_load_lds((const unsigned*)((const char*)(gbase) + (voff)[_i]), (PG8_LAS unsigned*)(lds + (bufoff) + ldsw + _i * 8192), 16, 0, 0); } while (0)
; #define PG8_LDA(dst, b, h) do { _Pragma("unroll") for (int m = 0; m < 4; ++m) _Pragma("unroll") for (int k = 0; k < 2; ++k) dst[m][k] = *(const PG8_LAS bf16x8*)(lds + PG8_SA(b, h) + aoff + m * 2048 + k * 1024); } while (0)
; #define PG8_LDB(dst, b, h) do { _Pragma("unroll") for (int n = 0; n < 2; ++n) _Pragma("unroll") for (int k = 0; k < 2; ++k) dst[n][k] = *(const PG8_LAS bf16x8*)(lds + PG8_SB(b, h) + boff + n * 2048 + k * 1024); } while (0)
; #define PG8_MMA(ai, bj, At, Bt) do { __builtin_amdgcn_s_setprio(1); _Pragma("unroll") for (int m = 0; m < 4; ++m) _Pragma("unroll") for (int n = 0; n < 2; ++n) _Pragma("unroll") for (int k = 0; k < 2; ++k) \
;         acc[ai][bj][m][n] = __builtin_amdgcn_mfma_f32_16x16x32_bf16(Bt[n][k], At[m][k], acc[ai][bj][m][n], 0, 0, 0); __builtin_amdgcn_s_setprio(0); } while (0)
; #define PG8_BAR __builtin_amdgcn_s_barrier()
; template <class Epi, class Sched, bool ALIGN_EPI = false, bool SP2 = false>
; __device__ __forceinline__ void gemm_phase(PG8_LAS unsigned char* lds, const Gemm g, const Sched& S, const Epi& E, int wave0) {
;     ...
;             PG8_LDB(B0, 0, 0); PG8_LDB(B1, 0, 1); PG8_SCHED; PG8_LDA(At, 0, 0); PG8_STAGE(PG8_SA(1, 1), a1 + hstep, voffA);
;             PG8_WAIT_V(8); PG8_WAIT_L(0); PG8_BAR; PG8_MMA(0, 0, At, B0); PG8_MMA(0, 1, At, B1); PG8_BAR; PG8_SCHED;
;             PG8_LDA(At, 0, 1); PG8_STAGE(PG8_SB(0, 0), b2, voffB); PG8_STAGE(PG8_SB(0, 1), b2 + hstep, voffB); PG8_STAGE(PG8_SA(0, 0), a2, voffA);
;             PG8_WAIT_V(8); PG8_WAIT_L(0); PG8_BAR; PG8_MMA(1, 0, At, B0); PG8_MMA(1, 1, At, B1); PG8_BAR; PG8_SCHED;
;             PG8_LDB(B0, 1, 0); PG8_LDB(B1, 1, 1); PG8_SCHED; PG8_LDA(At, 1, 0); PG8_STAGE(PG8_SA(0, 1), a2 + hstep, voffA);
;             PG8_WAIT_V(8); PG8_WAIT_L(0); PG8_BAR; PG8_MMA(0, 0, At, B0); PG8_MMA(0, 1, At, B1); PG8_BAR; PG8_SCHED;
;             PG8_LDA(At, 1, 1); PG8_STAGE(PG8_SB(1, 0), b3, voffB); PG8_STAGE(PG8_SB(1, 1), b3 + hstep, voffB); PG8_STAGE(PG8_SA(1, 0), a3, voffA);
;             PG8_WAIT_V(8); PG8_WAIT_L(0); PG8_BAR; PG8_MMA(1, 0, At, B0); PG8_MMA(1, 1, At, B1); PG8_BAR; PG8_SCHED;
	s_add_i32 s76, s74, s59
	s_mov_b64 s[82:83], 0x180
	s_add_i32 s74, s76, 0x2000
	v_lshl_add_u64 v[206:207], v[206:207], 0, s[82:83]
	s_mov_b32 m0, s76
	s_add_u32 s78, s52, 0x10180
	ds_read_b128 v[174:177], v159 offset:49152
	ds_read_b128 v[178:181], v159 offset:50176
	ds_read_b128 v[182:185], v159 offset:51200
	ds_read_b128 v[186:189], v159 offset:52224
	ds_read_b128 v[190:193], v159 offset:53248
	ds_read_b128 v[194:197], v159 offset:54272
	ds_read_b128 v[198:201], v159 offset:55296
	ds_read_b128 v[202:205], v159 offset:56320
	global_load_lds_dwordx4 v[206:207], off
	v_lshl_add_u64 v[206:207], v[208:209], 0, s[82:83]
	s_mov_b32 m0, s74
	s_addc_u32 s79, s53, 0
	s_add_i32 s52, s80, s59
	global_load_lds_dwordx4 v[206:207], off
	v_lshl_add_u64 v[206:207], s[78:79], 0, v[0:1]
	s_mov_b32 m0, s52
	s_add_i32 s53, s52, 0x2000
	global_load_lds_dwordx4 v[206:207], off
	v_lshl_add_u64 v[206:207], s[78:79], 0, v[146:147]
	s_mov_b32 m0, s53
	s_nop 0
	global_load_lds_dwordx4 v[206:207], off
	v_lshl_add_u64 v[206:207], v[210:211], 0, s[82:83]
	s_mov_b32 m0, s65
	s_nop 0
	global_load_lds_dwordx4 v[206:207], off
	v_lshl_add_u64 v[206:207], v[212:213], 0, s[82:83]
	s_mov_b32 m0, s66
	s_nop 0
	global_load_lds_dwordx4 v[206:207], off
	s_waitcnt vmcnt(8)
	s_waitcnt lgkmcnt(0)
	s_barrier
	s_setprio 1
	s_waitcnt lgkmcnt(0)
	v_mfma_f32_16x16x32_bf16 v[2:5], v[26:29], v[198:201], v[2:5]
	v_mfma_f32_16x16x32_bf16 v[6:9], v[114:117], v[198:201], v[6:9]
	v_mfma_f32_16x16x32_bf16 v[130:133], v[26:29], v[174:177], v[130:133]
	v_mfma_f32_16x16x32_bf16 v[134:137], v[114:117], v[174:177], v[134:137]
	v_mfma_f32_16x16x32_bf16 v[138:141], v[26:29], v[182:185], v[138:141]
	v_mfma_f32_16x16x32_bf16 v[142:145], v[114:117], v[182:185], v[142:145]
	v_mfma_f32_16x16x32_bf16 v[154:157], v[26:29], v[190:193], v[154:157]
	v_mfma_f32_16x16x32_bf16 v[160:163], v[114:117], v[190:193], v[160:163]
	v_mfma_f32_16x16x32_bf16 v[2:5], v[30:33], v[202:205], v[2:5]
	v_mfma_f32_16x16x32_bf16 v[6:9], v[118:121], v[202:205], v[6:9]
	v_mfma_f32_16x16x32_bf16 v[130:133], v[30:33], v[178:181], v[130:133]
	v_mfma_f32_16x16x32_bf16 v[134:137], v[118:121], v[178:181], v[134:137]
	v_mfma_f32_16x16x32_bf16 v[138:141], v[30:33], v[186:189], v[138:141]
	v_mfma_f32_16x16x32_bf16 v[142:145], v[118:121], v[186:189], v[142:145]
	v_mfma_f32_16x16x32_bf16 v[154:157], v[30:33], v[194:197], v[154:157]
	v_mfma_f32_16x16x32_bf16 v[160:163], v[118:121], v[194:197], v[160:163]
	v_mfma_f32_16x16x32_bf16 v[10:13], v[122:125], v[174:177], v[10:13]
	v_mfma_f32_16x16x32_bf16 v[14:17], v[164:167], v[174:177], v[14:17]
	v_mfma_f32_16x16x32_bf16 v[26:29], v[122:125], v[182:185], v[62:65]
	v_mfma_f32_16x16x32_bf16 v[30:33], v[164:167], v[182:185], v[102:105]
	v_mfma_f32_16x16x32_bf16 v[62:65], v[122:125], v[190:193], v[106:109]
	v_mfma_f32_16x16x32_bf16 v[102:105], v[164:167], v[190:193], v[110:113]
	v_mfma_f32_16x16x32_bf16 v[18:21], v[122:125], v[198:201], v[18:21]
	v_mfma_f32_16x16x32_bf16 v[22:25], v[164:167], v[198:201], v[22:25]
	v_mfma_f32_16x16x32_bf16 v[10:13], v[126:129], v[178:181], v[10:13]
	v_mfma_f32_16x16x32_bf16 v[14:17], v[168:171], v[178:181], v[14:17]
	v_mfma_f32_16x16x32_bf16 v[26:29], v[126:129], v[186:189], v[26:29]
	v_mfma_f32_16x16x32_bf16 v[30:33], v[168:171], v[186:189], v[30:33]
	v_mfma_f32_16x16x32_bf16 v[62:65], v[126:129], v[194:197], v[62:65]
	v_mfma_f32_16x16x32_bf16 v[102:105], v[168:171], v[194:197], v[102:105]
	v_mfma_f32_16x16x32_bf16 v[18:21], v[126:129], v[202:205], v[18:21]
	v_mfma_f32_16x16x32_bf16 v[22:25], v[168:171], v[202:205], v[22:25]
	s_setprio 0
	s_barrier
	ds_read_b128 v[106:109], v152
	ds_read_b128 v[110:113], v152 offset:1024
	ds_read_b128 v[114:117], v152 offset:2048
	ds_read_b128 v[118:121], v152 offset:3072
	ds_read_b128 v[122:125], v158
	ds_read_b128 v[126:129], v158 offset:1024
	ds_read_b128 v[164:167], v158 offset:2048
	ds_read_b128 v[168:171], v158 offset:3072
	s_add_u32 s4, s4, 0x10180
	s_addc_u32 s5, s5, 0
	s_mov_b32 m0, s75
	v_lshl_add_u64 v[206:207], s[4:5], 0, v[150:151]
	ds_read_b128 v[174:177], v159
	ds_read_b128 v[178:181], v159 offset:1024
	ds_read_b128 v[182:185], v159 offset:2048
	ds_read_b128 v[186:189], v159 offset:3072
	ds_read_b128 v[190:193], v159 offset:4096
	ds_read_b128 v[194:197], v159 offset:5120
	ds_read_b128 v[198:201], v159 offset:6144
	ds_read_b128 v[202:205], v159 offset:7168
	global_load_lds_dwordx4 v[206:207], off
	v_lshl_add_u64 v[206:207], s[4:5], 0, v[148:149]
	s_mov_b32 m0, s29
	s_nop 0
	global_load_lds_dwordx4 v[206:207], off
	s_waitcnt vmcnt(8)
	s_waitcnt lgkmcnt(0)
	s_barrier
; #define PG8_STAGE(bufoff, gbase, voff) do { _Pragma("unroll") for (int _i = 0; _i < 2; ++_i) \
;         __builtin_amdgcn_global_load_lds((const unsigned*)((const char*)(gbase) + (voff)[_i]), (PG8_LAS unsigned*)(lds + (bufoff) + ldsw + _i * 8192), 16, 0, 0); } while (0)
; #define PG8_LDA(dst, b, h) do { _Pragma("unroll") for (int m = 0; m < 4; ++m) _Pragma("unroll") for (int k = 0; k < 2; ++k) dst[m][k] = *(const PG8_LAS bf16x8*)(lds + PG8_SA(b, h) + aoff + m * 2048 + k * 1024); } while (0)
; #define PG8_MMA(ai, bj, At, Bt) do { __builtin_amdgcn_s_setprio(1); _Pragma("unroll") for (int m = 0; m < 4; ++m) _Pragma("unroll") for (int n = 0; n < 2; ++n) _Pragma("unroll") for (int k = 0; k < 2; ++k) \
;         acc[ai][bj][m][n] = __builtin_amdgcn_mfma_f32_16x16x32_bf16(Bt[n][k], At[m][k], acc[ai][bj][m][n], 0, 0, 0); __builtin_amdgcn_s_setprio(0); } while (0)
; #define PG8_WAIT_V(n) asm volatile("s_waitcnt vmcnt(" #n ")" ::: "memory")
; #define PG8_WAIT_L(n) asm volatile("s_waitcnt lgkmcnt(" #n ")" ::: "memory")
; #define PG8_BAR __builtin_amdgcn_s_barrier()
; #define PG8_SCHED __builtin_amdgcn_sched_barrier(0)
; template <class Epi, class Sched, bool ALIGN_EPI = false, bool SP2 = false>
; __device__ __forceinline__ void gemm_phase(PG8_LAS unsigned char* lds, const Gemm g, const Sched& S, const Epi& E, int wave0) {
;     ...
;             PG8_WAIT_V(8); PG8_WAIT_L(0); PG8_BAR; PG8_MMA(0, 0, At, B0); PG8_MMA(0, 1, At, B1); PG8_BAR; PG8_SCHED;
;             PG8_LDA(At, 0, 1); PG8_STAGE(PG8_SB(0, 0), b2, voffB); PG8_STAGE(PG8_SB(0, 1), b2 + hstep, voffB); PG8_STAGE(PG8_SA(0, 0), a2, voffA);
;             PG8_WAIT_V(8); PG8_WAIT_L(0); PG8_BAR; PG8_MMA(1, 0, At, B0); PG8_MMA(1, 1, At, B1); PG8_BAR; PG8_SCHED;
	s_setprio 1
	s_waitcnt lgkmcnt(0)
	v_mfma_f32_16x16x32_bf16 v[66:69], v[106:109], v[174:177], v[66:69]
	v_mfma_f32_16x16x32_bf16 v[70:73], v[114:117], v[174:177], v[70:73]
	v_mfma_f32_16x16x32_bf16 v[74:77], v[106:109], v[182:185], v[74:77]
	v_mfma_f32_16x16x32_bf16 v[78:81], v[114:117], v[182:185], v[78:81]
	v_mfma_f32_16x16x32_bf16 v[82:85], v[106:109], v[190:193], v[82:85]
	v_mfma_f32_16x16x32_bf16 v[86:89], v[114:117], v[190:193], v[86:89]
	v_mfma_f32_16x16x32_bf16 v[90:93], v[106:109], v[198:201], v[90:93]
	v_mfma_f32_16x16x32_bf16 v[66:69], v[110:113], v[178:181], v[66:69]
	v_mfma_f32_16x16x32_bf16 v[70:73], v[118:121], v[178:181], v[70:73]
	v_mfma_f32_16x16x32_bf16 v[74:77], v[110:113], v[186:189], v[74:77]
	v_mfma_f32_16x16x32_bf16 v[78:81], v[118:121], v[186:189], v[78:81]
	v_mfma_f32_16x16x32_bf16 v[82:85], v[110:113], v[194:197], v[82:85]
	v_mfma_f32_16x16x32_bf16 v[86:89], v[118:121], v[194:197], v[86:89]
	v_mfma_f32_16x16x32_bf16 v[90:93], v[110:113], v[202:205], v[90:93]
	v_mfma_f32_16x16x32_bf16 v[94:97], v[114:117], v[198:201], v[94:97]
	v_mfma_f32_16x16x32_bf16 v[206:209], v[118:121], v[202:205], v[94:97]
	v_mfma_f32_16x16x32_bf16 v[94:97], v[122:125], v[174:177], v[98:101]
	v_mfma_f32_16x16x32_bf16 v[34:37], v[164:167], v[174:177], v[34:37]
	v_mfma_f32_16x16x32_bf16 v[38:41], v[122:125], v[182:185], v[38:41]
	v_mfma_f32_16x16x32_bf16 v[42:45], v[164:167], v[182:185], v[42:45]
	v_mfma_f32_16x16x32_bf16 v[46:49], v[122:125], v[190:193], v[46:49]
	v_mfma_f32_16x16x32_bf16 v[50:53], v[164:167], v[190:193], v[50:53]
	v_mfma_f32_16x16x32_bf16 v[54:57], v[122:125], v[198:201], v[54:57]
	v_mfma_f32_16x16x32_bf16 v[58:61], v[164:167], v[198:201], v[58:61]
	v_mfma_f32_16x16x32_bf16 v[98:101], v[126:129], v[178:181], v[94:97]
	v_mfma_f32_16x16x32_bf16 v[34:37], v[168:171], v[178:181], v[34:37]
	v_mfma_f32_16x16x32_bf16 v[38:41], v[126:129], v[186:189], v[38:41]
	v_mfma_f32_16x16x32_bf16 v[42:45], v[168:171], v[186:189], v[42:45]
	v_mfma_f32_16x16x32_bf16 v[46:49], v[126:129], v[194:197], v[46:49]
	v_mfma_f32_16x16x32_bf16 v[50:53], v[168:171], v[194:197], v[50:53]
	v_mfma_f32_16x16x32_bf16 v[54:57], v[126:129], v[202:205], v[54:57]
	v_mfma_f32_16x16x32_bf16 v[58:61], v[168:171], v[202:205], v[58:61]
	s_setprio 0
	s_barrier
	s_mov_b32 m0, s73
	v_lshl_add_u64 v[230:231], s[54:55], 0, v[0:1]
	s_add_u32 s4, s54, 0x10000
	ds_read_b128 v[94:97], v159 offset:16384
	ds_read_b128 v[174:177], v159 offset:17408
	ds_read_b128 v[178:181], v159 offset:18432
	ds_read_b128 v[182:185], v159 offset:19456
	ds_read_b128 v[186:189], v159 offset:20480
	ds_read_b128 v[190:193], v159 offset:21504
	ds_read_b128 v[194:197], v159 offset:22528
	ds_read_b128 v[198:201], v159 offset:23552
	global_load_lds_dwordx4 v[230:231], off
	v_lshl_add_u64 v[232:233], s[54:55], 0, v[146:147]
	s_mov_b32 m0, s47
	s_addc_u32 s5, s55, 0
	global_load_lds_dwordx4 v[232:233], off
	v_lshl_add_u64 v[202:203], s[4:5], 0, v[0:1]
	s_mov_b32 m0, s71
	v_lshl_add_u64 v[234:235], s[56:57], 0, v[150:151]
	global_load_lds_dwordx4 v[202:203], off
	v_lshl_add_u64 v[202:203], s[4:5], 0, v[146:147]
	s_mov_b32 m0, s72
	v_lshl_add_u64 v[246:247], s[56:57], 0, v[148:149]
	global_load_lds_dwordx4 v[202:203], off
	s_mov_b32 m0, s60
	s_nop 0
	global_load_lds_dwordx4 v[234:235], off
	s_mov_b32 m0, s61
	s_nop 0
	global_load_lds_dwordx4 v[246:247], off
	s_waitcnt vmcnt(8)
	s_waitcnt lgkmcnt(0)
	s_barrier
	s_setprio 1
	s_waitcnt lgkmcnt(0)
	v_mfma_f32_16x16x32_bf16 v[2:5], v[106:109], v[194:197], v[2:5]
	v_mfma_f32_16x16x32_bf16 v[6:9], v[114:117], v[194:197], v[6:9]
	v_mfma_f32_16x16x32_bf16 v[130:133], v[106:109], v[94:97], v[130:133]
	v_mfma_f32_16x16x32_bf16 v[134:137], v[114:117], v[94:97], v[134:137]
	v_mfma_f32_16x16x32_bf16 v[138:141], v[106:109], v[178:181], v[138:141]
	v_mfma_f32_16x16x32_bf16 v[142:145], v[114:117], v[178:181], v[142:145]
	v_mfma_f32_16x16x32_bf16 v[154:157], v[106:109], v[186:189], v[154:157]
	v_mfma_f32_16x16x32_bf16 v[160:163], v[114:117], v[186:189], v[160:163]
	v_mfma_f32_16x16x32_bf16 v[2:5], v[110:113], v[198:201], v[2:5]
	v_mfma_f32_16x16x32_bf16 v[6:9], v[118:121], v[198:201], v[6:9]
	v_mfma_f32_16x16x32_bf16 v[130:133], v[110:113], v[174:177], v[130:133]
	v_mfma_f32_16x16x32_bf16 v[134:137], v[118:121], v[174:177], v[134:137]
	v_mfma_f32_16x16x32_bf16 v[138:141], v[110:113], v[182:185], v[138:141]
	v_mfma_f32_16x16x32_bf16 v[142:145], v[118:121], v[182:185], v[142:145]
	v_mfma_f32_16x16x32_bf16 v[154:157], v[110:113], v[190:193], v[154:157]
	v_mfma_f32_16x16x32_bf16 v[160:163], v[118:121], v[190:193], v[160:163]
	v_mfma_f32_16x16x32_bf16 v[10:13], v[122:125], v[94:97], v[10:13]
	v_mfma_f32_16x16x32_bf16 v[14:17], v[164:167], v[94:97], v[14:17]
	v_mfma_f32_16x16x32_bf16 v[10:13], v[126:129], v[174:177], v[10:13]
	v_mfma_f32_16x16x32_bf16 v[174:177], v[168:171], v[174:177], v[14:17]
	v_mfma_f32_16x16x32_bf16 v[14:17], v[122:125], v[178:181], v[26:29]
	v_mfma_f32_16x16x32_bf16 v[26:29], v[126:129], v[182:185], v[14:17]
	v_mfma_f32_16x16x32_bf16 v[14:17], v[164:167], v[178:181], v[30:33]
	v_mfma_f32_16x16x32_bf16 v[178:181], v[168:171], v[182:185], v[14:17]
	v_mfma_f32_16x16x32_bf16 v[14:17], v[122:125], v[186:189], v[62:65]
	v_mfma_f32_16x16x32_bf16 v[182:185], v[126:129], v[190:193], v[14:17]
	v_mfma_f32_16x16x32_bf16 v[14:17], v[164:167], v[186:189], v[102:105]
	v_mfma_f32_16x16x32_bf16 v[186:189], v[168:171], v[190:193], v[14:17]
	v_mfma_f32_16x16x32_bf16 v[14:17], v[122:125], v[194:197], v[18:21]
	v_mfma_f32_16x16x32_bf16 v[190:193], v[126:129], v[198:201], v[14:17]
	v_mfma_f32_16x16x32_bf16 v[14:17], v[164:167], v[194:197], v[22:25]
	v_mfma_f32_16x16x32_bf16 v[164:167], v[168:171], v[198:201], v[14:17]
	s_setprio 0
	s_barrier
; #define PG8_STAGE(bufoff, gbase, voff) do { _Pragma("unroll") for (int _i = 0; _i < 2; ++_i) \
;         __builtin_amdgcn_global_load_lds((const unsigned*)((const char*)(gbase) + (voff)[_i]), (PG8_LAS unsigned*)(lds + (bufoff) + ldsw + _i * 8192), 16, 0, 0); } while (0)
; #define PG8_LDA(dst, b, h) do { _Pragma("unroll") for (int m = 0; m < 4; ++m) _Pragma("unroll") for (int k = 0; k < 2; ++k) dst[m][k] = *(const PG8_LAS bf16x8*)(lds + PG8_SA(b, h) + aoff + m * 2048 + k * 1024); } while (0)
; #define PG8_LDB(dst, b, h) do { _Pragma("unroll") for (int n = 0; n < 2; ++n) _Pragma("unroll") for (int k = 0; k < 2; ++k) dst[n][k] = *(const PG8_LAS bf16x8*)(lds + PG8_SB(b, h) + boff + n * 2048 + k * 1024); } while (0)
; #define PG8_MMA(ai, bj, At, Bt) do { __builtin_amdgcn_s_setprio(1); _Pragma("unroll") for (int m = 0; m < 4; ++m) _Pragma("unroll") for (int n = 0; n < 2; ++n) _Pragma("unroll") for (int k = 0; k < 2; ++k) \
;         acc[ai][bj][m][n] = __builtin_amdgcn_mfma_f32_16x16x32_bf16(Bt[n][k], At[m][k], acc[ai][bj][m][n], 0, 0, 0); __builtin_amdgcn_s_setprio(0); } while (0)
; #define PG8_WAIT_V(n) asm volatile("s_waitcnt vmcnt(" #n ")" ::: "memory")
; #define PG8_WAIT_L(n) asm volatile("s_waitcnt lgkmcnt(" #n ")" ::: "memory")
; #define PG8_BAR __builtin_amdgcn_s_barrier()
; #define PG8_SCHED __builtin_amdgcn_sched_barrier(0)
; template <class Epi, class Sched, bool ALIGN_EPI = false, bool SP2 = false>
; __device__ __forceinline__ void gemm_phase(PG8_LAS unsigned char* lds, const Gemm g, const Sched& S, const Epi& E, int wave0) {
;     ...
;             PG8_LDB(B0, 1, 0); PG8_LDB(B1, 1, 1); PG8_SCHED; PG8_LDA(At, 1, 0); PG8_STAGE(PG8_SA(0, 1), a2 + hstep, voffA);
;             PG8_WAIT_V(8); PG8_WAIT_L(0); PG8_BAR; PG8_MMA(0, 0, At, B0); PG8_MMA(0, 1, At, B1); PG8_BAR; PG8_SCHED;
;             PG8_LDA(At, 1, 1); PG8_STAGE(PG8_SB(1, 0), b3, voffB); PG8_STAGE(PG8_SB(1, 1), b3 + hstep, voffB); PG8_STAGE(PG8_SA(1, 0), a3, voffA);
;             PG8_WAIT_V(8); PG8_WAIT_L(0); PG8_BAR; PG8_MMA(1, 0, At, B0); PG8_MMA(1, 1, At, B1); PG8_BAR; PG8_SCHED;
;     ...
;         if constexpr (ALIGN_EPI) { if (wr == 0) PG8_BAR; }
	s_nop 4
	ds_read_b128 v[14:17], v172
	ds_read_b128 v[18:21], v172 offset:1024
	ds_read_b128 v[168:171], v172 offset:2048
	ds_read_b128 v[194:197], v172 offset:3072
	ds_read_b128 v[198:201], v216
	ds_read_b128 v[202:205], v216 offset:1024
	ds_read_b128 v[210:213], v216 offset:2048
	ds_read_b128 v[214:217], v216 offset:3072
	s_add_u32 s4, s56, 0x10000
	s_addc_u32 s5, s57, 0
	s_mov_b32 m0, s62
	v_lshl_add_u64 v[94:95], s[4:5], 0, v[150:151]
	ds_read_b128 v[22:25], v159 offset:32768
	ds_read_b128 v[30:33], v159 offset:33792
	ds_read_b128 v[62:65], v159 offset:34816
	ds_read_b128 v[218:221], v159 offset:35840
	ds_read_b128 v[222:225], v159 offset:36864
	ds_read_b128 v[226:229], v159 offset:37888
	ds_read_b128 v[238:241], v159 offset:38912
	ds_read_b128 v[242:245], v159 offset:39936
	global_load_lds_dwordx4 v[94:95], off
	v_lshl_add_u64 v[94:95], s[4:5], 0, v[148:149]
	s_mov_b32 m0, s63
	s_nop 0
	global_load_lds_dwordx4 v[94:95], off
	s_waitcnt vmcnt(8)
	s_waitcnt lgkmcnt(0)
	s_barrier
	s_setprio 1
	s_waitcnt lgkmcnt(0)
	v_mfma_f32_16x16x32_bf16 v[66:69], v[14:17], v[22:25], v[66:69]
	v_mfma_f32_16x16x32_bf16 v[126:129], v[18:21], v[30:33], v[66:69]
	v_mfma_f32_16x16x32_bf16 v[66:69], v[168:171], v[22:25], v[70:73]
	v_mfma_f32_16x16x32_bf16 v[118:121], v[194:197], v[30:33], v[66:69]
	v_mfma_f32_16x16x32_bf16 v[66:69], v[14:17], v[62:65], v[74:77]
	v_mfma_f32_16x16x32_bf16 v[110:113], v[18:21], v[218:221], v[66:69]
	v_mfma_f32_16x16x32_bf16 v[66:69], v[168:171], v[62:65], v[78:81]
	v_mfma_f32_16x16x32_bf16 v[102:105], v[194:197], v[218:221], v[66:69]
	v_mfma_f32_16x16x32_bf16 v[66:69], v[14:17], v[222:225], v[82:85]
	v_mfma_f32_16x16x32_bf16 v[94:97], v[18:21], v[226:229], v[66:69]
	v_mfma_f32_16x16x32_bf16 v[66:69], v[168:171], v[222:225], v[86:89]
	v_mfma_f32_16x16x32_bf16 v[86:89], v[194:197], v[226:229], v[66:69]
	v_mfma_f32_16x16x32_bf16 v[66:69], v[14:17], v[238:241], v[90:93]
	v_mfma_f32_16x16x32_bf16 v[78:81], v[18:21], v[242:245], v[66:69]
	v_mfma_f32_16x16x32_bf16 v[66:69], v[168:171], v[238:241], v[206:209]
	v_mfma_f32_16x16x32_bf16 v[70:73], v[194:197], v[242:245], v[66:69]
	v_mfma_f32_16x16x32_bf16 v[66:69], v[198:201], v[22:25], v[98:101]
	v_mfma_f32_16x16x32_bf16 v[22:25], v[210:213], v[22:25], v[34:37]
	v_mfma_f32_16x16x32_bf16 v[114:117], v[214:217], v[30:33], v[22:25]
	v_mfma_f32_16x16x32_bf16 v[22:25], v[198:201], v[62:65], v[38:41]
	v_mfma_f32_16x16x32_bf16 v[106:109], v[202:205], v[218:221], v[22:25]
	v_mfma_f32_16x16x32_bf16 v[22:25], v[210:213], v[62:65], v[42:45]
	v_mfma_f32_16x16x32_bf16 v[98:101], v[214:217], v[218:221], v[22:25]
	v_mfma_f32_16x16x32_bf16 v[22:25], v[198:201], v[222:225], v[46:49]
	v_mfma_f32_16x16x32_bf16 v[90:93], v[202:205], v[226:229], v[22:25]
	v_mfma_f32_16x16x32_bf16 v[22:25], v[210:213], v[222:225], v[50:53]
	v_mfma_f32_16x16x32_bf16 v[82:85], v[214:217], v[226:229], v[22:25]
	v_mfma_f32_16x16x32_bf16 v[22:25], v[198:201], v[238:241], v[54:57]
	v_mfma_f32_16x16x32_bf16 v[74:77], v[202:205], v[242:245], v[22:25]
	v_mfma_f32_16x16x32_bf16 v[22:25], v[210:213], v[238:241], v[58:61]
	v_mfma_f32_16x16x32_bf16 v[122:125], v[202:205], v[30:33], v[66:69]
	v_mfma_f32_16x16x32_bf16 v[66:69], v[214:217], v[242:245], v[22:25]
	s_setprio 0
	s_barrier
	s_mov_b32 m0, s76
	s_nop 2
	v_lshl_add_u64 v[22:23], v[230:231], 0, s[34:35]
	s_add_u32 s4, s54, 0x10080
	ds_read_b128 v[34:37], v159 offset:49152
	ds_read_b128 v[42:45], v159 offset:50176
	ds_read_b128 v[206:209], v159 offset:51200
	ds_read_b128 v[218:221], v159 offset:52224
	ds_read_b128 v[222:225], v159 offset:53248
	ds_read_b128 v[226:229], v159 offset:54272
	ds_read_b128 v[238:241], v159 offset:55296
	ds_read_b128 v[242:245], v159 offset:56320
	global_load_lds_dwordx4 v[22:23], off
	v_lshl_add_u64 v[22:23], v[232:233], 0, s[34:35]
	s_mov_b32 m0, s74
	s_addc_u32 s5, s55, 0
	global_load_lds_dwordx4 v[22:23], off
	v_lshl_add_u64 v[22:23], s[4:5], 0, v[0:1]
	s_mov_b32 m0, s52
	s_nop 0
	global_load_lds_dwordx4 v[22:23], off
	v_lshl_add_u64 v[22:23], s[4:5], 0, v[146:147]
	s_mov_b32 m0, s53
	s_nop 0
	global_load_lds_dwordx4 v[22:23], off
	v_lshl_add_u64 v[22:23], v[234:235], 0, s[34:35]
	s_mov_b32 m0, s65
	s_nop 0
	global_load_lds_dwordx4 v[22:23], off
	v_lshl_add_u64 v[22:23], v[246:247], 0, s[34:35]
	s_mov_b32 m0, s66
	s_nop 0
	global_load_lds_dwordx4 v[22:23], off
	s_waitcnt vmcnt(8)
	s_waitcnt lgkmcnt(0)
	s_barrier
	s_setprio 1
	s_waitcnt lgkmcnt(0)
	v_mfma_f32_16x16x32_bf16 v[22:25], v[14:17], v[34:37], v[130:133]
	v_mfma_f32_16x16x32_bf16 v[62:65], v[18:21], v[42:45], v[22:25]
	v_mfma_f32_16x16x32_bf16 v[22:25], v[168:171], v[34:37], v[134:137]
	v_mfma_f32_16x16x32_bf16 v[54:57], v[194:197], v[42:45], v[22:25]
	v_mfma_f32_16x16x32_bf16 v[22:25], v[14:17], v[206:209], v[138:141]
	v_mfma_f32_16x16x32_bf16 v[46:49], v[18:21], v[218:221], v[22:25]
	v_mfma_f32_16x16x32_bf16 v[22:25], v[168:171], v[206:209], v[142:145]
	v_mfma_f32_16x16x32_bf16 v[38:41], v[194:197], v[218:221], v[22:25]
	v_mfma_f32_16x16x32_bf16 v[22:25], v[14:17], v[222:225], v[154:157]
	v_mfma_f32_16x16x32_bf16 v[2:5], v[14:17], v[238:241], v[2:5]
	v_mfma_f32_16x16x32_bf16 v[30:33], v[18:21], v[226:229], v[22:25]
	v_mfma_f32_16x16x32_bf16 v[22:25], v[168:171], v[222:225], v[160:163]
	v_mfma_f32_16x16x32_bf16 v[14:17], v[18:21], v[242:245], v[2:5]
	v_mfma_f32_16x16x32_bf16 v[2:5], v[168:171], v[238:241], v[6:9]
	v_mfma_f32_16x16x32_bf16 v[22:25], v[194:197], v[226:229], v[22:25]
	v_mfma_f32_16x16x32_bf16 v[6:9], v[194:197], v[242:245], v[2:5]
	v_mfma_f32_16x16x32_bf16 v[2:5], v[198:201], v[34:37], v[10:13]
	v_mfma_f32_16x16x32_bf16 v[58:61], v[202:205], v[42:45], v[2:5]
	v_mfma_f32_16x16x32_bf16 v[2:5], v[210:213], v[34:37], v[174:177]
	v_mfma_f32_16x16x32_bf16 v[50:53], v[214:217], v[42:45], v[2:5]
	v_mfma_f32_16x16x32_bf16 v[2:5], v[198:201], v[206:209], v[26:29]
	v_mfma_f32_16x16x32_bf16 v[42:45], v[202:205], v[218:221], v[2:5]
	v_mfma_f32_16x16x32_bf16 v[2:5], v[210:213], v[206:209], v[178:181]
	v_mfma_f32_16x16x32_bf16 v[34:37], v[214:217], v[218:221], v[2:5]
	v_mfma_f32_16x16x32_bf16 v[2:5], v[198:201], v[222:225], v[182:185]
	v_mfma_f32_16x16x32_bf16 v[26:29], v[202:205], v[226:229], v[2:5]
	v_mfma_f32_16x16x32_bf16 v[2:5], v[210:213], v[222:225], v[186:189]
	v_mfma_f32_16x16x32_bf16 v[18:21], v[214:217], v[226:229], v[2:5]
	v_mfma_f32_16x16x32_bf16 v[2:5], v[198:201], v[238:241], v[190:193]
	v_mfma_f32_16x16x32_bf16 v[10:13], v[202:205], v[242:245], v[2:5]
	v_mfma_f32_16x16x32_bf16 v[2:5], v[210:213], v[238:241], v[164:167]
	v_mfma_f32_16x16x32_bf16 v[2:5], v[214:217], v[242:245], v[2:5]
	s_setprio 0
	s_barrier
	s_andn2_b64 vcc, exec, s[38:39]
	s_cbranch_vccnz .LBB0_414
	s_barrier

; #define PG8_STAGE(bufoff, gbase, voff) do { _Pragma("unroll") for (int _i = 0; _i < 2; ++_i) \
;         __builtin_amdgcn_global_load_lds((const unsigned*)((const char*)(gbase) + (voff)[_i]), (PG8_LAS unsigned*)(lds + (bufoff) + ldsw + _i * 8192), 16, 0, 0); } while (0)
; #define PG8_LDA(dst, b, h) do { _Pragma("unroll") for (int m = 0; m < 4; ++m) _Pragma("unroll") for (int k = 0; k < 2; ++k) dst[m][k] = *(const PG8_LAS bf16x8*)(lds + PG8_SA(b, h) + aoff + m * 2048 + k * 1024); } while (0)
; #define PG8_LDB(dst, b, h) do { _Pragma("unroll") for (int n = 0; n < 2; ++n) _Pragma("unroll") for (int k = 0; k < 2; ++k) dst[n][k] = *(const PG8_LAS bf16x8*)(lds + PG8_SB(b, h) + boff + n * 2048 + k * 1024); } while (0)
; #define PG8_MMA(ai, bj, At, Bt) do { __builtin_amdgcn_s_setprio(1); _Pragma("unroll") for (int m = 0; m < 4; ++m) _Pragma("unroll") for (int n = 0; n < 2; ++n) _Pragma("unroll") for (int k = 0; k < 2; ++k) \
;         acc[ai][bj][m][n] = __builtin_amdgcn_mfma_f32_16x16x32_bf16(Bt[n][k], At[m][k], acc[ai][bj][m][n], 0, 0, 0); __builtin_amdgcn_s_setprio(0); } while (0)
; #define PG8_WAIT_V(n) asm volatile("s_waitcnt vmcnt(" #n ")" ::: "memory")
; #define PG8_WAIT_L(n) asm volatile("s_waitcnt lgkmcnt(" #n ")" ::: "memory")
; #define PG8_BAR __builtin_amdgcn_s_barrier()
; template <class Epi, class Sched, bool ALIGN_EPI = false, bool SP2 = false>
; __device__ __forceinline__ void gemm_phase(PG8_LAS unsigned char* lds, const Gemm g, const Sched& S, const Epi& E, int wave0) {
;     ...
;             const bool last = (t == nt - 2);
;             const char* a1 = cA + (size_t)(t + 1) * kstep;
;             const char* a2 = last ? nA : cA + (size_t)(t + 2) * kstep; const char* b2 = last ? nB : cB + (size_t)(t + 2) * kstep;
;             const char* a3 = a2 + kstep; const char* b3 = b2 + kstep;
;             if constexpr (SP2) {
;             PG8_LDB(B0, 0, 0); PG8_LDB(B1, 0, 1); PG8_SCHED; PG8_LDA(At, 0, 0); PG8_STAGE(PG8_SA(1, 1), a1 + hstep, voffA);
;             PG8_WAIT_V(8); PG8_WAIT_L(0); PG8_BAR; PG8_MMA(0, 0, At, B0); PG8_MMA(0, 1, At, B1); PG8_BAR; PG8_SCHED;
;             PG8_LDA(At, 0, 1); PG8_STAGE(PG8_SB(0, 0), b2, voffB); PG8_STAGE(PG8_SB(0, 1), b2 + hstep, voffB); PG8_STAGE(PG8_SA(0, 0), a2, voffA);
;             PG8_WAIT_V(8); PG8_WAIT_L(0); PG8_BAR; PG8_MMA(1, 0, At, B0); PG8_MMA(1, 1, At, B1); PG8_BAR; PG8_SCHED;
.LBB0_812:
	s_add_u32 s4, s0, 0xfffe0080
	s_addc_u32 s5, s1, -1
	s_add_i32 s36, 0, 0x10000
	s_cmp_eq_u32 s66, 4
	s_cselect_b32 s47, s25, s5
	s_cselect_b32 s46, s63, s4
	v_add_u32_e32 v0, s36, v238
	s_cselect_b32 s5, s23, s65
	s_cselect_b32 s4, s31, s64
	s_add_i32 s67, 0, 0x14000
	ds_read_b128 v[36:39], v0
	ds_read_b128 v[48:51], v0 offset:1024
	ds_read_b128 v[68:71], v0 offset:2048
	ds_read_b128 v[80:83], v0 offset:3072
	v_add_u32_e32 v0, s67, v238
	ds_read_b128 v[100:103], v0
	ds_read_b128 v[104:107], v0 offset:1024
	ds_read_b128 v[124:127], v0 offset:2048
	ds_read_b128 v[128:131], v0 offset:3072
	v_lshl_add_u64 v[2:3], s[0:1], 0, v[204:205]
	s_add_i32 m0, s49, 0xc000
	ds_read_b128 v[156:159], v239
	ds_read_b128 v[160:163], v239 offset:1024
	ds_read_b128 v[172:175], v239 offset:2048
	ds_read_b128 v[176:179], v239 offset:3072
	ds_read_b128 v[180:183], v239 offset:4096
	ds_read_b128 v[184:187], v239 offset:5120
	ds_read_b128 v[188:191], v239 offset:6144
	ds_read_b128 v[192:195], v239 offset:7168
	global_load_lds_dwordx4 v[2:3], off
	v_lshl_add_u64 v[2:3], s[0:1], 0, v[206:207]
	s_add_i32 m0, s49, 0xe000
	s_nop 0
	global_load_lds_dwordx4 v[2:3], off
	s_waitcnt vmcnt(8)
	s_waitcnt lgkmcnt(0)
	s_barrier
	s_setprio 1
	s_waitcnt lgkmcnt(0)
	v_mfma_f32_16x16x32_bf16 v[56:59], v[36:39], v[156:159], v[56:59]
	v_mfma_f32_16x16x32_bf16 v[52:55], v[68:71], v[156:159], v[52:55]
	v_mfma_f32_16x16x32_bf16 v[88:91], v[36:39], v[172:175], v[88:91]
	v_mfma_f32_16x16x32_bf16 v[84:87], v[68:71], v[172:175], v[84:87]
	v_mfma_f32_16x16x32_bf16 v[112:115], v[36:39], v[180:183], v[112:115]
	v_mfma_f32_16x16x32_bf16 v[108:111], v[68:71], v[180:183], v[108:111]
	v_mfma_f32_16x16x32_bf16 v[136:139], v[36:39], v[188:191], v[136:139]
	v_mfma_f32_16x16x32_bf16 v[132:135], v[68:71], v[188:191], v[132:135]
	v_mfma_f32_16x16x32_bf16 v[56:59], v[48:51], v[160:163], v[56:59]
	v_mfma_f32_16x16x32_bf16 v[52:55], v[80:83], v[160:163], v[52:55]
	v_mfma_f32_16x16x32_bf16 v[88:91], v[48:51], v[176:179], v[88:91]
	v_mfma_f32_16x16x32_bf16 v[84:87], v[80:83], v[176:179], v[84:87]
	v_mfma_f32_16x16x32_bf16 v[112:115], v[48:51], v[184:187], v[112:115]
	v_mfma_f32_16x16x32_bf16 v[108:111], v[80:83], v[184:187], v[108:111]
	v_mfma_f32_16x16x32_bf16 v[136:139], v[48:51], v[192:195], v[136:139]
	v_mfma_f32_16x16x32_bf16 v[132:135], v[80:83], v[192:195], v[132:135]
	v_mfma_f32_16x16x32_bf16 v[168:171], v[100:103], v[156:159], v[168:171]
	v_mfma_f32_16x16x32_bf16 v[152:155], v[100:103], v[172:175], v[152:155]
	v_mfma_f32_16x16x32_bf16 v[148:151], v[124:127], v[172:175], v[148:151]
	v_mfma_f32_16x16x32_bf16 v[144:147], v[100:103], v[180:183], v[144:147]
	v_mfma_f32_16x16x32_bf16 v[140:143], v[124:127], v[180:183], v[140:143]
	v_mfma_f32_16x16x32_bf16 v[120:123], v[100:103], v[188:191], v[120:123]
	v_mfma_f32_16x16x32_bf16 v[116:119], v[124:127], v[188:191], v[116:119]
	v_mfma_f32_16x16x32_bf16 v[168:171], v[104:107], v[160:163], v[168:171]
	v_mfma_f32_16x16x32_bf16 v[156:159], v[124:127], v[156:159], v[164:167]
	v_mfma_f32_16x16x32_bf16 v[152:155], v[104:107], v[176:179], v[152:155]
	v_mfma_f32_16x16x32_bf16 v[148:151], v[128:131], v[176:179], v[148:151]
	v_mfma_f32_16x16x32_bf16 v[144:147], v[104:107], v[184:187], v[144:147]
	v_mfma_f32_16x16x32_bf16 v[140:143], v[128:131], v[184:187], v[140:143]
	v_mfma_f32_16x16x32_bf16 v[120:123], v[104:107], v[192:195], v[120:123]
	v_mfma_f32_16x16x32_bf16 v[116:119], v[128:131], v[192:195], v[116:119]
	v_mfma_f32_16x16x32_bf16 v[156:159], v[128:131], v[160:163], v[156:159]
	s_setprio 0
	s_barrier
	s_add_i32 s36, s36, s48
	v_lshl_add_u64 v[208:209], s[4:5], 0, v[200:201]
	s_mov_b32 m0, s36
	ds_read_b128 v[160:163], v239 offset:16384
	ds_read_b128 v[164:167], v239 offset:17408
	ds_read_b128 v[172:175], v239 offset:18432
	ds_read_b128 v[176:179], v239 offset:19456
	ds_read_b128 v[180:183], v239 offset:20480
	ds_read_b128 v[184:187], v239 offset:21504
	ds_read_b128 v[188:191], v239 offset:22528
	ds_read_b128 v[192:195], v239 offset:23552
	global_load_lds_dwordx4 v[208:209], off
	s_add_i32 m0, s36, 0x2000
	s_add_u32 s68, s4, 0x20000
	v_lshl_add_u64 v[210:211], s[4:5], 0, v[196:197]
	s_addc_u32 s69, s5, 0
	s_add_i32 s36, s67, s48
	global_load_lds_dwordx4 v[210:211], off
	v_lshl_add_u64 v[2:3], s[68:69], 0, v[200:201]
	s_mov_b32 m0, s36
	v_lshl_add_u64 v[212:213], s[46:47], 0, v[202:203]
	global_load_lds_dwordx4 v[2:3], off
	v_lshl_add_u64 v[2:3], s[68:69], 0, v[196:197]
	s_add_i32 m0, s36, 0x2000
	v_lshl_add_u64 v[214:215], s[46:47], 0, v[198:199]
	global_load_lds_dwordx4 v[2:3], off
	s_mov_b32 m0, s49
	s_nop 0
	global_load_lds_dwordx4 v[212:213], off
	s_mov_b32 m0, s50
	s_nop 0
	global_load_lds_dwordx4 v[214:215], off
	s_waitcnt vmcnt(8)
	s_waitcnt lgkmcnt(0)
	s_barrier
; #define PG8_STAGE(bufoff, gbase, voff) do { _Pragma("unroll") for (int _i = 0; _i < 2; ++_i) \
;         __builtin_amdgcn_global_load_lds((const unsigned*)((const char*)(gbase) + (voff)[_i]), (PG8_LAS unsigned*)(lds + (bufoff) + ldsw + _i * 8192), 16, 0, 0); } while (0)
; #define PG8_LDA(dst, b, h) do { _Pragma("unroll") for (int m = 0; m < 4; ++m) _Pragma("unroll") for (int k = 0; k < 2; ++k) dst[m][k] = *(const PG8_LAS bf16x8*)(lds + PG8_SA(b, h) + aoff + m * 2048 + k * 1024); } while (0)
; #define PG8_LDB(dst, b, h) do { _Pragma("unroll") for (int n = 0; n < 2; ++n) _Pragma("unroll") for (int k = 0; k < 2; ++k) dst[n][k] = *(const PG8_LAS bf16x8*)(lds + PG8_SB(b, h) + boff + n * 2048 + k * 1024); } while (0)
; #define PG8_MMA(ai, bj, At, Bt) do { __builtin_amdgcn_s_setprio(1); _Pragma("unroll") for (int m = 0; m < 4; ++m) _Pragma("unroll") for (int n = 0; n < 2; ++n) _Pragma("unroll") for (int k = 0; k < 2; ++k) \
;         acc[ai][bj][m][n] = __builtin_amdgcn_mfma_f32_16x16x32_bf16(Bt[n][k], At[m][k], acc[ai][bj][m][n], 0, 0, 0); __builtin_amdgcn_s_setprio(0); } while (0)
; #define PG8_WAIT_V(n) asm volatile("s_waitcnt vmcnt(" #n ")" ::: "memory")
; #define PG8_WAIT_L(n) asm volatile("s_waitcnt lgkmcnt(" #n ")" ::: "memory")
; #define PG8_BAR __builtin_amdgcn_s_barrier()
; #define PG8_SCHED __builtin_amdgcn_sched_barrier(0)
; template <class Epi, class Sched, bool ALIGN_EPI = false, bool SP2 = false>
; __device__ __forceinline__ void gemm_phase(PG8_LAS unsigned char* lds, const Gemm g, const Sched& S, const Epi& E, int wave0) {
;     ...
;             PG8_WAIT_V(8); PG8_WAIT_L(0); PG8_BAR; PG8_MMA(1, 0, At, B0); PG8_MMA(1, 1, At, B1); PG8_BAR; PG8_SCHED;
;             PG8_LDB(B0, 1, 0); PG8_LDB(B1, 1, 1); PG8_SCHED; PG8_LDA(At, 1, 0); PG8_STAGE(PG8_SA(0, 1), a2 + hstep, voffA);
;             PG8_WAIT_V(8); PG8_WAIT_L(0); PG8_BAR; PG8_MMA(0, 0, At, B0); PG8_MMA(0, 1, At, B1); PG8_BAR; PG8_SCHED;
	s_setprio 1
	s_waitcnt lgkmcnt(0)
	v_mfma_f32_16x16x32_bf16 v[96:99], v[36:39], v[160:163], v[96:99]
	v_mfma_f32_16x16x32_bf16 v[92:95], v[68:71], v[160:163], v[92:95]
	v_mfma_f32_16x16x32_bf16 v[64:67], v[36:39], v[172:175], v[64:67]
	v_mfma_f32_16x16x32_bf16 v[60:63], v[68:71], v[172:175], v[60:63]
	v_mfma_f32_16x16x32_bf16 v[32:35], v[36:39], v[180:183], v[32:35]
	v_mfma_f32_16x16x32_bf16 v[28:31], v[68:71], v[180:183], v[28:31]
	v_mfma_f32_16x16x32_bf16 v[16:19], v[36:39], v[188:191], v[16:19]
	v_mfma_f32_16x16x32_bf16 v[12:15], v[68:71], v[188:191], v[12:15]
	v_mfma_f32_16x16x32_bf16 v[96:99], v[48:51], v[164:167], v[96:99]
	v_mfma_f32_16x16x32_bf16 v[92:95], v[80:83], v[164:167], v[92:95]
	v_mfma_f32_16x16x32_bf16 v[64:67], v[48:51], v[176:179], v[64:67]
	v_mfma_f32_16x16x32_bf16 v[60:63], v[80:83], v[176:179], v[60:63]
	v_mfma_f32_16x16x32_bf16 v[32:35], v[48:51], v[184:187], v[32:35]
	v_mfma_f32_16x16x32_bf16 v[28:31], v[80:83], v[184:187], v[28:31]
	v_mfma_f32_16x16x32_bf16 v[16:19], v[48:51], v[192:195], v[16:19]
	v_mfma_f32_16x16x32_bf16 v[12:15], v[80:83], v[192:195], v[12:15]
	v_mfma_f32_16x16x32_bf16 v[44:47], v[100:103], v[172:175], v[44:47]
	v_mfma_f32_16x16x32_bf16 v[40:43], v[124:127], v[172:175], v[40:43]
	v_mfma_f32_16x16x32_bf16 v[24:27], v[100:103], v[180:183], v[24:27]
	v_mfma_f32_16x16x32_bf16 v[20:23], v[124:127], v[180:183], v[20:23]
	v_mfma_f32_16x16x32_bf16 v[8:11], v[100:103], v[188:191], v[8:11]
	v_mfma_f32_16x16x32_bf16 v[2:5], v[124:127], v[188:191], v[4:7]
	v_mfma_f32_16x16x32_bf16 v[36:39], v[100:103], v[160:163], v[76:79]
	v_mfma_f32_16x16x32_bf16 v[48:51], v[124:127], v[160:163], v[72:75]
	v_mfma_f32_16x16x32_bf16 v[44:47], v[104:107], v[176:179], v[44:47]
	v_mfma_f32_16x16x32_bf16 v[40:43], v[128:131], v[176:179], v[40:43]
	v_mfma_f32_16x16x32_bf16 v[24:27], v[104:107], v[184:187], v[24:27]
	v_mfma_f32_16x16x32_bf16 v[20:23], v[128:131], v[184:187], v[20:23]
	v_mfma_f32_16x16x32_bf16 v[8:11], v[104:107], v[192:195], v[8:11]
	v_mfma_f32_16x16x32_bf16 v[2:5], v[128:131], v[192:195], v[2:5]
	v_mfma_f32_16x16x32_bf16 v[36:39], v[104:107], v[164:167], v[36:39]
	v_mfma_f32_16x16x32_bf16 v[48:51], v[128:131], v[164:167], v[48:51]
	s_setprio 0
	s_barrier
	s_add_i32 s36, 0, 0x18000
	v_add_u32_e32 v0, s36, v238
	s_add_i32 s67, 0, 0x1c000
	ds_read_b128 v[68:71], v0
	ds_read_b128 v[72:75], v0 offset:1024
	ds_read_b128 v[76:79], v0 offset:2048
	ds_read_b128 v[80:83], v0 offset:3072
	v_add_u32_e32 v0, s67, v238
	ds_read_b128 v[100:103], v0
	ds_read_b128 v[104:107], v0 offset:1024
	ds_read_b128 v[124:127], v0 offset:2048
	ds_read_b128 v[128:131], v0 offset:3072
	s_add_u32 s46, s46, 0x20000
	s_addc_u32 s47, s47, 0
	s_mov_b32 m0, s51
	v_lshl_add_u64 v[6:7], s[46:47], 0, v[202:203]
	ds_read_b128 v[160:163], v239 offset:32768
	ds_read_b128 v[164:167], v239 offset:33792
	ds_read_b128 v[172:175], v239 offset:34816
	ds_read_b128 v[176:179], v239 offset:35840
	ds_read_b128 v[180:183], v239 offset:36864
	ds_read_b128 v[184:187], v239 offset:37888
	ds_read_b128 v[188:191], v239 offset:38912
	ds_read_b128 v[192:195], v239 offset:39936
	global_load_lds_dwordx4 v[6:7], off
	v_lshl_add_u64 v[6:7], s[46:47], 0, v[198:199]
	s_mov_b32 m0, s52
	s_nop 0
	global_load_lds_dwordx4 v[6:7], off
	s_waitcnt vmcnt(8)
	s_waitcnt lgkmcnt(0)
	s_barrier
	s_setprio 1
	s_waitcnt lgkmcnt(0)
	v_mfma_f32_16x16x32_bf16 v[56:59], v[68:71], v[160:163], v[56:59]
	v_mfma_f32_16x16x32_bf16 v[52:55], v[76:79], v[160:163], v[52:55]
	v_mfma_f32_16x16x32_bf16 v[88:91], v[68:71], v[172:175], v[88:91]
	v_mfma_f32_16x16x32_bf16 v[84:87], v[76:79], v[172:175], v[84:87]
	v_mfma_f32_16x16x32_bf16 v[112:115], v[68:71], v[180:183], v[112:115]
	v_mfma_f32_16x16x32_bf16 v[108:111], v[76:79], v[180:183], v[108:111]
	v_mfma_f32_16x16x32_bf16 v[136:139], v[68:71], v[188:191], v[136:139]
	v_mfma_f32_16x16x32_bf16 v[132:135], v[76:79], v[188:191], v[132:135]
	v_mfma_f32_16x16x32_bf16 v[56:59], v[72:75], v[164:167], v[56:59]
	v_mfma_f32_16x16x32_bf16 v[52:55], v[80:83], v[164:167], v[52:55]
	v_mfma_f32_16x16x32_bf16 v[88:91], v[72:75], v[176:179], v[88:91]
	v_mfma_f32_16x16x32_bf16 v[84:87], v[80:83], v[176:179], v[84:87]
	v_mfma_f32_16x16x32_bf16 v[112:115], v[72:75], v[184:187], v[112:115]
	v_mfma_f32_16x16x32_bf16 v[108:111], v[80:83], v[184:187], v[108:111]
	v_mfma_f32_16x16x32_bf16 v[136:139], v[72:75], v[192:195], v[136:139]
	v_mfma_f32_16x16x32_bf16 v[132:135], v[80:83], v[192:195], v[132:135]
	v_mfma_f32_16x16x32_bf16 v[168:171], v[100:103], v[160:163], v[168:171]
	v_mfma_f32_16x16x32_bf16 v[156:159], v[124:127], v[160:163], v[156:159]
	v_mfma_f32_16x16x32_bf16 v[152:155], v[100:103], v[172:175], v[152:155]
	v_mfma_f32_16x16x32_bf16 v[148:151], v[124:127], v[172:175], v[148:151]
	v_mfma_f32_16x16x32_bf16 v[144:147], v[100:103], v[180:183], v[144:147]
	v_mfma_f32_16x16x32_bf16 v[140:143], v[124:127], v[180:183], v[140:143]
	v_mfma_f32_16x16x32_bf16 v[120:123], v[100:103], v[188:191], v[120:123]
	v_mfma_f32_16x16x32_bf16 v[116:119], v[124:127], v[188:191], v[116:119]
	v_mfma_f32_16x16x32_bf16 v[168:171], v[104:107], v[164:167], v[168:171]
	v_mfma_f32_16x16x32_bf16 v[164:167], v[128:131], v[164:167], v[156:159]
	v_mfma_f32_16x16x32_bf16 v[152:155], v[104:107], v[176:179], v[152:155]
	v_mfma_f32_16x16x32_bf16 v[148:151], v[128:131], v[176:179], v[148:151]
	v_mfma_f32_16x16x32_bf16 v[144:147], v[104:107], v[184:187], v[144:147]
	v_mfma_f32_16x16x32_bf16 v[140:143], v[128:131], v[184:187], v[140:143]
	v_mfma_f32_16x16x32_bf16 v[120:123], v[104:107], v[192:195], v[120:123]
	v_mfma_f32_16x16x32_bf16 v[116:119], v[128:131], v[192:195], v[116:119]
	s_setprio 0
	s_barrier
; #define PG8_STAGE(bufoff, gbase, voff) do { _Pragma("unroll") for (int _i = 0; _i < 2; ++_i) \
;         __builtin_amdgcn_global_load_lds((const unsigned*)((const char*)(gbase) + (voff)[_i]), (PG8_LAS unsigned*)(lds + (bufoff) + ldsw + _i * 8192), 16, 0, 0); } while (0)
; #define PG8_LDA(dst, b, h) do { _Pragma("unroll") for (int m = 0; m < 4; ++m) _Pragma("unroll") for (int k = 0; k < 2; ++k) dst[m][k] = *(const PG8_LAS bf16x8*)(lds + PG8_SA(b, h) + aoff + m * 2048 + k * 1024); } while (0)
; #define PG8_MMA(ai, bj, At, Bt) do { __builtin_amdgcn_s_setprio(1); _Pragma("unroll") for (int m = 0; m < 4; ++m) _Pragma("unroll") for (int n = 0; n < 2; ++n) _Pragma("unroll") for (int k = 0; k < 2; ++k) \
;         acc[ai][bj][m][n] = __builtin_amdgcn_mfma_f32_16x16x32_bf16(Bt[n][k], At[m][k], acc[ai][bj][m][n], 0, 0, 0); __builtin_amdgcn_s_setprio(0); } while (0)
; #define PG8_WAIT_V(n) asm volatile("s_waitcnt vmcnt(" #n ")" ::: "memory")
; #define PG8_WAIT_L(n) asm volatile("s_waitcnt lgkmcnt(" #n ")" ::: "memory")
; #define PG8_BAR __builtin_amdgcn_s_barrier()
; #define PG8_SCHED __builtin_amdgcn_sched_barrier(0)
; template <class Epi, class Sched, bool ALIGN_EPI = false, bool SP2 = false>
; __device__ __forceinline__ void gemm_phase(PG8_LAS unsigned char* lds, const Gemm g, const Sched& S, const Epi& E, int wave0) {
;     ...
;         for (int t = 0; t < nt; t += 2) {
;             const bool last = (t == nt - 2);
;             const char* a1 = cA + (size_t)(t + 1) * kstep;
;             const char* a2 = last ? nA : cA + (size_t)(t + 2) * kstep; const char* b2 = last ? nB : cB + (size_t)(t + 2) * kstep;
;             const char* a3 = a2 + kstep; const char* b3 = b2 + kstep;
;     ...
;             PG8_LDA(At, 1, 1); PG8_STAGE(PG8_SB(1, 0), b3, voffB); PG8_STAGE(PG8_SB(1, 1), b3 + hstep, voffB); PG8_STAGE(PG8_SA(1, 0), a3, voffA);
;             PG8_WAIT_V(8); PG8_WAIT_L(0); PG8_BAR; PG8_MMA(1, 0, At, B0); PG8_MMA(1, 1, At, B1); PG8_BAR; PG8_SCHED;
	s_add_i32 s36, s36, s48
	v_lshl_add_u64 v[6:7], v[208:209], 0, s[34:35]
	s_mov_b32 m0, s36
	ds_read_b128 v[156:159], v239 offset:49152
	ds_read_b128 v[160:163], v239 offset:50176
	ds_read_b128 v[172:175], v239 offset:51200
	ds_read_b128 v[176:179], v239 offset:52224
	ds_read_b128 v[180:183], v239 offset:53248
	ds_read_b128 v[184:187], v239 offset:54272
	ds_read_b128 v[188:191], v239 offset:55296
	ds_read_b128 v[192:195], v239 offset:56320
	global_load_lds_dwordx4 v[6:7], off
	s_add_i32 m0, s36, 0x2000
	s_add_u32 s4, s4, 0x20080
	v_lshl_add_u64 v[6:7], v[210:211], 0, s[34:35]
	s_addc_u32 s5, s5, 0
	s_add_i32 s36, s67, s48
	global_load_lds_dwordx4 v[6:7], off
	v_lshl_add_u64 v[6:7], s[4:5], 0, v[200:201]
	s_mov_b32 m0, s36
	s_nop 0
	global_load_lds_dwordx4 v[6:7], off
	v_lshl_add_u64 v[6:7], s[4:5], 0, v[196:197]
	s_add_i32 m0, s36, 0x2000
	s_nop 0
	global_load_lds_dwordx4 v[6:7], off
	v_lshl_add_u64 v[6:7], v[212:213], 0, s[34:35]
	s_mov_b32 m0, s57
	s_nop 0
	global_load_lds_dwordx4 v[6:7], off
	v_lshl_add_u64 v[6:7], v[214:215], 0, s[34:35]
	s_mov_b32 m0, s58
	s_nop 0
	global_load_lds_dwordx4 v[6:7], off
	s_waitcnt vmcnt(8)
	s_waitcnt lgkmcnt(0)
	s_barrier
	s_setprio 1
	s_waitcnt lgkmcnt(0)
	v_mfma_f32_16x16x32_bf16 v[96:99], v[68:71], v[156:159], v[96:99]
	v_mfma_f32_16x16x32_bf16 v[92:95], v[76:79], v[156:159], v[92:95]
	v_mfma_f32_16x16x32_bf16 v[64:67], v[68:71], v[172:175], v[64:67]
	v_mfma_f32_16x16x32_bf16 v[60:63], v[76:79], v[172:175], v[60:63]
	v_mfma_f32_16x16x32_bf16 v[32:35], v[68:71], v[180:183], v[32:35]
	v_mfma_f32_16x16x32_bf16 v[28:31], v[76:79], v[180:183], v[28:31]
	v_mfma_f32_16x16x32_bf16 v[16:19], v[68:71], v[188:191], v[16:19]
	v_mfma_f32_16x16x32_bf16 v[12:15], v[76:79], v[188:191], v[12:15]
	v_mfma_f32_16x16x32_bf16 v[96:99], v[72:75], v[160:163], v[96:99]
	v_mfma_f32_16x16x32_bf16 v[92:95], v[80:83], v[160:163], v[92:95]
	v_mfma_f32_16x16x32_bf16 v[64:67], v[72:75], v[176:179], v[64:67]
	v_mfma_f32_16x16x32_bf16 v[60:63], v[80:83], v[176:179], v[60:63]
	v_mfma_f32_16x16x32_bf16 v[32:35], v[72:75], v[184:187], v[32:35]
	v_mfma_f32_16x16x32_bf16 v[28:31], v[80:83], v[184:187], v[28:31]
	v_mfma_f32_16x16x32_bf16 v[16:19], v[72:75], v[192:195], v[16:19]
	v_mfma_f32_16x16x32_bf16 v[12:15], v[80:83], v[192:195], v[12:15]
	v_mfma_f32_16x16x32_bf16 v[36:39], v[100:103], v[156:159], v[36:39]
	v_mfma_f32_16x16x32_bf16 v[76:79], v[104:107], v[160:163], v[36:39]
	v_mfma_f32_16x16x32_bf16 v[36:39], v[124:127], v[156:159], v[48:51]
	v_mfma_f32_16x16x32_bf16 v[72:75], v[128:131], v[160:163], v[36:39]
	v_mfma_f32_16x16x32_bf16 v[36:39], v[100:103], v[172:175], v[44:47]
	v_mfma_f32_16x16x32_bf16 v[44:47], v[104:107], v[176:179], v[36:39]
	v_mfma_f32_16x16x32_bf16 v[36:39], v[124:127], v[172:175], v[40:43]
	v_mfma_f32_16x16x32_bf16 v[24:27], v[100:103], v[180:183], v[24:27]
	v_mfma_f32_16x16x32_bf16 v[20:23], v[124:127], v[180:183], v[20:23]
	v_mfma_f32_16x16x32_bf16 v[6:9], v[100:103], v[188:191], v[8:11]
	v_mfma_f32_16x16x32_bf16 v[2:5], v[124:127], v[188:191], v[2:5]
	v_mfma_f32_16x16x32_bf16 v[40:43], v[128:131], v[176:179], v[36:39]
	v_mfma_f32_16x16x32_bf16 v[24:27], v[104:107], v[184:187], v[24:27]
	v_mfma_f32_16x16x32_bf16 v[20:23], v[128:131], v[184:187], v[20:23]
	v_mfma_f32_16x16x32_bf16 v[8:11], v[104:107], v[192:195], v[6:9]
	v_mfma_f32_16x16x32_bf16 v[4:7], v[128:131], v[192:195], v[2:5]
	s_setprio 0
	s_barrier
	s_add_i32 s66, s66, 2
	s_add_u32 s0, s0, 0x100
	s_addc_u32 s1, s1, 0
	s_add_u32 s64, s64, 0x100
	s_addc_u32 s65, s65, 0
	s_cmp_gt_u32 s66, 5
	s_cbranch_scc0 .LBB0_812
	s_and_b64 vcc, exec, s[20:21]
	s_cbranch_vccz .LBB0_815
	s_barrier

; #define PG8_STAGE(bufoff, gbase, voff) do { _Pragma("unroll") for (int _i = 0; _i < 2; ++_i) \
;         __builtin_amdgcn_global_load_lds((const unsigned*)((const char*)(gbase) + (voff)[_i]), (PG8_LAS unsigned*)(lds + (bufoff) + ldsw + _i * 8192), 16, 0, 0); } while (0)
; #define PG8_LDA(dst, b, h) do { _Pragma("unroll") for (int m = 0; m < 4; ++m) _Pragma("unroll") for (int k = 0; k < 2; ++k) dst[m][k] = *(const PG8_LAS bf16x8*)(lds + PG8_SA(b, h) + aoff + m * 2048 + k * 1024); } while (0)
; #define PG8_LDB(dst, b, h) do { _Pragma("unroll") for (int n = 0; n < 2; ++n) _Pragma("unroll") for (int k = 0; k < 2; ++k) dst[n][k] = *(const PG8_LAS bf16x8*)(lds + PG8_SB(b, h) + boff + n * 2048 + k * 1024); } while (0)
; #define PG8_MMA(ai, bj, At, Bt) do { __builtin_amdgcn_s_setprio(1); _Pragma("unroll") for (int m = 0; m < 4; ++m) _Pragma("unroll") for (int n = 0; n < 2; ++n) _Pragma("unroll") for (int k = 0; k < 2; ++k) \
;         acc[ai][bj][m][n] = __builtin_amdgcn_mfma_f32_16x16x32_bf16(Bt[n][k], At[m][k], acc[ai][bj][m][n], 0, 0, 0); __builtin_amdgcn_s_setprio(0); } while (0)
; #define PG8_WAIT_V(n) asm volatile("s_waitcnt vmcnt(" #n ")" ::: "memory")
; #define PG8_WAIT_L(n) asm volatile("s_waitcnt lgkmcnt(" #n ")" ::: "memory")
; #define PG8_BAR __builtin_amdgcn_s_barrier()
; template <class Epi, class Sched, bool ALIGN_EPI = false, bool SP2 = false>
; __device__ __forceinline__ void gemm_phase(PG8_LAS unsigned char* lds, const Gemm g, const Sched& S, const Epi& E, int wave0) {
;     ...
;             const bool last = (t == nt - 2);
;             const char* a1 = cA + (size_t)(t + 1) * kstep;
;             const char* a2 = last ? nA : cA + (size_t)(t + 2) * kstep; const char* b2 = last ? nB : cB + (size_t)(t + 2) * kstep;
;             const char* a3 = a2 + kstep; const char* b3 = b2 + kstep;
;             if constexpr (SP2) {
;             PG8_LDB(B0, 0, 0); PG8_LDB(B1, 0, 1); PG8_SCHED; PG8_LDA(At, 0, 0); PG8_STAGE(PG8_SA(1, 1), a1 + hstep, voffA);
;             PG8_WAIT_V(8); PG8_WAIT_L(0); PG8_BAR; PG8_MMA(0, 0, At, B0); PG8_MMA(0, 1, At, B1); PG8_BAR; PG8_SCHED;
;             PG8_LDA(At, 0, 1); PG8_STAGE(PG8_SB(0, 0), b2, voffB); PG8_STAGE(PG8_SB(0, 1), b2 + hstep, voffB); PG8_STAGE(PG8_SA(0, 0), a2, voffA);
;             PG8_WAIT_V(8); PG8_WAIT_L(0); PG8_BAR; PG8_MMA(1, 0, At, B0); PG8_MMA(1, 1, At, B1); PG8_BAR; PG8_SCHED;
.LBB0_997:
	s_add_u32 s28, s46, 0xfffc0080
	s_addc_u32 s29, s47, -1
	s_add_i32 s36, 0, 0x10000
	s_cmp_eq_u32 s67, 12
	s_cselect_b32 s49, s31, s29
	s_cselect_b32 s48, s63, s28
	s_cselect_b32 s29, s25, s66
	s_cselect_b32 s28, s64, s65
	s_add_i32 s70, 0, 0x14000
	v_add_u32_e32 v156, s36, v145
	v_add_u32_e32 v172, s70, v145
	ds_read_b128 v[140:143], v156
	ds_read_b128 v[148:151], v156 offset:1024
	ds_read_b128 v[152:155], v156 offset:2048
	ds_read_b128 v[156:159], v156 offset:3072
	ds_read_b128 v[160:163], v172
	ds_read_b128 v[164:167], v172 offset:1024
	ds_read_b128 v[168:171], v172 offset:2048
	ds_read_b128 v[172:175], v172 offset:3072
	v_lshl_add_u64 v[208:209], s[46:47], 0, v[136:137]
	s_add_i32 m0, s55, 0xc000
	ds_read_b128 v[176:179], v147
	ds_read_b128 v[180:183], v147 offset:1024
	ds_read_b128 v[184:187], v147 offset:2048
	ds_read_b128 v[188:191], v147 offset:3072
	ds_read_b128 v[192:195], v147 offset:4096
	ds_read_b128 v[196:199], v147 offset:5120
	ds_read_b128 v[200:203], v147 offset:6144
	ds_read_b128 v[204:207], v147 offset:7168
	global_load_lds_dwordx4 v[208:209], off
	v_lshl_add_u64 v[208:209], s[46:47], 0, v[138:139]
	s_add_i32 m0, s55, 0xe000
	s_nop 0
	global_load_lds_dwordx4 v[208:209], off
	s_waitcnt vmcnt(8)
	s_waitcnt lgkmcnt(0)
	s_barrier
	s_setprio 1
	s_waitcnt lgkmcnt(0)
	v_mfma_f32_16x16x32_bf16 v[126:129], v[140:143], v[176:179], v[126:129]
	v_mfma_f32_16x16x32_bf16 v[122:125], v[152:155], v[176:179], v[122:125]
	v_mfma_f32_16x16x32_bf16 v[110:113], v[140:143], v[184:187], v[110:113]
	v_mfma_f32_16x16x32_bf16 v[106:109], v[152:155], v[184:187], v[106:109]
	v_mfma_f32_16x16x32_bf16 v[94:97], v[140:143], v[192:195], v[94:97]
	v_mfma_f32_16x16x32_bf16 v[90:93], v[152:155], v[192:195], v[90:93]
	v_mfma_f32_16x16x32_bf16 v[78:81], v[140:143], v[200:203], v[78:81]
	v_mfma_f32_16x16x32_bf16 v[74:77], v[152:155], v[200:203], v[74:77]
	v_mfma_f32_16x16x32_bf16 v[126:129], v[148:151], v[180:183], v[126:129]
	v_mfma_f32_16x16x32_bf16 v[122:125], v[156:159], v[180:183], v[122:125]
	v_mfma_f32_16x16x32_bf16 v[110:113], v[148:151], v[188:191], v[110:113]
	v_mfma_f32_16x16x32_bf16 v[106:109], v[156:159], v[188:191], v[106:109]
	v_mfma_f32_16x16x32_bf16 v[94:97], v[148:151], v[196:199], v[94:97]
	v_mfma_f32_16x16x32_bf16 v[90:93], v[156:159], v[196:199], v[90:93]
	v_mfma_f32_16x16x32_bf16 v[78:81], v[148:151], v[204:207], v[78:81]
	v_mfma_f32_16x16x32_bf16 v[74:77], v[156:159], v[204:207], v[74:77]
	v_mfma_f32_16x16x32_bf16 v[118:121], v[160:163], v[176:179], v[118:121]
	v_mfma_f32_16x16x32_bf16 v[114:117], v[168:171], v[176:179], v[114:117]
	v_mfma_f32_16x16x32_bf16 v[102:105], v[160:163], v[184:187], v[102:105]
	v_mfma_f32_16x16x32_bf16 v[98:101], v[168:171], v[184:187], v[98:101]
	v_mfma_f32_16x16x32_bf16 v[86:89], v[160:163], v[192:195], v[86:89]
	v_mfma_f32_16x16x32_bf16 v[82:85], v[168:171], v[192:195], v[82:85]
	v_mfma_f32_16x16x32_bf16 v[70:73], v[160:163], v[200:203], v[70:73]
	v_mfma_f32_16x16x32_bf16 v[66:69], v[168:171], v[200:203], v[66:69]
	v_mfma_f32_16x16x32_bf16 v[118:121], v[164:167], v[180:183], v[118:121]
	v_mfma_f32_16x16x32_bf16 v[114:117], v[172:175], v[180:183], v[114:117]
	v_mfma_f32_16x16x32_bf16 v[102:105], v[164:167], v[188:191], v[102:105]
	v_mfma_f32_16x16x32_bf16 v[98:101], v[172:175], v[188:191], v[98:101]
	v_mfma_f32_16x16x32_bf16 v[86:89], v[164:167], v[196:199], v[86:89]
	v_mfma_f32_16x16x32_bf16 v[82:85], v[172:175], v[196:199], v[82:85]
	v_mfma_f32_16x16x32_bf16 v[70:73], v[164:167], v[204:207], v[70:73]
	v_mfma_f32_16x16x32_bf16 v[66:69], v[172:175], v[204:207], v[66:69]
	s_setprio 0
	s_barrier
	s_add_i32 s36, s36, s52
	v_lshl_add_u64 v[208:209], s[28:29], 0, v[0:1]
	s_mov_b32 m0, s36
	ds_read_b128 v[176:179], v147 offset:16384
	ds_read_b128 v[180:183], v147 offset:17408
	ds_read_b128 v[184:187], v147 offset:18432
	ds_read_b128 v[188:191], v147 offset:19456
	ds_read_b128 v[192:195], v147 offset:20480
	ds_read_b128 v[196:199], v147 offset:21504
	ds_read_b128 v[200:203], v147 offset:22528
	ds_read_b128 v[204:207], v147 offset:23552
	global_load_lds_dwordx4 v[208:209], off
	s_add_i32 m0, s36, 0x2000
	s_add_u32 s68, s28, 0x40000
	v_lshl_add_u64 v[210:211], s[28:29], 0, v[130:131]
	s_addc_u32 s69, s29, 0
	s_add_i32 s36, s70, s52
	global_load_lds_dwordx4 v[210:211], off
	v_lshl_add_u64 v[212:213], s[68:69], 0, v[0:1]
	s_mov_b32 m0, s36
	v_lshl_add_u64 v[214:215], s[48:49], 0, v[132:133]
	global_load_lds_dwordx4 v[212:213], off
	v_lshl_add_u64 v[212:213], s[68:69], 0, v[130:131]
	s_add_i32 m0, s36, 0x2000
	s_nop 0
	global_load_lds_dwordx4 v[212:213], off
	v_lshl_add_u64 v[212:213], s[48:49], 0, v[134:135]
	s_mov_b32 m0, s55
	s_nop 0
	global_load_lds_dwordx4 v[212:213], off
	s_mov_b32 m0, s56
	s_nop 0
	global_load_lds_dwordx4 v[214:215], off
	s_waitcnt vmcnt(8)
	s_waitcnt lgkmcnt(0)
	s_barrier
; #define PG8_STAGE(bufoff, gbase, voff) do { _Pragma("unroll") for (int _i = 0; _i < 2; ++_i) \
;         __builtin_amdgcn_global_load_lds((const unsigned*)((const char*)(gbase) + (voff)[_i]), (PG8_LAS unsigned*)(lds + (bufoff) + ldsw + _i * 8192), 16, 0, 0); } while (0)
; #define PG8_LDA(dst, b, h) do { _Pragma("unroll") for (int m = 0; m < 4; ++m) _Pragma("unroll") for (int k = 0; k < 2; ++k) dst[m][k] = *(const PG8_LAS bf16x8*)(lds + PG8_SA(b, h) + aoff + m * 2048 + k * 1024); } while (0)
; #define PG8_LDB(dst, b, h) do { _Pragma("unroll") for (int n = 0; n < 2; ++n) _Pragma("unroll") for (int k = 0; k < 2; ++k) dst[n][k] = *(const PG8_LAS bf16x8*)(lds + PG8_SB(b, h) + boff + n * 2048 + k * 1024); } while (0)
; #define PG8_MMA(ai, bj, At, Bt) do { __builtin_amdgcn_s_setprio(1); _Pragma("unroll") for (int m = 0; m < 4; ++m) _Pragma("unroll") for (int n = 0; n < 2; ++n) _Pragma("unroll") for (int k = 0; k < 2; ++k) \
;         acc[ai][bj][m][n] = __builtin_amdgcn_mfma_f32_16x16x32_bf16(Bt[n][k], At[m][k], acc[ai][bj][m][n], 0, 0, 0); __builtin_amdgcn_s_setprio(0); } while (0)
; #define PG8_WAIT_V(n) asm volatile("s_waitcnt vmcnt(" #n ")" ::: "memory")
; #define PG8_WAIT_L(n) asm volatile("s_waitcnt lgkmcnt(" #n ")" ::: "memory")
; #define PG8_BAR __builtin_amdgcn_s_barrier()
; #define PG8_SCHED __builtin_amdgcn_sched_barrier(0)
; template <class Epi, class Sched, bool ALIGN_EPI = false, bool SP2 = false>
; __device__ __forceinline__ void gemm_phase(PG8_LAS unsigned char* lds, const Gemm g, const Sched& S, const Epi& E, int wave0) {
;     ...
;             PG8_WAIT_V(8); PG8_WAIT_L(0); PG8_BAR; PG8_MMA(1, 0, At, B0); PG8_MMA(1, 1, At, B1); PG8_BAR; PG8_SCHED;
;             PG8_LDB(B0, 1, 0); PG8_LDB(B1, 1, 1); PG8_SCHED; PG8_LDA(At, 1, 0); PG8_STAGE(PG8_SA(0, 1), a2 + hstep, voffA);
;             PG8_WAIT_V(8); PG8_WAIT_L(0); PG8_BAR; PG8_MMA(0, 0, At, B0); PG8_MMA(0, 1, At, B1); PG8_BAR; PG8_SCHED;
	s_setprio 1
	s_waitcnt lgkmcnt(0)
	v_mfma_f32_16x16x32_bf16 v[58:61], v[140:143], v[176:179], v[58:61]
	v_mfma_f32_16x16x32_bf16 v[62:65], v[152:155], v[176:179], v[62:65]
	v_mfma_f32_16x16x32_bf16 v[42:45], v[140:143], v[184:187], v[42:45]
	v_mfma_f32_16x16x32_bf16 v[46:49], v[152:155], v[184:187], v[46:49]
	v_mfma_f32_16x16x32_bf16 v[26:29], v[140:143], v[192:195], v[26:29]
	v_mfma_f32_16x16x32_bf16 v[30:33], v[152:155], v[192:195], v[30:33]
	v_mfma_f32_16x16x32_bf16 v[10:13], v[140:143], v[200:203], v[10:13]
	v_mfma_f32_16x16x32_bf16 v[14:17], v[152:155], v[200:203], v[14:17]
	v_mfma_f32_16x16x32_bf16 v[58:61], v[148:151], v[180:183], v[58:61]
	v_mfma_f32_16x16x32_bf16 v[62:65], v[156:159], v[180:183], v[62:65]
	v_mfma_f32_16x16x32_bf16 v[42:45], v[148:151], v[188:191], v[42:45]
	v_mfma_f32_16x16x32_bf16 v[46:49], v[156:159], v[188:191], v[46:49]
	v_mfma_f32_16x16x32_bf16 v[26:29], v[148:151], v[196:199], v[26:29]
	v_mfma_f32_16x16x32_bf16 v[30:33], v[156:159], v[196:199], v[30:33]
	v_mfma_f32_16x16x32_bf16 v[10:13], v[148:151], v[204:207], v[10:13]
	v_mfma_f32_16x16x32_bf16 v[14:17], v[156:159], v[204:207], v[14:17]
	v_mfma_f32_16x16x32_bf16 v[54:57], v[160:163], v[176:179], v[54:57]
	v_mfma_f32_16x16x32_bf16 v[50:53], v[168:171], v[176:179], v[50:53]
	v_mfma_f32_16x16x32_bf16 v[38:41], v[160:163], v[184:187], v[38:41]
	v_mfma_f32_16x16x32_bf16 v[34:37], v[168:171], v[184:187], v[34:37]
	v_mfma_f32_16x16x32_bf16 v[22:25], v[160:163], v[192:195], v[22:25]
	v_mfma_f32_16x16x32_bf16 v[18:21], v[168:171], v[192:195], v[18:21]
	v_mfma_f32_16x16x32_bf16 v[6:9], v[160:163], v[200:203], v[6:9]
	v_mfma_f32_16x16x32_bf16 v[2:5], v[168:171], v[200:203], v[2:5]
	v_mfma_f32_16x16x32_bf16 v[54:57], v[164:167], v[180:183], v[54:57]
	v_mfma_f32_16x16x32_bf16 v[50:53], v[172:175], v[180:183], v[50:53]
	v_mfma_f32_16x16x32_bf16 v[38:41], v[164:167], v[188:191], v[38:41]
	v_mfma_f32_16x16x32_bf16 v[34:37], v[172:175], v[188:191], v[34:37]
	v_mfma_f32_16x16x32_bf16 v[22:25], v[164:167], v[196:199], v[22:25]
	v_mfma_f32_16x16x32_bf16 v[18:21], v[172:175], v[196:199], v[18:21]
	v_mfma_f32_16x16x32_bf16 v[6:9], v[164:167], v[204:207], v[6:9]
	v_mfma_f32_16x16x32_bf16 v[2:5], v[172:175], v[204:207], v[2:5]
	s_setprio 0
	s_barrier
	s_add_i32 s36, 0, 0x18000
	s_add_i32 s68, 0, 0x1c000
	v_add_u32_e32 v156, s36, v145
	v_add_u32_e32 v172, s68, v145
	ds_read_b128 v[140:143], v156
	ds_read_b128 v[148:151], v156 offset:1024
	ds_read_b128 v[152:155], v156 offset:2048
	ds_read_b128 v[156:159], v156 offset:3072
	ds_read_b128 v[160:163], v172
	ds_read_b128 v[164:167], v172 offset:1024
	ds_read_b128 v[168:171], v172 offset:2048
	ds_read_b128 v[172:175], v172 offset:3072
	s_add_u32 s48, s48, 0x40000
	s_addc_u32 s49, s49, 0
	s_mov_b32 m0, s57
	v_lshl_add_u64 v[216:217], s[48:49], 0, v[134:135]
	ds_read_b128 v[176:179], v147 offset:32768
	ds_read_b128 v[180:183], v147 offset:33792
	ds_read_b128 v[184:187], v147 offset:34816
	ds_read_b128 v[188:191], v147 offset:35840
	ds_read_b128 v[192:195], v147 offset:36864
	ds_read_b128 v[196:199], v147 offset:37888
	ds_read_b128 v[200:203], v147 offset:38912
	ds_read_b128 v[204:207], v147 offset:39936
	global_load_lds_dwordx4 v[216:217], off
	v_lshl_add_u64 v[216:217], s[48:49], 0, v[132:133]
	s_mov_b32 m0, s58
	s_nop 0
	global_load_lds_dwordx4 v[216:217], off
	s_waitcnt vmcnt(8)
	s_waitcnt lgkmcnt(0)
	s_barrier
	s_setprio 1
	s_waitcnt lgkmcnt(0)
	v_mfma_f32_16x16x32_bf16 v[126:129], v[140:143], v[176:179], v[126:129]
	v_mfma_f32_16x16x32_bf16 v[122:125], v[152:155], v[176:179], v[122:125]
	v_mfma_f32_16x16x32_bf16 v[110:113], v[140:143], v[184:187], v[110:113]
	v_mfma_f32_16x16x32_bf16 v[106:109], v[152:155], v[184:187], v[106:109]
	v_mfma_f32_16x16x32_bf16 v[94:97], v[140:143], v[192:195], v[94:97]
	v_mfma_f32_16x16x32_bf16 v[90:93], v[152:155], v[192:195], v[90:93]
	v_mfma_f32_16x16x32_bf16 v[78:81], v[140:143], v[200:203], v[78:81]
	v_mfma_f32_16x16x32_bf16 v[74:77], v[152:155], v[200:203], v[74:77]
	v_mfma_f32_16x16x32_bf16 v[126:129], v[148:151], v[180:183], v[126:129]
	v_mfma_f32_16x16x32_bf16 v[122:125], v[156:159], v[180:183], v[122:125]
	v_mfma_f32_16x16x32_bf16 v[110:113], v[148:151], v[188:191], v[110:113]
	v_mfma_f32_16x16x32_bf16 v[106:109], v[156:159], v[188:191], v[106:109]
	v_mfma_f32_16x16x32_bf16 v[94:97], v[148:151], v[196:199], v[94:97]
	v_mfma_f32_16x16x32_bf16 v[90:93], v[156:159], v[196:199], v[90:93]
	v_mfma_f32_16x16x32_bf16 v[78:81], v[148:151], v[204:207], v[78:81]
	v_mfma_f32_16x16x32_bf16 v[74:77], v[156:159], v[204:207], v[74:77]
	v_mfma_f32_16x16x32_bf16 v[118:121], v[160:163], v[176:179], v[118:121]
	v_mfma_f32_16x16x32_bf16 v[114:117], v[168:171], v[176:179], v[114:117]
	v_mfma_f32_16x16x32_bf16 v[102:105], v[160:163], v[184:187], v[102:105]
	v_mfma_f32_16x16x32_bf16 v[98:101], v[168:171], v[184:187], v[98:101]
	v_mfma_f32_16x16x32_bf16 v[86:89], v[160:163], v[192:195], v[86:89]
	v_mfma_f32_16x16x32_bf16 v[82:85], v[168:171], v[192:195], v[82:85]
	v_mfma_f32_16x16x32_bf16 v[70:73], v[160:163], v[200:203], v[70:73]
	v_mfma_f32_16x16x32_bf16 v[66:69], v[168:171], v[200:203], v[66:69]
	v_mfma_f32_16x16x32_bf16 v[118:121], v[164:167], v[180:183], v[118:121]
	v_mfma_f32_16x16x32_bf16 v[114:117], v[172:175], v[180:183], v[114:117]
	v_mfma_f32_16x16x32_bf16 v[102:105], v[164:167], v[188:191], v[102:105]
	v_mfma_f32_16x16x32_bf16 v[98:101], v[172:175], v[188:191], v[98:101]
	v_mfma_f32_16x16x32_bf16 v[86:89], v[164:167], v[196:199], v[86:89]
	v_mfma_f32_16x16x32_bf16 v[82:85], v[172:175], v[196:199], v[82:85]
	v_mfma_f32_16x16x32_bf16 v[70:73], v[164:167], v[204:207], v[70:73]
	v_mfma_f32_16x16x32_bf16 v[66:69], v[172:175], v[204:207], v[66:69]
	s_setprio 0
	s_barrier
; #define PG8_STAGE(bufoff, gbase, voff) do { _Pragma("unroll") for (int _i = 0; _i < 2; ++_i) \
;         __builtin_amdgcn_global_load_lds((const unsigned*)((const char*)(gbase) + (voff)[_i]), (PG8_LAS unsigned*)(lds + (bufoff) + ldsw + _i * 8192), 16, 0, 0); } while (0)
; #define PG8_LDA(dst, b, h) do { _Pragma("unroll") for (int m = 0; m < 4; ++m) _Pragma("unroll") for (int k = 0; k < 2; ++k) dst[m][k] = *(const PG8_LAS bf16x8*)(lds + PG8_SA(b, h) + aoff + m * 2048 + k * 1024); } while (0)
; #define PG8_MMA(ai, bj, At, Bt) do { __builtin_amdgcn_s_setprio(1); _Pragma("unroll") for (int m = 0; m < 4; ++m) _Pragma("unroll") for (int n = 0; n < 2; ++n) _Pragma("unroll") for (int k = 0; k < 2; ++k) \
;         acc[ai][bj][m][n] = __builtin_amdgcn_mfma_f32_16x16x32_bf16(Bt[n][k], At[m][k], acc[ai][bj][m][n], 0, 0, 0); __builtin_amdgcn_s_setprio(0); } while (0)
; #define PG8_WAIT_V(n) asm volatile("s_waitcnt vmcnt(" #n ")" ::: "memory")
; #define PG8_WAIT_L(n) asm volatile("s_waitcnt lgkmcnt(" #n ")" ::: "memory")
; #define PG8_BAR __builtin_amdgcn_s_barrier()
; #define PG8_SCHED __builtin_amdgcn_sched_barrier(0)
; template <class Epi, class Sched, bool ALIGN_EPI = false, bool SP2 = false>
; __device__ __forceinline__ void gemm_phase(PG8_LAS unsigned char* lds, const Gemm g, const Sched& S, const Epi& E, int wave0) {
;     ...
;         for (int t = 0; t < nt; t += 2) {
;             const bool last = (t == nt - 2);
;             const char* a1 = cA + (size_t)(t + 1) * kstep;
;             const char* a2 = last ? nA : cA + (size_t)(t + 2) * kstep; const char* b2 = last ? nB : cB + (size_t)(t + 2) * kstep;
;             const char* a3 = a2 + kstep; const char* b3 = b2 + kstep;
;     ...
;             PG8_LDA(At, 1, 1); PG8_STAGE(PG8_SB(1, 0), b3, voffB); PG8_STAGE(PG8_SB(1, 1), b3 + hstep, voffB); PG8_STAGE(PG8_SA(1, 0), a3, voffA);
;             PG8_WAIT_V(8); PG8_WAIT_L(0); PG8_BAR; PG8_MMA(1, 0, At, B0); PG8_MMA(1, 1, At, B1); PG8_BAR; PG8_SCHED;
	s_add_i32 s36, s36, s52
	v_lshl_add_u64 v[208:209], v[208:209], 0, s[34:35]
	s_mov_b32 m0, s36
	ds_read_b128 v[176:179], v147 offset:49152
	ds_read_b128 v[180:183], v147 offset:50176
	ds_read_b128 v[184:187], v147 offset:51200
	ds_read_b128 v[188:191], v147 offset:52224
	ds_read_b128 v[192:195], v147 offset:53248
	ds_read_b128 v[196:199], v147 offset:54272
	ds_read_b128 v[200:203], v147 offset:55296
	ds_read_b128 v[204:207], v147 offset:56320
	global_load_lds_dwordx4 v[208:209], off
	s_add_i32 m0, s36, 0x2000
	s_add_u32 s28, s28, 0x40080
	v_lshl_add_u64 v[208:209], v[210:211], 0, s[34:35]
	s_addc_u32 s29, s29, 0
	s_add_i32 s36, s68, s52
	global_load_lds_dwordx4 v[208:209], off
	v_lshl_add_u64 v[208:209], s[28:29], 0, v[0:1]
	s_mov_b32 m0, s36
	s_nop 0
	global_load_lds_dwordx4 v[208:209], off
	v_lshl_add_u64 v[208:209], s[28:29], 0, v[130:131]
	s_add_i32 m0, s36, 0x2000
	s_nop 0
	global_load_lds_dwordx4 v[208:209], off
	v_lshl_add_u64 v[208:209], v[212:213], 0, s[34:35]
	s_mov_b32 m0, s59
	s_nop 0
	global_load_lds_dwordx4 v[208:209], off
	v_lshl_add_u64 v[208:209], v[214:215], 0, s[34:35]
	s_mov_b32 m0, s60
	s_nop 0
	global_load_lds_dwordx4 v[208:209], off
	s_waitcnt vmcnt(8)
	s_waitcnt lgkmcnt(0)
	s_barrier
	s_setprio 1
	s_waitcnt lgkmcnt(0)
	v_mfma_f32_16x16x32_bf16 v[58:61], v[140:143], v[176:179], v[58:61]
	v_mfma_f32_16x16x32_bf16 v[62:65], v[152:155], v[176:179], v[62:65]
	v_mfma_f32_16x16x32_bf16 v[42:45], v[140:143], v[184:187], v[42:45]
	v_mfma_f32_16x16x32_bf16 v[46:49], v[152:155], v[184:187], v[46:49]
	v_mfma_f32_16x16x32_bf16 v[26:29], v[140:143], v[192:195], v[26:29]
	v_mfma_f32_16x16x32_bf16 v[30:33], v[152:155], v[192:195], v[30:33]
	v_mfma_f32_16x16x32_bf16 v[10:13], v[140:143], v[200:203], v[10:13]
	v_mfma_f32_16x16x32_bf16 v[14:17], v[152:155], v[200:203], v[14:17]
	v_mfma_f32_16x16x32_bf16 v[58:61], v[148:151], v[180:183], v[58:61]
	v_mfma_f32_16x16x32_bf16 v[62:65], v[156:159], v[180:183], v[62:65]
	v_mfma_f32_16x16x32_bf16 v[42:45], v[148:151], v[188:191], v[42:45]
	v_mfma_f32_16x16x32_bf16 v[46:49], v[156:159], v[188:191], v[46:49]
	v_mfma_f32_16x16x32_bf16 v[26:29], v[148:151], v[196:199], v[26:29]
	v_mfma_f32_16x16x32_bf16 v[30:33], v[156:159], v[196:199], v[30:33]
	v_mfma_f32_16x16x32_bf16 v[10:13], v[148:151], v[204:207], v[10:13]
	v_mfma_f32_16x16x32_bf16 v[14:17], v[156:159], v[204:207], v[14:17]
	v_mfma_f32_16x16x32_bf16 v[54:57], v[160:163], v[176:179], v[54:57]
	v_mfma_f32_16x16x32_bf16 v[50:53], v[168:171], v[176:179], v[50:53]
	v_mfma_f32_16x16x32_bf16 v[38:41], v[160:163], v[184:187], v[38:41]
	v_mfma_f32_16x16x32_bf16 v[34:37], v[168:171], v[184:187], v[34:37]
	v_mfma_f32_16x16x32_bf16 v[22:25], v[160:163], v[192:195], v[22:25]
	v_mfma_f32_16x16x32_bf16 v[18:21], v[168:171], v[192:195], v[18:21]
	v_mfma_f32_16x16x32_bf16 v[6:9], v[160:163], v[200:203], v[6:9]
	v_mfma_f32_16x16x32_bf16 v[2:5], v[168:171], v[200:203], v[2:5]
	v_mfma_f32_16x16x32_bf16 v[54:57], v[164:167], v[180:183], v[54:57]
	v_mfma_f32_16x16x32_bf16 v[50:53], v[172:175], v[180:183], v[50:53]
	v_mfma_f32_16x16x32_bf16 v[38:41], v[164:167], v[188:191], v[38:41]
	v_mfma_f32_16x16x32_bf16 v[34:37], v[172:175], v[188:191], v[34:37]
	v_mfma_f32_16x16x32_bf16 v[22:25], v[164:167], v[196:199], v[22:25]
	v_mfma_f32_16x16x32_bf16 v[18:21], v[172:175], v[196:199], v[18:21]
	v_mfma_f32_16x16x32_bf16 v[6:9], v[164:167], v[204:207], v[6:9]
	v_mfma_f32_16x16x32_bf16 v[2:5], v[172:175], v[204:207], v[2:5]
	s_setprio 0
	s_barrier
	s_add_i32 s67, s67, 2
	s_add_u32 s46, s46, 0x100
	s_addc_u32 s47, s47, 0
	s_add_u32 s65, s65, 0x100
	s_addc_u32 s66, s66, 0
	s_cmp_gt_u32 s67, 13
	s_cbranch_scc0 .LBB0_997
	s_and_b64 vcc, exec, s[22:23]
	s_cbranch_vccz .LBB0_1000
	s_barrier

; #define PG8_STAGE(bufoff, gbase, voff) do { _Pragma("unroll") for (int _i = 0; _i < 2; ++_i) \
;         __builtin_amdgcn_global_load_lds((const unsigned*)((const char*)(gbase) + (voff)[_i]), (PG8_LAS unsigned*)(lds + (bufoff) + ldsw + _i * 8192), 16, 0, 0); } while (0)
; #define PG8_LDA(dst, b, h) do { _Pragma("unroll") for (int m = 0; m < 4; ++m) _Pragma("unroll") for (int k = 0; k < 2; ++k) dst[m][k] = *(const PG8_LAS bf16x8*)(lds + PG8_SA(b, h) + aoff + m * 2048 + k * 1024); } while (0)
; #define PG8_LDB(dst, b, h) do { _Pragma("unroll") for (int n = 0; n < 2; ++n) _Pragma("unroll") for (int k = 0; k < 2; ++k) dst[n][k] = *(const PG8_LAS bf16x8*)(lds + PG8_SB(b, h) + boff + n * 2048 + k * 1024); } while (0)
; #define PG8_MMA(ai, bj, At, Bt) do { __builtin_amdgcn_s_setprio(1); _Pragma("unroll") for (int m = 0; m < 4; ++m) _Pragma("unroll") for (int n = 0; n < 2; ++n) _Pragma("unroll") for (int k = 0; k < 2; ++k) \
;         acc[ai][bj][m][n] = __builtin_amdgcn_mfma_f32_16x16x32_bf16(Bt[n][k], At[m][k], acc[ai][bj][m][n], 0, 0, 0); __builtin_amdgcn_s_setprio(0); } while (0)
; #define PG8_WAIT_V(n) asm volatile("s_waitcnt vmcnt(" #n ")" ::: "memory")
; #define PG8_WAIT_L(n) asm volatile("s_waitcnt lgkmcnt(" #n ")" ::: "memory")
; #define PG8_BAR __builtin_amdgcn_s_barrier()
; template <class Epi, class Sched, bool ALIGN_EPI = false, bool SP2 = false>
; __device__ __forceinline__ void gemm_phase(PG8_LAS unsigned char* lds, const Gemm g, const Sched& S, const Epi& E, int wave0) {
;     ...
;             const bool last = (t == nt - 2);
;             const char* a1 = cA + (size_t)(t + 1) * kstep;
;             const char* a2 = last ? nA : cA + (size_t)(t + 2) * kstep; const char* b2 = last ? nB : cB + (size_t)(t + 2) * kstep;
;             const char* a3 = a2 + kstep; const char* b3 = b2 + kstep;
;             if constexpr (SP2) {
;             PG8_LDB(B0, 0, 0); PG8_LDB(B1, 0, 1); PG8_SCHED; PG8_LDA(At, 0, 0); PG8_STAGE(PG8_SA(1, 1), a1 + hstep, voffA);
;             PG8_WAIT_V(8); PG8_WAIT_L(0); PG8_BAR; PG8_MMA(0, 0, At, B0); PG8_MMA(0, 1, At, B1); PG8_BAR; PG8_SCHED;
;             PG8_LDA(At, 0, 1); PG8_STAGE(PG8_SB(0, 0), b2, voffB); PG8_STAGE(PG8_SB(0, 1), b2 + hstep, voffB); PG8_STAGE(PG8_SA(0, 0), a2, voffA);
;             PG8_WAIT_V(8); PG8_WAIT_L(0); PG8_BAR; PG8_MMA(1, 0, At, B0); PG8_MMA(1, 1, At, B1); PG8_BAR; PG8_SCHED;
.LBB0_1111:
	s_add_u32 s36, s28, 0xfffc0080
	s_addc_u32 s38, s29, -1
	s_add_i32 s65, 0, 0x10000
	s_cmp_eq_u32 s64, 12
	s_cselect_b32 s43, s23, s38
	s_cselect_b32 s42, s60, s36
	s_cselect_b32 s39, s21, s63
	s_cselect_b32 s38, s61, s62
	s_add_i32 s36, 0, 0x14000
	v_add_u32_e32 v154, s65, v148
	v_add_u32_e32 v170, s36, v148
	ds_read_b128 v[140:143], v154
	ds_read_b128 v[144:147], v154 offset:1024
	ds_read_b128 v[150:153], v154 offset:2048
	ds_read_b128 v[154:157], v154 offset:3072
	ds_read_b128 v[158:161], v170
	ds_read_b128 v[162:165], v170 offset:1024
	ds_read_b128 v[166:169], v170 offset:2048
	ds_read_b128 v[170:173], v170 offset:3072
	v_lshl_add_u64 v[206:207], s[28:29], 0, v[136:137]
	s_add_i32 m0, s47, 0xc000
	ds_read_b128 v[174:177], v149
	ds_read_b128 v[178:181], v149 offset:1024
	ds_read_b128 v[182:185], v149 offset:2048
	ds_read_b128 v[186:189], v149 offset:3072
	ds_read_b128 v[190:193], v149 offset:4096
	ds_read_b128 v[194:197], v149 offset:5120
	ds_read_b128 v[198:201], v149 offset:6144
	ds_read_b128 v[202:205], v149 offset:7168
	global_load_lds_dwordx4 v[206:207], off
	v_lshl_add_u64 v[206:207], s[28:29], 0, v[138:139]
	s_add_i32 m0, s47, 0xe000
	s_nop 0
	global_load_lds_dwordx4 v[206:207], off
	s_waitcnt vmcnt(8)
	s_waitcnt lgkmcnt(0)
	s_barrier
	s_setprio 1
	s_waitcnt lgkmcnt(0)
	v_mfma_f32_16x16x32_bf16 v[126:129], v[140:143], v[174:177], v[126:129]
	v_mfma_f32_16x16x32_bf16 v[122:125], v[150:153], v[174:177], v[122:125]
	v_mfma_f32_16x16x32_bf16 v[110:113], v[140:143], v[182:185], v[110:113]
	v_mfma_f32_16x16x32_bf16 v[106:109], v[150:153], v[182:185], v[106:109]
	v_mfma_f32_16x16x32_bf16 v[94:97], v[140:143], v[190:193], v[94:97]
	v_mfma_f32_16x16x32_bf16 v[90:93], v[150:153], v[190:193], v[90:93]
	v_mfma_f32_16x16x32_bf16 v[78:81], v[140:143], v[198:201], v[78:81]
	v_mfma_f32_16x16x32_bf16 v[74:77], v[150:153], v[198:201], v[74:77]
	v_mfma_f32_16x16x32_bf16 v[126:129], v[144:147], v[178:181], v[126:129]
	v_mfma_f32_16x16x32_bf16 v[122:125], v[154:157], v[178:181], v[122:125]
	v_mfma_f32_16x16x32_bf16 v[110:113], v[144:147], v[186:189], v[110:113]
	v_mfma_f32_16x16x32_bf16 v[106:109], v[154:157], v[186:189], v[106:109]
	v_mfma_f32_16x16x32_bf16 v[94:97], v[144:147], v[194:197], v[94:97]
	v_mfma_f32_16x16x32_bf16 v[90:93], v[154:157], v[194:197], v[90:93]
	v_mfma_f32_16x16x32_bf16 v[78:81], v[144:147], v[202:205], v[78:81]
	v_mfma_f32_16x16x32_bf16 v[74:77], v[154:157], v[202:205], v[74:77]
	v_mfma_f32_16x16x32_bf16 v[118:121], v[158:161], v[174:177], v[118:121]
	v_mfma_f32_16x16x32_bf16 v[114:117], v[166:169], v[174:177], v[114:117]
	v_mfma_f32_16x16x32_bf16 v[102:105], v[158:161], v[182:185], v[102:105]
	v_mfma_f32_16x16x32_bf16 v[98:101], v[166:169], v[182:185], v[98:101]
	v_mfma_f32_16x16x32_bf16 v[86:89], v[158:161], v[190:193], v[86:89]
	v_mfma_f32_16x16x32_bf16 v[82:85], v[166:169], v[190:193], v[82:85]
	v_mfma_f32_16x16x32_bf16 v[70:73], v[158:161], v[198:201], v[70:73]
	v_mfma_f32_16x16x32_bf16 v[66:69], v[166:169], v[198:201], v[66:69]
	v_mfma_f32_16x16x32_bf16 v[118:121], v[162:165], v[178:181], v[118:121]
	v_mfma_f32_16x16x32_bf16 v[114:117], v[170:173], v[178:181], v[114:117]
	v_mfma_f32_16x16x32_bf16 v[102:105], v[162:165], v[186:189], v[102:105]
	v_mfma_f32_16x16x32_bf16 v[98:101], v[170:173], v[186:189], v[98:101]
	v_mfma_f32_16x16x32_bf16 v[86:89], v[162:165], v[194:197], v[86:89]
	v_mfma_f32_16x16x32_bf16 v[82:85], v[170:173], v[194:197], v[82:85]
	v_mfma_f32_16x16x32_bf16 v[70:73], v[162:165], v[202:205], v[70:73]
	v_mfma_f32_16x16x32_bf16 v[66:69], v[170:173], v[202:205], v[66:69]
	s_setprio 0
	s_barrier
	s_add_i32 s65, s65, s46
	v_lshl_add_u64 v[206:207], s[38:39], 0, v[0:1]
	s_mov_b32 m0, s65
	ds_read_b128 v[174:177], v149 offset:16384
	ds_read_b128 v[178:181], v149 offset:17408
	ds_read_b128 v[182:185], v149 offset:18432
	ds_read_b128 v[186:189], v149 offset:19456
	ds_read_b128 v[190:193], v149 offset:20480
	ds_read_b128 v[194:197], v149 offset:21504
	ds_read_b128 v[198:201], v149 offset:22528
	ds_read_b128 v[202:205], v149 offset:23552
	global_load_lds_dwordx4 v[206:207], off
	s_add_i32 m0, s65, 0x2000
	s_add_u32 s66, s38, 0x40000
	v_lshl_add_u64 v[208:209], s[38:39], 0, v[130:131]
	s_addc_u32 s67, s39, 0
	s_add_i32 s36, s36, s46
	global_load_lds_dwordx4 v[208:209], off
	v_lshl_add_u64 v[210:211], s[66:67], 0, v[0:1]
	s_mov_b32 m0, s36
	v_lshl_add_u64 v[212:213], s[42:43], 0, v[132:133]
	global_load_lds_dwordx4 v[210:211], off
	v_lshl_add_u64 v[210:211], s[66:67], 0, v[130:131]
	s_add_i32 m0, s36, 0x2000
	s_nop 0
	global_load_lds_dwordx4 v[210:211], off
	v_lshl_add_u64 v[210:211], s[42:43], 0, v[134:135]
	s_mov_b32 m0, s47
	s_nop 0
	global_load_lds_dwordx4 v[210:211], off
	s_mov_b32 m0, s48
	s_nop 0
	global_load_lds_dwordx4 v[212:213], off
	s_waitcnt vmcnt(8)
	s_waitcnt lgkmcnt(0)
	s_barrier
; #define PG8_STAGE(bufoff, gbase, voff) do { _Pragma("unroll") for (int _i = 0; _i < 2; ++_i) \
;         __builtin_amdgcn_global_load_lds((const unsigned*)((const char*)(gbase) + (voff)[_i]), (PG8_LAS unsigned*)(lds + (bufoff) + ldsw + _i * 8192), 16, 0, 0); } while (0)
; #define PG8_LDA(dst, b, h) do { _Pragma("unroll") for (int m = 0; m < 4; ++m) _Pragma("unroll") for (int k = 0; k < 2; ++k) dst[m][k] = *(const PG8_LAS bf16x8*)(lds + PG8_SA(b, h) + aoff + m * 2048 + k * 1024); } while (0)
; #define PG8_LDB(dst, b, h) do { _Pragma("unroll") for (int n = 0; n < 2; ++n) _Pragma("unroll") for (int k = 0; k < 2; ++k) dst[n][k] = *(const PG8_LAS bf16x8*)(lds + PG8_SB(b, h) + boff + n * 2048 + k * 1024); } while (0)
; #define PG8_MMA(ai, bj, At, Bt) do { __builtin_amdgcn_s_setprio(1); _Pragma("unroll") for (int m = 0; m < 4; ++m) _Pragma("unroll") for (int n = 0; n < 2; ++n) _Pragma("unroll") for (int k = 0; k < 2; ++k) \
;         acc[ai][bj][m][n] = __builtin_amdgcn_mfma_f32_16x16x32_bf16(Bt[n][k], At[m][k], acc[ai][bj][m][n], 0, 0, 0); __builtin_amdgcn_s_setprio(0); } while (0)
; #define PG8_WAIT_V(n) asm volatile("s_waitcnt vmcnt(" #n ")" ::: "memory")
; #define PG8_WAIT_L(n) asm volatile("s_waitcnt lgkmcnt(" #n ")" ::: "memory")
; #define PG8_BAR __builtin_amdgcn_s_barrier()
; #define PG8_SCHED __builtin_amdgcn_sched_barrier(0)
; template <class Epi, class Sched, bool ALIGN_EPI = false, bool SP2 = false>
; __device__ __forceinline__ void gemm_phase(PG8_LAS unsigned char* lds, const Gemm g, const Sched& S, const Epi& E, int wave0) {
;     ...
;             PG8_WAIT_V(8); PG8_WAIT_L(0); PG8_BAR; PG8_MMA(1, 0, At, B0); PG8_MMA(1, 1, At, B1); PG8_BAR; PG8_SCHED;
;             PG8_LDB(B0, 1, 0); PG8_LDB(B1, 1, 1); PG8_SCHED; PG8_LDA(At, 1, 0); PG8_STAGE(PG8_SA(0, 1), a2 + hstep, voffA);
;             PG8_WAIT_V(8); PG8_WAIT_L(0); PG8_BAR; PG8_MMA(0, 0, At, B0); PG8_MMA(0, 1, At, B1); PG8_BAR; PG8_SCHED;
	s_setprio 1
	s_waitcnt lgkmcnt(0)
	v_mfma_f32_16x16x32_bf16 v[62:65], v[140:143], v[174:177], v[62:65]
	v_mfma_f32_16x16x32_bf16 v[58:61], v[150:153], v[174:177], v[58:61]
	v_mfma_f32_16x16x32_bf16 v[46:49], v[140:143], v[182:185], v[46:49]
	v_mfma_f32_16x16x32_bf16 v[42:45], v[150:153], v[182:185], v[42:45]
	v_mfma_f32_16x16x32_bf16 v[30:33], v[140:143], v[190:193], v[30:33]
	v_mfma_f32_16x16x32_bf16 v[26:29], v[150:153], v[190:193], v[26:29]
	v_mfma_f32_16x16x32_bf16 v[14:17], v[140:143], v[198:201], v[14:17]
	v_mfma_f32_16x16x32_bf16 v[10:13], v[150:153], v[198:201], v[10:13]
	v_mfma_f32_16x16x32_bf16 v[62:65], v[144:147], v[178:181], v[62:65]
	v_mfma_f32_16x16x32_bf16 v[58:61], v[154:157], v[178:181], v[58:61]
	v_mfma_f32_16x16x32_bf16 v[46:49], v[144:147], v[186:189], v[46:49]
	v_mfma_f32_16x16x32_bf16 v[42:45], v[154:157], v[186:189], v[42:45]
	v_mfma_f32_16x16x32_bf16 v[30:33], v[144:147], v[194:197], v[30:33]
	v_mfma_f32_16x16x32_bf16 v[26:29], v[154:157], v[194:197], v[26:29]
	v_mfma_f32_16x16x32_bf16 v[14:17], v[144:147], v[202:205], v[14:17]
	v_mfma_f32_16x16x32_bf16 v[10:13], v[154:157], v[202:205], v[10:13]
	v_mfma_f32_16x16x32_bf16 v[54:57], v[158:161], v[174:177], v[54:57]
	v_mfma_f32_16x16x32_bf16 v[50:53], v[166:169], v[174:177], v[50:53]
	v_mfma_f32_16x16x32_bf16 v[38:41], v[158:161], v[182:185], v[38:41]
	v_mfma_f32_16x16x32_bf16 v[34:37], v[166:169], v[182:185], v[34:37]
	v_mfma_f32_16x16x32_bf16 v[22:25], v[158:161], v[190:193], v[22:25]
	v_mfma_f32_16x16x32_bf16 v[18:21], v[166:169], v[190:193], v[18:21]
	v_mfma_f32_16x16x32_bf16 v[6:9], v[158:161], v[198:201], v[6:9]
	v_mfma_f32_16x16x32_bf16 v[2:5], v[166:169], v[198:201], v[2:5]
	v_mfma_f32_16x16x32_bf16 v[54:57], v[162:165], v[178:181], v[54:57]
	v_mfma_f32_16x16x32_bf16 v[50:53], v[170:173], v[178:181], v[50:53]
	v_mfma_f32_16x16x32_bf16 v[38:41], v[162:165], v[186:189], v[38:41]
	v_mfma_f32_16x16x32_bf16 v[34:37], v[170:173], v[186:189], v[34:37]
	v_mfma_f32_16x16x32_bf16 v[22:25], v[162:165], v[194:197], v[22:25]
	v_mfma_f32_16x16x32_bf16 v[18:21], v[170:173], v[194:197], v[18:21]
	v_mfma_f32_16x16x32_bf16 v[6:9], v[162:165], v[202:205], v[6:9]
	v_mfma_f32_16x16x32_bf16 v[2:5], v[170:173], v[202:205], v[2:5]
	s_setprio 0
	s_barrier
	s_add_i32 s36, 0, 0x18000
	s_add_i32 s65, 0, 0x1c000
	v_add_u32_e32 v154, s36, v148
	v_add_u32_e32 v170, s65, v148
	ds_read_b128 v[140:143], v154
	ds_read_b128 v[144:147], v154 offset:1024
	ds_read_b128 v[150:153], v154 offset:2048
	ds_read_b128 v[154:157], v154 offset:3072
	ds_read_b128 v[158:161], v170
	ds_read_b128 v[162:165], v170 offset:1024
	ds_read_b128 v[166:169], v170 offset:2048
	ds_read_b128 v[170:173], v170 offset:3072
	s_add_u32 s42, s42, 0x40000
	s_addc_u32 s43, s43, 0
	s_mov_b32 m0, s49
	v_lshl_add_u64 v[214:215], s[42:43], 0, v[134:135]
	ds_read_b128 v[174:177], v149 offset:32768
	ds_read_b128 v[178:181], v149 offset:33792
	ds_read_b128 v[182:185], v149 offset:34816
	ds_read_b128 v[186:189], v149 offset:35840
	ds_read_b128 v[190:193], v149 offset:36864
	ds_read_b128 v[194:197], v149 offset:37888
	ds_read_b128 v[198:201], v149 offset:38912
	ds_read_b128 v[202:205], v149 offset:39936
	global_load_lds_dwordx4 v[214:215], off
	v_lshl_add_u64 v[214:215], s[42:43], 0, v[132:133]
	s_mov_b32 m0, s50
	s_nop 0
	global_load_lds_dwordx4 v[214:215], off
	s_waitcnt vmcnt(8)
	s_waitcnt lgkmcnt(0)
	s_barrier
	s_setprio 1
	s_waitcnt lgkmcnt(0)
	v_mfma_f32_16x16x32_bf16 v[126:129], v[140:143], v[174:177], v[126:129]
	v_mfma_f32_16x16x32_bf16 v[122:125], v[150:153], v[174:177], v[122:125]
	v_mfma_f32_16x16x32_bf16 v[110:113], v[140:143], v[182:185], v[110:113]
	v_mfma_f32_16x16x32_bf16 v[106:109], v[150:153], v[182:185], v[106:109]
	v_mfma_f32_16x16x32_bf16 v[94:97], v[140:143], v[190:193], v[94:97]
	v_mfma_f32_16x16x32_bf16 v[90:93], v[150:153], v[190:193], v[90:93]
	v_mfma_f32_16x16x32_bf16 v[78:81], v[140:143], v[198:201], v[78:81]
	v_mfma_f32_16x16x32_bf16 v[74:77], v[150:153], v[198:201], v[74:77]
	v_mfma_f32_16x16x32_bf16 v[126:129], v[144:147], v[178:181], v[126:129]
	v_mfma_f32_16x16x32_bf16 v[122:125], v[154:157], v[178:181], v[122:125]
	v_mfma_f32_16x16x32_bf16 v[110:113], v[144:147], v[186:189], v[110:113]
	v_mfma_f32_16x16x32_bf16 v[106:109], v[154:157], v[186:189], v[106:109]
	v_mfma_f32_16x16x32_bf16 v[94:97], v[144:147], v[194:197], v[94:97]
	v_mfma_f32_16x16x32_bf16 v[90:93], v[154:157], v[194:197], v[90:93]
	v_mfma_f32_16x16x32_bf16 v[78:81], v[144:147], v[202:205], v[78:81]
	v_mfma_f32_16x16x32_bf16 v[74:77], v[154:157], v[202:205], v[74:77]
	v_mfma_f32_16x16x32_bf16 v[118:121], v[158:161], v[174:177], v[118:121]
	v_mfma_f32_16x16x32_bf16 v[114:117], v[166:169], v[174:177], v[114:117]
	v_mfma_f32_16x16x32_bf16 v[102:105], v[158:161], v[182:185], v[102:105]
	v_mfma_f32_16x16x32_bf16 v[98:101], v[166:169], v[182:185], v[98:101]
	v_mfma_f32_16x16x32_bf16 v[86:89], v[158:161], v[190:193], v[86:89]
	v_mfma_f32_16x16x32_bf16 v[82:85], v[166:169], v[190:193], v[82:85]
	v_mfma_f32_16x16x32_bf16 v[70:73], v[158:161], v[198:201], v[70:73]
	v_mfma_f32_16x16x32_bf16 v[66:69], v[166:169], v[198:201], v[66:69]
	v_mfma_f32_16x16x32_bf16 v[118:121], v[162:165], v[178:181], v[118:121]
	v_mfma_f32_16x16x32_bf16 v[114:117], v[170:173], v[178:181], v[114:117]
	v_mfma_f32_16x16x32_bf16 v[102:105], v[162:165], v[186:189], v[102:105]
	v_mfma_f32_16x16x32_bf16 v[98:101], v[170:173], v[186:189], v[98:101]
	v_mfma_f32_16x16x32_bf16 v[86:89], v[162:165], v[194:197], v[86:89]
	v_mfma_f32_16x16x32_bf16 v[82:85], v[170:173], v[194:197], v[82:85]
	v_mfma_f32_16x16x32_bf16 v[70:73], v[162:165], v[202:205], v[70:73]
	v_mfma_f32_16x16x32_bf16 v[66:69], v[170:173], v[202:205], v[66:69]
	s_setprio 0
	s_barrier
; #define PG8_STAGE(bufoff, gbase, voff) do { _Pragma("unroll") for (int _i = 0; _i < 2; ++_i) \
;         __builtin_amdgcn_global_load_lds((const unsigned*)((const char*)(gbase) + (voff)[_i]), (PG8_LAS unsigned*)(lds + (bufoff) + ldsw + _i * 8192), 16, 0, 0); } while (0)
; #define PG8_LDA(dst, b, h) do { _Pragma("unroll") for (int m = 0; m < 4; ++m) _Pragma("unroll") for (int k = 0; k < 2; ++k) dst[m][k] = *(const PG8_LAS bf16x8*)(lds + PG8_SA(b, h) + aoff + m * 2048 + k * 1024); } while (0)
; #define PG8_MMA(ai, bj, At, Bt) do { __builtin_amdgcn_s_setprio(1); _Pragma("unroll") for (int m = 0; m < 4; ++m) _Pragma("unroll") for (int n = 0; n < 2; ++n) _Pragma("unroll") for (int k = 0; k < 2; ++k) \
;         acc[ai][bj][m][n] = __builtin_amdgcn_mfma_f32_16x16x32_bf16(Bt[n][k], At[m][k], acc[ai][bj][m][n], 0, 0, 0); __builtin_amdgcn_s_setprio(0); } while (0)
; #define PG8_WAIT_V(n) asm volatile("s_waitcnt vmcnt(" #n ")" ::: "memory")
; #define PG8_WAIT_L(n) asm volatile("s_waitcnt lgkmcnt(" #n ")" ::: "memory")
; #define PG8_BAR __builtin_amdgcn_s_barrier()
; #define PG8_SCHED __builtin_amdgcn_sched_barrier(0)
; template <class Epi, class Sched, bool ALIGN_EPI = false, bool SP2 = false>
; __device__ __forceinline__ void gemm_phase(PG8_LAS unsigned char* lds, const Gemm g, const Sched& S, const Epi& E, int wave0) {
;     ...
;         for (int t = 0; t < nt; t += 2) {
;             const bool last = (t == nt - 2);
;             const char* a1 = cA + (size_t)(t + 1) * kstep;
;             const char* a2 = last ? nA : cA + (size_t)(t + 2) * kstep; const char* b2 = last ? nB : cB + (size_t)(t + 2) * kstep;
;             const char* a3 = a2 + kstep; const char* b3 = b2 + kstep;
;     ...
;             PG8_LDA(At, 1, 1); PG8_STAGE(PG8_SB(1, 0), b3, voffB); PG8_STAGE(PG8_SB(1, 1), b3 + hstep, voffB); PG8_STAGE(PG8_SA(1, 0), a3, voffA);
;             PG8_WAIT_V(8); PG8_WAIT_L(0); PG8_BAR; PG8_MMA(1, 0, At, B0); PG8_MMA(1, 1, At, B1); PG8_BAR; PG8_SCHED;
	s_add_i32 s36, s36, s46
	v_lshl_add_u64 v[206:207], v[206:207], 0, s[34:35]
	s_mov_b32 m0, s36
	ds_read_b128 v[174:177], v149 offset:49152
	ds_read_b128 v[178:181], v149 offset:50176
	ds_read_b128 v[182:185], v149 offset:51200
	ds_read_b128 v[186:189], v149 offset:52224
	ds_read_b128 v[190:193], v149 offset:53248
	ds_read_b128 v[194:197], v149 offset:54272
	ds_read_b128 v[198:201], v149 offset:55296
	ds_read_b128 v[202:205], v149 offset:56320
	global_load_lds_dwordx4 v[206:207], off
	s_add_i32 m0, s36, 0x2000
	s_add_u32 s38, s38, 0x40080
	v_lshl_add_u64 v[206:207], v[208:209], 0, s[34:35]
	s_addc_u32 s39, s39, 0
	s_add_i32 s36, s65, s46
	global_load_lds_dwordx4 v[206:207], off
	v_lshl_add_u64 v[206:207], s[38:39], 0, v[0:1]
	s_mov_b32 m0, s36
	s_nop 0
	global_load_lds_dwordx4 v[206:207], off
	v_lshl_add_u64 v[206:207], s[38:39], 0, v[130:131]
	s_add_i32 m0, s36, 0x2000
	s_nop 0
	global_load_lds_dwordx4 v[206:207], off
	v_lshl_add_u64 v[206:207], v[210:211], 0, s[34:35]
	s_mov_b32 m0, s53
	s_nop 0
	global_load_lds_dwordx4 v[206:207], off
	v_lshl_add_u64 v[206:207], v[212:213], 0, s[34:35]
	s_mov_b32 m0, s54
	s_nop 0
	global_load_lds_dwordx4 v[206:207], off
	s_waitcnt vmcnt(8)
	s_waitcnt lgkmcnt(0)
	s_barrier
	s_setprio 1
	s_waitcnt lgkmcnt(0)
	v_mfma_f32_16x16x32_bf16 v[62:65], v[140:143], v[174:177], v[62:65]
	v_mfma_f32_16x16x32_bf16 v[58:61], v[150:153], v[174:177], v[58:61]
	v_mfma_f32_16x16x32_bf16 v[46:49], v[140:143], v[182:185], v[46:49]
	v_mfma_f32_16x16x32_bf16 v[42:45], v[150:153], v[182:185], v[42:45]
	v_mfma_f32_16x16x32_bf16 v[30:33], v[140:143], v[190:193], v[30:33]
	v_mfma_f32_16x16x32_bf16 v[26:29], v[150:153], v[190:193], v[26:29]
	v_mfma_f32_16x16x32_bf16 v[14:17], v[140:143], v[198:201], v[14:17]
	v_mfma_f32_16x16x32_bf16 v[10:13], v[150:153], v[198:201], v[10:13]
	v_mfma_f32_16x16x32_bf16 v[62:65], v[144:147], v[178:181], v[62:65]
	v_mfma_f32_16x16x32_bf16 v[58:61], v[154:157], v[178:181], v[58:61]
	v_mfma_f32_16x16x32_bf16 v[46:49], v[144:147], v[186:189], v[46:49]
	v_mfma_f32_16x16x32_bf16 v[42:45], v[154:157], v[186:189], v[42:45]
	v_mfma_f32_16x16x32_bf16 v[30:33], v[144:147], v[194:197], v[30:33]
	v_mfma_f32_16x16x32_bf16 v[26:29], v[154:157], v[194:197], v[26:29]
	v_mfma_f32_16x16x32_bf16 v[14:17], v[144:147], v[202:205], v[14:17]
	v_mfma_f32_16x16x32_bf16 v[10:13], v[154:157], v[202:205], v[10:13]
	v_mfma_f32_16x16x32_bf16 v[54:57], v[158:161], v[174:177], v[54:57]
	v_mfma_f32_16x16x32_bf16 v[50:53], v[166:169], v[174:177], v[50:53]
	v_mfma_f32_16x16x32_bf16 v[38:41], v[158:161], v[182:185], v[38:41]
	v_mfma_f32_16x16x32_bf16 v[34:37], v[166:169], v[182:185], v[34:37]
	v_mfma_f32_16x16x32_bf16 v[22:25], v[158:161], v[190:193], v[22:25]
	v_mfma_f32_16x16x32_bf16 v[18:21], v[166:169], v[190:193], v[18:21]
	v_mfma_f32_16x16x32_bf16 v[6:9], v[158:161], v[198:201], v[6:9]
	v_mfma_f32_16x16x32_bf16 v[2:5], v[166:169], v[198:201], v[2:5]
	v_mfma_f32_16x16x32_bf16 v[54:57], v[162:165], v[178:181], v[54:57]
	v_mfma_f32_16x16x32_bf16 v[50:53], v[170:173], v[178:181], v[50:53]
	v_mfma_f32_16x16x32_bf16 v[38:41], v[162:165], v[186:189], v[38:41]
	v_mfma_f32_16x16x32_bf16 v[34:37], v[170:173], v[186:189], v[34:37]
	v_mfma_f32_16x16x32_bf16 v[22:25], v[162:165], v[194:197], v[22:25]
	v_mfma_f32_16x16x32_bf16 v[18:21], v[170:173], v[194:197], v[18:21]
	v_mfma_f32_16x16x32_bf16 v[6:9], v[162:165], v[202:205], v[6:9]
	v_mfma_f32_16x16x32_bf16 v[2:5], v[170:173], v[202:205], v[2:5]
	s_setprio 0
	s_barrier
	s_add_i32 s64, s64, 2
	s_add_u32 s28, s28, 0x100
	s_addc_u32 s29, s29, 0
	s_add_u32 s62, s62, 0x100
	s_addc_u32 s63, s63, 0
	s_cmp_gt_u32 s64, 13
	s_cbranch_scc0 .LBB0_1111
	s_and_b64 vcc, exec, s[10:11]
	s_cbranch_vccz .LBB0_1114
	s_barrier

; #define PG8_STAGE(bufoff, gbase, voff) do { _Pragma("unroll") for (int _i = 0; _i < 2; ++_i) \
;         __builtin_amdgcn_global_load_lds((const unsigned*)((const char*)(gbase) + (voff)[_i]), (PG8_LAS unsigned*)(lds + (bufoff) + ldsw + _i * 8192), 16, 0, 0); } while (0)
; #define PG8_LDA(dst, b, h) do { _Pragma("unroll") for (int m = 0; m < 4; ++m) _Pragma("unroll") for (int k = 0; k < 2; ++k) dst[m][k] = *(const PG8_LAS bf16x8*)(lds + PG8_SA(b, h) + aoff + m * 2048 + k * 1024); } while (0)
; #define PG8_LDB(dst, b, h) do { _Pragma("unroll") for (int n = 0; n < 2; ++n) _Pragma("unroll") for (int k = 0; k < 2; ++k) dst[n][k] = *(const PG8_LAS bf16x8*)(lds + PG8_SB(b, h) + boff + n * 2048 + k * 1024); } while (0)
; #define PG8_MMA(ai, bj, At, Bt) do { __builtin_amdgcn_s_setprio(1); _Pragma("unroll") for (int m = 0; m < 4; ++m) _Pragma("unroll") for (int n = 0; n < 2; ++n) _Pragma("unroll") for (int k = 0; k < 2; ++k) \
;         acc[ai][bj][m][n] = __builtin_amdgcn_mfma_f32_16x16x32_bf16(Bt[n][k], At[m][k], acc[ai][bj][m][n], 0, 0, 0); __builtin_amdgcn_s_setprio(0); } while (0)
; #define PG8_WAIT_V(n) asm volatile("s_waitcnt vmcnt(" #n ")" ::: "memory")
; #define PG8_WAIT_L(n) asm volatile("s_waitcnt lgkmcnt(" #n ")" ::: "memory")
; #define PG8_BAR __builtin_amdgcn_s_barrier()
; template <class Epi, class Sched, bool ALIGN_EPI = false, bool SP2 = false>
; __device__ __forceinline__ void gemm_phase(PG8_LAS unsigned char* lds, const Gemm g, const Sched& S, const Epi& E, int wave0) {
;     ...
;             const bool last = (t == nt - 2);
;             const char* a1 = cA + (size_t)(t + 1) * kstep;
;             const char* a2 = last ? nA : cA + (size_t)(t + 2) * kstep; const char* b2 = last ? nB : cB + (size_t)(t + 2) * kstep;
;             const char* a3 = a2 + kstep; const char* b3 = b2 + kstep;
;             if constexpr (SP2) {
;             PG8_LDB(B0, 0, 0); PG8_LDB(B1, 0, 1); PG8_SCHED; PG8_LDA(At, 0, 0); PG8_STAGE(PG8_SA(1, 1), a1 + hstep, voffA);
;             PG8_WAIT_V(8); PG8_WAIT_L(0); PG8_BAR; PG8_MMA(0, 0, At, B0); PG8_MMA(0, 1, At, B1); PG8_BAR; PG8_SCHED;
;             PG8_LDA(At, 0, 1); PG8_STAGE(PG8_SB(0, 0), b2, voffB); PG8_STAGE(PG8_SB(0, 1), b2 + hstep, voffB); PG8_STAGE(PG8_SA(0, 0), a2, voffA);
;             PG8_WAIT_V(8); PG8_WAIT_L(0); PG8_BAR; PG8_MMA(1, 0, At, B0); PG8_MMA(1, 1, At, B1); PG8_BAR; PG8_SCHED;
.LBB0_1198:
	s_add_u32 s4, s6, 0xfff00080
	s_addc_u32 s5, s7, -1
	s_add_i32 s36, 0, 0x10000
	s_cmp_eq_u32 s63, 60
	s_cselect_b32 s29, s39, s5
	s_cselect_b32 s28, s47, s4
	v_add_u32_e32 v144, s36, v147
	s_cselect_b32 s5, s31, s62
	s_cselect_b32 s4, s60, s61
	s_add_i32 s66, 0, 0x14000
	ds_read_b128 v[140:143], v144
	ds_read_b128 v[150:153], v144 offset:1024
	ds_read_b128 v[154:157], v144 offset:2048
	ds_read_b128 v[158:161], v144 offset:3072
	v_add_u32_e32 v144, s66, v147
	ds_read_b128 v[162:165], v144
	ds_read_b128 v[166:169], v144 offset:1024
	ds_read_b128 v[170:173], v144 offset:2048
	ds_read_b128 v[174:177], v144 offset:3072
	v_lshl_add_u64 v[144:145], s[6:7], 0, v[136:137]
	s_add_i32 m0, s53, 0xc000
	ds_read_b128 v[178:181], v149
	ds_read_b128 v[182:185], v149 offset:1024
	ds_read_b128 v[186:189], v149 offset:2048
	ds_read_b128 v[190:193], v149 offset:3072
	ds_read_b128 v[194:197], v149 offset:4096
	ds_read_b128 v[198:201], v149 offset:5120
	ds_read_b128 v[202:205], v149 offset:6144
	ds_read_b128 v[206:209], v149 offset:7168
	global_load_lds_dwordx4 v[144:145], off
	v_lshl_add_u64 v[144:145], s[6:7], 0, v[138:139]
	s_add_i32 m0, s53, 0xe000
	s_nop 0
	global_load_lds_dwordx4 v[144:145], off
	s_waitcnt vmcnt(8)
	s_waitcnt lgkmcnt(0)
	s_barrier
	s_setprio 1
	s_waitcnt lgkmcnt(0)
	v_mfma_f32_16x16x32_bf16 v[126:129], v[140:143], v[178:181], v[126:129]
	v_mfma_f32_16x16x32_bf16 v[122:125], v[154:157], v[178:181], v[122:125]
	v_mfma_f32_16x16x32_bf16 v[110:113], v[140:143], v[186:189], v[110:113]
	v_mfma_f32_16x16x32_bf16 v[106:109], v[154:157], v[186:189], v[106:109]
	v_mfma_f32_16x16x32_bf16 v[94:97], v[140:143], v[194:197], v[94:97]
	v_mfma_f32_16x16x32_bf16 v[90:93], v[154:157], v[194:197], v[90:93]
	v_mfma_f32_16x16x32_bf16 v[78:81], v[140:143], v[202:205], v[78:81]
	v_mfma_f32_16x16x32_bf16 v[74:77], v[154:157], v[202:205], v[74:77]
	v_mfma_f32_16x16x32_bf16 v[126:129], v[150:153], v[182:185], v[126:129]
	v_mfma_f32_16x16x32_bf16 v[122:125], v[158:161], v[182:185], v[122:125]
	v_mfma_f32_16x16x32_bf16 v[110:113], v[150:153], v[190:193], v[110:113]
	v_mfma_f32_16x16x32_bf16 v[106:109], v[158:161], v[190:193], v[106:109]
	v_mfma_f32_16x16x32_bf16 v[94:97], v[150:153], v[198:201], v[94:97]
	v_mfma_f32_16x16x32_bf16 v[90:93], v[158:161], v[198:201], v[90:93]
	v_mfma_f32_16x16x32_bf16 v[78:81], v[150:153], v[206:209], v[78:81]
	v_mfma_f32_16x16x32_bf16 v[74:77], v[158:161], v[206:209], v[74:77]
	v_mfma_f32_16x16x32_bf16 v[118:121], v[162:165], v[178:181], v[118:121]
	v_mfma_f32_16x16x32_bf16 v[114:117], v[170:173], v[178:181], v[114:117]
	v_mfma_f32_16x16x32_bf16 v[102:105], v[162:165], v[186:189], v[102:105]
	v_mfma_f32_16x16x32_bf16 v[98:101], v[170:173], v[186:189], v[98:101]
	v_mfma_f32_16x16x32_bf16 v[86:89], v[162:165], v[194:197], v[86:89]
	v_mfma_f32_16x16x32_bf16 v[82:85], v[170:173], v[194:197], v[82:85]
	v_mfma_f32_16x16x32_bf16 v[70:73], v[162:165], v[202:205], v[70:73]
	v_mfma_f32_16x16x32_bf16 v[66:69], v[170:173], v[202:205], v[66:69]
	v_mfma_f32_16x16x32_bf16 v[118:121], v[166:169], v[182:185], v[118:121]
	v_mfma_f32_16x16x32_bf16 v[114:117], v[174:177], v[182:185], v[114:117]
	v_mfma_f32_16x16x32_bf16 v[102:105], v[166:169], v[190:193], v[102:105]
	v_mfma_f32_16x16x32_bf16 v[98:101], v[174:177], v[190:193], v[98:101]
	v_mfma_f32_16x16x32_bf16 v[86:89], v[166:169], v[198:201], v[86:89]
	v_mfma_f32_16x16x32_bf16 v[82:85], v[174:177], v[198:201], v[82:85]
	v_mfma_f32_16x16x32_bf16 v[70:73], v[166:169], v[206:209], v[70:73]
	v_mfma_f32_16x16x32_bf16 v[66:69], v[174:177], v[206:209], v[66:69]
	s_setprio 0
	s_barrier
	s_add_i32 s36, s36, s50
	v_lshl_add_u64 v[144:145], s[4:5], 0, v[0:1]
	s_mov_b32 m0, s36
	ds_read_b128 v[178:181], v149 offset:16384
	ds_read_b128 v[182:185], v149 offset:17408
	ds_read_b128 v[186:189], v149 offset:18432
	ds_read_b128 v[190:193], v149 offset:19456
	ds_read_b128 v[194:197], v149 offset:20480
	ds_read_b128 v[198:201], v149 offset:21504
	ds_read_b128 v[202:205], v149 offset:22528
	ds_read_b128 v[206:209], v149 offset:23552
	global_load_lds_dwordx4 v[144:145], off
	s_add_i32 m0, s36, 0x2000
	s_add_u32 s64, s4, 0x100000
	v_lshl_add_u64 v[210:211], s[4:5], 0, v[130:131]
	s_addc_u32 s65, s5, 0
	s_add_i32 s36, s66, s50
	global_load_lds_dwordx4 v[210:211], off
	v_lshl_add_u64 v[212:213], s[64:65], 0, v[0:1]
	s_mov_b32 m0, s36
	v_lshl_add_u64 v[214:215], s[28:29], 0, v[132:133]
	global_load_lds_dwordx4 v[212:213], off
	v_lshl_add_u64 v[212:213], s[64:65], 0, v[130:131]
	s_add_i32 m0, s36, 0x2000
	s_nop 0
	global_load_lds_dwordx4 v[212:213], off
	v_lshl_add_u64 v[212:213], s[28:29], 0, v[134:135]
	s_mov_b32 m0, s53
	s_nop 0
	global_load_lds_dwordx4 v[212:213], off
	s_mov_b32 m0, s54
	s_nop 0
	global_load_lds_dwordx4 v[214:215], off
	s_waitcnt vmcnt(8)
	s_waitcnt lgkmcnt(0)
	s_barrier
; #define PG8_STAGE(bufoff, gbase, voff) do { _Pragma("unroll") for (int _i = 0; _i < 2; ++_i) \
;         __builtin_amdgcn_global_load_lds((const unsigned*)((const char*)(gbase) + (voff)[_i]), (PG8_LAS unsigned*)(lds + (bufoff) + ldsw + _i * 8192), 16, 0, 0); } while (0)
; #define PG8_LDA(dst, b, h) do { _Pragma("unroll") for (int m = 0; m < 4; ++m) _Pragma("unroll") for (int k = 0; k < 2; ++k) dst[m][k] = *(const PG8_LAS bf16x8*)(lds + PG8_SA(b, h) + aoff + m * 2048 + k * 1024); } while (0)
; #define PG8_LDB(dst, b, h) do { _Pragma("unroll") for (int n = 0; n < 2; ++n) _Pragma("unroll") for (int k = 0; k < 2; ++k) dst[n][k] = *(const PG8_LAS bf16x8*)(lds + PG8_SB(b, h) + boff + n * 2048 + k * 1024); } while (0)
; #define PG8_MMA(ai, bj, At, Bt) do { __builtin_amdgcn_s_setprio(1); _Pragma("unroll") for (int m = 0; m < 4; ++m) _Pragma("unroll") for (int n = 0; n < 2; ++n) _Pragma("unroll") for (int k = 0; k < 2; ++k) \
;         acc[ai][bj][m][n] = __builtin_amdgcn_mfma_f32_16x16x32_bf16(Bt[n][k], At[m][k], acc[ai][bj][m][n], 0, 0, 0); __builtin_amdgcn_s_setprio(0); } while (0)
; #define PG8_WAIT_V(n) asm volatile("s_waitcnt vmcnt(" #n ")" ::: "memory")
; #define PG8_WAIT_L(n) asm volatile("s_waitcnt lgkmcnt(" #n ")" ::: "memory")
; #define PG8_BAR __builtin_amdgcn_s_barrier()
; #define PG8_SCHED __builtin_amdgcn_sched_barrier(0)
; template <class Epi, class Sched, bool ALIGN_EPI = false, bool SP2 = false>
; __device__ __forceinline__ void gemm_phase(PG8_LAS unsigned char* lds, const Gemm g, const Sched& S, const Epi& E, int wave0) {
;     ...
;             PG8_WAIT_V(8); PG8_WAIT_L(0); PG8_BAR; PG8_MMA(1, 0, At, B0); PG8_MMA(1, 1, At, B1); PG8_BAR; PG8_SCHED;
;             PG8_LDB(B0, 1, 0); PG8_LDB(B1, 1, 1); PG8_SCHED; PG8_LDA(At, 1, 0); PG8_STAGE(PG8_SA(0, 1), a2 + hstep, voffA);
;             PG8_WAIT_V(8); PG8_WAIT_L(0); PG8_BAR; PG8_MMA(0, 0, At, B0); PG8_MMA(0, 1, At, B1); PG8_BAR; PG8_SCHED;
	s_setprio 1
	s_waitcnt lgkmcnt(0)
	v_mfma_f32_16x16x32_bf16 v[58:61], v[140:143], v[178:181], v[58:61]
	v_mfma_f32_16x16x32_bf16 v[62:65], v[154:157], v[178:181], v[62:65]
	v_mfma_f32_16x16x32_bf16 v[42:45], v[140:143], v[186:189], v[42:45]
	v_mfma_f32_16x16x32_bf16 v[46:49], v[154:157], v[186:189], v[46:49]
	v_mfma_f32_16x16x32_bf16 v[26:29], v[140:143], v[194:197], v[26:29]
	v_mfma_f32_16x16x32_bf16 v[30:33], v[154:157], v[194:197], v[30:33]
	v_mfma_f32_16x16x32_bf16 v[10:13], v[140:143], v[202:205], v[10:13]
	v_mfma_f32_16x16x32_bf16 v[14:17], v[154:157], v[202:205], v[14:17]
	v_mfma_f32_16x16x32_bf16 v[58:61], v[150:153], v[182:185], v[58:61]
	v_mfma_f32_16x16x32_bf16 v[62:65], v[158:161], v[182:185], v[62:65]
	v_mfma_f32_16x16x32_bf16 v[42:45], v[150:153], v[190:193], v[42:45]
	v_mfma_f32_16x16x32_bf16 v[46:49], v[158:161], v[190:193], v[46:49]
	v_mfma_f32_16x16x32_bf16 v[26:29], v[150:153], v[198:201], v[26:29]
	v_mfma_f32_16x16x32_bf16 v[30:33], v[158:161], v[198:201], v[30:33]
	v_mfma_f32_16x16x32_bf16 v[10:13], v[150:153], v[206:209], v[10:13]
	v_mfma_f32_16x16x32_bf16 v[14:17], v[158:161], v[206:209], v[14:17]
	v_mfma_f32_16x16x32_bf16 v[54:57], v[162:165], v[178:181], v[54:57]
	v_mfma_f32_16x16x32_bf16 v[50:53], v[170:173], v[178:181], v[50:53]
	v_mfma_f32_16x16x32_bf16 v[38:41], v[162:165], v[186:189], v[38:41]
	v_mfma_f32_16x16x32_bf16 v[34:37], v[170:173], v[186:189], v[34:37]
	v_mfma_f32_16x16x32_bf16 v[22:25], v[162:165], v[194:197], v[22:25]
	v_mfma_f32_16x16x32_bf16 v[18:21], v[170:173], v[194:197], v[18:21]
	v_mfma_f32_16x16x32_bf16 v[6:9], v[162:165], v[202:205], v[6:9]
	v_mfma_f32_16x16x32_bf16 v[2:5], v[170:173], v[202:205], v[2:5]
	v_mfma_f32_16x16x32_bf16 v[54:57], v[166:169], v[182:185], v[54:57]
	v_mfma_f32_16x16x32_bf16 v[50:53], v[174:177], v[182:185], v[50:53]
	v_mfma_f32_16x16x32_bf16 v[38:41], v[166:169], v[190:193], v[38:41]
	v_mfma_f32_16x16x32_bf16 v[34:37], v[174:177], v[190:193], v[34:37]
	v_mfma_f32_16x16x32_bf16 v[22:25], v[166:169], v[198:201], v[22:25]
	v_mfma_f32_16x16x32_bf16 v[18:21], v[174:177], v[198:201], v[18:21]
	v_mfma_f32_16x16x32_bf16 v[6:9], v[166:169], v[206:209], v[6:9]
	v_mfma_f32_16x16x32_bf16 v[2:5], v[174:177], v[206:209], v[2:5]
	s_setprio 0
	s_barrier
	s_add_i32 s36, 0, 0x18000
	s_add_i32 s64, 0, 0x1c000
	v_add_u32_e32 v158, s36, v147
	v_add_u32_e32 v174, s64, v147
	ds_read_b128 v[140:143], v158
	ds_read_b128 v[150:153], v158 offset:1024
	ds_read_b128 v[154:157], v158 offset:2048
	ds_read_b128 v[158:161], v158 offset:3072
	ds_read_b128 v[162:165], v174
	ds_read_b128 v[166:169], v174 offset:1024
	ds_read_b128 v[170:173], v174 offset:2048
	ds_read_b128 v[174:177], v174 offset:3072
	s_add_u32 s28, s28, 0x100000
	s_addc_u32 s29, s29, 0
	s_mov_b32 m0, s55
	v_lshl_add_u64 v[216:217], s[28:29], 0, v[134:135]
	ds_read_b128 v[178:181], v149 offset:32768
	ds_read_b128 v[182:185], v149 offset:33792
	ds_read_b128 v[186:189], v149 offset:34816
	ds_read_b128 v[190:193], v149 offset:35840
	ds_read_b128 v[194:197], v149 offset:36864
	ds_read_b128 v[198:201], v149 offset:37888
	ds_read_b128 v[202:205], v149 offset:38912
	ds_read_b128 v[206:209], v149 offset:39936
	global_load_lds_dwordx4 v[216:217], off
	v_lshl_add_u64 v[216:217], s[28:29], 0, v[132:133]
	s_mov_b32 m0, s56
	s_nop 0
	global_load_lds_dwordx4 v[216:217], off
	s_waitcnt vmcnt(8)
	s_waitcnt lgkmcnt(0)
	s_barrier
	s_setprio 1
	s_waitcnt lgkmcnt(0)
	v_mfma_f32_16x16x32_bf16 v[126:129], v[140:143], v[178:181], v[126:129]
	v_mfma_f32_16x16x32_bf16 v[122:125], v[154:157], v[178:181], v[122:125]
	v_mfma_f32_16x16x32_bf16 v[110:113], v[140:143], v[186:189], v[110:113]
	v_mfma_f32_16x16x32_bf16 v[106:109], v[154:157], v[186:189], v[106:109]
	v_mfma_f32_16x16x32_bf16 v[94:97], v[140:143], v[194:197], v[94:97]
	v_mfma_f32_16x16x32_bf16 v[90:93], v[154:157], v[194:197], v[90:93]
	v_mfma_f32_16x16x32_bf16 v[78:81], v[140:143], v[202:205], v[78:81]
	v_mfma_f32_16x16x32_bf16 v[74:77], v[154:157], v[202:205], v[74:77]
	v_mfma_f32_16x16x32_bf16 v[126:129], v[150:153], v[182:185], v[126:129]
	v_mfma_f32_16x16x32_bf16 v[122:125], v[158:161], v[182:185], v[122:125]
	v_mfma_f32_16x16x32_bf16 v[110:113], v[150:153], v[190:193], v[110:113]
	v_mfma_f32_16x16x32_bf16 v[106:109], v[158:161], v[190:193], v[106:109]
	v_mfma_f32_16x16x32_bf16 v[94:97], v[150:153], v[198:201], v[94:97]
	v_mfma_f32_16x16x32_bf16 v[90:93], v[158:161], v[198:201], v[90:93]
	v_mfma_f32_16x16x32_bf16 v[78:81], v[150:153], v[206:209], v[78:81]
	v_mfma_f32_16x16x32_bf16 v[74:77], v[158:161], v[206:209], v[74:77]
	v_mfma_f32_16x16x32_bf16 v[118:121], v[162:165], v[178:181], v[118:121]
	v_mfma_f32_16x16x32_bf16 v[114:117], v[170:173], v[178:181], v[114:117]
	v_mfma_f32_16x16x32_bf16 v[102:105], v[162:165], v[186:189], v[102:105]
	v_mfma_f32_16x16x32_bf16 v[98:101], v[170:173], v[186:189], v[98:101]
	v_mfma_f32_16x16x32_bf16 v[86:89], v[162:165], v[194:197], v[86:89]
	v_mfma_f32_16x16x32_bf16 v[82:85], v[170:173], v[194:197], v[82:85]
	v_mfma_f32_16x16x32_bf16 v[70:73], v[162:165], v[202:205], v[70:73]
	v_mfma_f32_16x16x32_bf16 v[66:69], v[170:173], v[202:205], v[66:69]
	v_mfma_f32_16x16x32_bf16 v[118:121], v[166:169], v[182:185], v[118:121]
	v_mfma_f32_16x16x32_bf16 v[114:117], v[174:177], v[182:185], v[114:117]
	v_mfma_f32_16x16x32_bf16 v[102:105], v[166:169], v[190:193], v[102:105]
	v_mfma_f32_16x16x32_bf16 v[98:101], v[174:177], v[190:193], v[98:101]
	v_mfma_f32_16x16x32_bf16 v[86:89], v[166:169], v[198:201], v[86:89]
	v_mfma_f32_16x16x32_bf16 v[82:85], v[174:177], v[198:201], v[82:85]
	v_mfma_f32_16x16x32_bf16 v[70:73], v[166:169], v[206:209], v[70:73]
	v_mfma_f32_16x16x32_bf16 v[66:69], v[174:177], v[206:209], v[66:69]
	s_setprio 0
	s_barrier
; #define PG8_STAGE(bufoff, gbase, voff) do { _Pragma("unroll") for (int _i = 0; _i < 2; ++_i) \
;         __builtin_amdgcn_global_load_lds((const unsigned*)((const char*)(gbase) + (voff)[_i]), (PG8_LAS unsigned*)(lds + (bufoff) + ldsw + _i * 8192), 16, 0, 0); } while (0)
; #define PG8_LDA(dst, b, h) do { _Pragma("unroll") for (int m = 0; m < 4; ++m) _Pragma("unroll") for (int k = 0; k < 2; ++k) dst[m][k] = *(const PG8_LAS bf16x8*)(lds + PG8_SA(b, h) + aoff + m * 2048 + k * 1024); } while (0)
; #define PG8_MMA(ai, bj, At, Bt) do { __builtin_amdgcn_s_setprio(1); _Pragma("unroll") for (int m = 0; m < 4; ++m) _Pragma("unroll") for (int n = 0; n < 2; ++n) _Pragma("unroll") for (int k = 0; k < 2; ++k) \
;         acc[ai][bj][m][n] = __builtin_amdgcn_mfma_f32_16x16x32_bf16(Bt[n][k], At[m][k], acc[ai][bj][m][n], 0, 0, 0); __builtin_amdgcn_s_setprio(0); } while (0)
; #define PG8_WAIT_V(n) asm volatile("s_waitcnt vmcnt(" #n ")" ::: "memory")
; #define PG8_WAIT_L(n) asm volatile("s_waitcnt lgkmcnt(" #n ")" ::: "memory")
; #define PG8_BAR __builtin_amdgcn_s_barrier()
; #define PG8_SCHED __builtin_amdgcn_sched_barrier(0)
; template <class Epi, class Sched, bool ALIGN_EPI = false, bool SP2 = false>
; __device__ __forceinline__ void gemm_phase(PG8_LAS unsigned char* lds, const Gemm g, const Sched& S, const Epi& E, int wave0) {
;     ...
;         for (int t = 0; t < nt; t += 2) {
;             const bool last = (t == nt - 2);
;             const char* a1 = cA + (size_t)(t + 1) * kstep;
;             const char* a2 = last ? nA : cA + (size_t)(t + 2) * kstep; const char* b2 = last ? nB : cB + (size_t)(t + 2) * kstep;
;             const char* a3 = a2 + kstep; const char* b3 = b2 + kstep;
;     ...
;             PG8_LDA(At, 1, 1); PG8_STAGE(PG8_SB(1, 0), b3, voffB); PG8_STAGE(PG8_SB(1, 1), b3 + hstep, voffB); PG8_STAGE(PG8_SA(1, 0), a3, voffA);
;             PG8_WAIT_V(8); PG8_WAIT_L(0); PG8_BAR; PG8_MMA(1, 0, At, B0); PG8_MMA(1, 1, At, B1); PG8_BAR; PG8_SCHED;
	s_add_i32 s28, s36, s50
	v_lshl_add_u64 v[144:145], v[144:145], 0, s[34:35]
	s_mov_b32 m0, s28
	ds_read_b128 v[178:181], v149 offset:49152
	ds_read_b128 v[182:185], v149 offset:50176
	ds_read_b128 v[186:189], v149 offset:51200
	ds_read_b128 v[190:193], v149 offset:52224
	ds_read_b128 v[194:197], v149 offset:53248
	ds_read_b128 v[198:201], v149 offset:54272
	ds_read_b128 v[202:205], v149 offset:55296
	ds_read_b128 v[206:209], v149 offset:56320
	global_load_lds_dwordx4 v[144:145], off
	s_add_i32 m0, s28, 0x2000
	s_add_u32 s4, s4, 0x100080
	v_lshl_add_u64 v[144:145], v[210:211], 0, s[34:35]
	s_addc_u32 s5, s5, 0
	s_add_i32 s28, s64, s50
	global_load_lds_dwordx4 v[144:145], off
	v_lshl_add_u64 v[144:145], s[4:5], 0, v[0:1]
	s_mov_b32 m0, s28
	s_nop 0
	global_load_lds_dwordx4 v[144:145], off
	v_lshl_add_u64 v[144:145], s[4:5], 0, v[130:131]
	s_add_i32 m0, s28, 0x2000
	s_nop 0
	global_load_lds_dwordx4 v[144:145], off
	v_lshl_add_u64 v[144:145], v[212:213], 0, s[34:35]
	s_mov_b32 m0, s57
	s_nop 0
	global_load_lds_dwordx4 v[144:145], off
	v_lshl_add_u64 v[144:145], v[214:215], 0, s[34:35]
	s_mov_b32 m0, s58
	s_nop 0
	global_load_lds_dwordx4 v[144:145], off
	s_waitcnt vmcnt(8)
	s_waitcnt lgkmcnt(0)
	s_barrier
	s_setprio 1
	s_waitcnt lgkmcnt(0)
	v_mfma_f32_16x16x32_bf16 v[58:61], v[140:143], v[178:181], v[58:61]
	v_mfma_f32_16x16x32_bf16 v[62:65], v[154:157], v[178:181], v[62:65]
	v_mfma_f32_16x16x32_bf16 v[42:45], v[140:143], v[186:189], v[42:45]
	v_mfma_f32_16x16x32_bf16 v[46:49], v[154:157], v[186:189], v[46:49]
	v_mfma_f32_16x16x32_bf16 v[26:29], v[140:143], v[194:197], v[26:29]
	v_mfma_f32_16x16x32_bf16 v[30:33], v[154:157], v[194:197], v[30:33]
	v_mfma_f32_16x16x32_bf16 v[10:13], v[140:143], v[202:205], v[10:13]
	v_mfma_f32_16x16x32_bf16 v[14:17], v[154:157], v[202:205], v[14:17]
	v_mfma_f32_16x16x32_bf16 v[58:61], v[150:153], v[182:185], v[58:61]
	v_mfma_f32_16x16x32_bf16 v[62:65], v[158:161], v[182:185], v[62:65]
	v_mfma_f32_16x16x32_bf16 v[42:45], v[150:153], v[190:193], v[42:45]
	v_mfma_f32_16x16x32_bf16 v[46:49], v[158:161], v[190:193], v[46:49]
	v_mfma_f32_16x16x32_bf16 v[26:29], v[150:153], v[198:201], v[26:29]
	v_mfma_f32_16x16x32_bf16 v[30:33], v[158:161], v[198:201], v[30:33]
	v_mfma_f32_16x16x32_bf16 v[10:13], v[150:153], v[206:209], v[10:13]
	v_mfma_f32_16x16x32_bf16 v[14:17], v[158:161], v[206:209], v[14:17]
	v_mfma_f32_16x16x32_bf16 v[54:57], v[162:165], v[178:181], v[54:57]
	v_mfma_f32_16x16x32_bf16 v[50:53], v[170:173], v[178:181], v[50:53]
	v_mfma_f32_16x16x32_bf16 v[38:41], v[162:165], v[186:189], v[38:41]
	v_mfma_f32_16x16x32_bf16 v[34:37], v[170:173], v[186:189], v[34:37]
	v_mfma_f32_16x16x32_bf16 v[22:25], v[162:165], v[194:197], v[22:25]
	v_mfma_f32_16x16x32_bf16 v[18:21], v[170:173], v[194:197], v[18:21]
	v_mfma_f32_16x16x32_bf16 v[6:9], v[162:165], v[202:205], v[6:9]
	v_mfma_f32_16x16x32_bf16 v[2:5], v[170:173], v[202:205], v[2:5]
	v_mfma_f32_16x16x32_bf16 v[54:57], v[166:169], v[182:185], v[54:57]
	v_mfma_f32_16x16x32_bf16 v[50:53], v[174:177], v[182:185], v[50:53]
	v_mfma_f32_16x16x32_bf16 v[38:41], v[166:169], v[190:193], v[38:41]
	v_mfma_f32_16x16x32_bf16 v[34:37], v[174:177], v[190:193], v[34:37]
	v_mfma_f32_16x16x32_bf16 v[22:25], v[166:169], v[198:201], v[22:25]
	v_mfma_f32_16x16x32_bf16 v[18:21], v[174:177], v[198:201], v[18:21]
	v_mfma_f32_16x16x32_bf16 v[6:9], v[166:169], v[206:209], v[6:9]
	v_mfma_f32_16x16x32_bf16 v[2:5], v[174:177], v[206:209], v[2:5]
	s_setprio 0
	s_barrier
	s_add_i32 s63, s63, 2
	s_add_u32 s6, s6, 0x100
	s_addc_u32 s7, s7, 0
	s_add_u32 s61, s61, 0x100
	s_addc_u32 s62, s62, 0
	s_cmp_gt_u32 s63, 61
	s_cbranch_scc0 .LBB0_1198
	s_and_b64 vcc, exec, s[24:25]
	s_cbranch_vccz .LBB0_1201
	s_barrier
